# GEMM K-loops: LDS-DMA loads take their voffset registers directly (v_mov copies removed), 64-bit VALU address sums replaced by SALU sums in vcc
# speedup vs baseline: 1.0332x; 1.0049x over previous
;     __device__ bool next(int i, Unit& u) const { const bool r = base.next(i >> 1, u); u.kh = i & 1; return r; }
; #define PG8_LDA(dst, b, h) do { _Pragma("unroll") for (int m = 0; m < 4; ++m) _Pragma("unroll") for (int k = 0; k < 2; ++k) dst[m][k] = *(const PG8_LAS bf16x8*)(lds + PG8_SA(b, h) + aoff + m * 2048 + k * 1024); } while (0)
; template <class Epi, class Sched, bool ALIGN_EPI = false, bool SP2 = false, bool ABLK = false, bool F8 = false>
; __device__ __forceinline__ void gemm_phase(PG8_LAS unsigned char* lds, const Gemm g, const Sched& S, const Epi& E, const int wave_s) {
;     ...
;         const bool has_next = S.next(ui + 1, nxt); nxt.par = (ui + 1) & 1;
;         const char* nA = has_next ? (const char*)g.A + (size_t)nxt.pm * tstep + nxt.kh * khbA : cA; const char* nB = has_next ? (const char*)g.Bt + (size_t)nxt.pn * tstep + nxt.kh * khb : cB;
;         for (int t = 0; t < nt; t += 2) {
;             const bool last = (t == nt - 2);
;             const char* a1 = cA + (size_t)(t + 1) * kstepA;
;             const char* a2 = last ? nA : cA + (size_t)(t + 2) * kstepA; const char* b2 = last ? nB : cB + (size_t)(t + 2) * kstep;
;             const char* a3 = a2 + kstepA; const char* b3 = b2 + kstep;
;             if (last && has_next) { S.a_ready(nxt); if constexpr (Epi::PREF) E.prefetch(nxt, wid, lane); }
;             if constexpr (SP2) {
;             PG8_LDB(B0, 0, 0); PG8_LDB(B1, 0, 1); PG8_SCHED; PG8_LDA(At, 0, 0); PG8_STAGE(PG8_SA(1, 1), a1 + hstepA, voffA);
;             PG8_WAIT_V(8); PG8_WAIT_L(0); PG8_BAR; PG8_MMA(0, 0, At, B0); PG8_MMA(0, 1, At, B1); PG8_BAR; PG8_SCHED;
;             PG8_LDA(At, 0, 1); PG8_STAGE(PG8_SB(0, 0), b2, voffB); PG8_STAGE(PG8_SB(0, 1), b2 + hstep, voffB); PG8_STAGE(PG8_SA(0, 0), a2, voffA);
;             PG8_WAIT_V(8); PG8_WAIT_L(0); PG8_BAR; PG8_MMA(1, 0, At, B0); PG8_MMA(1, 1, At, B1); PG8_BAR; PG8_SCHED;
;             PG8_LDB(B0, 1, 0); PG8_LDB(B1, 1, 1); PG8_SCHED; PG8_LDA(At, 1, 0); PG8_STAGE(PG8_SA(0, 1), a2 + hstepA, voffA);
;             PG8_WAIT_V(8); PG8_WAIT_L(0); PG8_BAR; PG8_MMA(0, 0, At, B0); PG8_MMA(0, 1, At, B1); PG8_BAR; PG8_SCHED;
;             PG8_LDA(At, 1, 1); PG8_STAGE(PG8_SB(1, 0), b3, voffB); PG8_STAGE(PG8_SB(1, 1), b3 + hstep, voffB); PG8_STAGE(PG8_SA(1, 0), a3, voffA);
;             PG8_WAIT_V(8); PG8_WAIT_L(0); PG8_BAR; PG8_MMA(1, 0, At, B0); PG8_MMA(1, 1, At, B1); PG8_BAR; PG8_SCHED;
.LBB0_223:
	v_add_u32_e32 v128, s64, v160
	ds_read_b128 v[166:169], v128
	ds_read_b128 v[170:173], v128 offset:1024
	ds_read_b128 v[174:177], v128 offset:2048
	ds_read_b128 v[178:181], v128 offset:3072
	v_add_u32_e32 v128, s65, v160
	ds_read_b128 v[182:185], v128
	ds_read_b128 v[186:189], v128 offset:1024
	ds_read_b128 v[190:193], v128 offset:2048
	ds_read_b128 v[194:197], v128 offset:3072
	s_add_u32 s62, s58, 0xfff80080
	s_addc_u32 s63, s59, -1
	s_and_b64 s[60:61], s[60:61], exec
	s_cselect_b32 s61, s63, s49
	s_cselect_b32 s60, s62, s77
	s_cselect_b32 s63, s80, s17
	s_cselect_b32 s62, s79, s78
	ds_read_b128 v[198:201], v163
	ds_read_b128 v[202:205], v163 offset:1024
	ds_read_b128 v[206:209], v163 offset:2048
	ds_read_b128 v[210:213], v163 offset:3072
	ds_read_b128 v[214:217], v163 offset:4096
	ds_read_b128 v[218:221], v163 offset:5120
	ds_read_b128 v[222:225], v163 offset:6144
	ds_read_b128 v[230:233], v163 offset:7168
	s_add_i32 m0, s22, 0xc000
	s_nop 0
	global_load_lds_dwordx4 v156, s[58:59]
	s_add_i32 m0, s22, 0xe000
	s_nop 0
	global_load_lds_dwordx4 v158, s[58:59]
	s_waitcnt vmcnt(8)
	s_waitcnt lgkmcnt(0)
	s_barrier
	s_setprio 1
	s_waitcnt lgkmcnt(0)
	v_mfma_f32_16x16x32_bf16 v[124:127], v[166:169], v[198:201], v[124:127]
	v_mfma_f32_16x16x32_bf16 v[116:119], v[174:177], v[198:201], v[116:119]
	v_mfma_f32_16x16x32_bf16 v[108:111], v[166:169], v[206:209], v[108:111]
	v_mfma_f32_16x16x32_bf16 v[100:103], v[174:177], v[206:209], v[100:103]
	v_mfma_f32_16x16x32_bf16 v[92:95], v[166:169], v[214:217], v[92:95]
	v_mfma_f32_16x16x32_bf16 v[84:87], v[174:177], v[214:217], v[84:87]
	v_mfma_f32_16x16x32_bf16 v[76:79], v[166:169], v[222:225], v[76:79]
	v_mfma_f32_16x16x32_bf16 v[68:71], v[174:177], v[222:225], v[68:71]
	v_mfma_f32_16x16x32_bf16 v[124:127], v[170:173], v[202:205], v[124:127]
	v_mfma_f32_16x16x32_bf16 v[116:119], v[178:181], v[202:205], v[116:119]
	v_mfma_f32_16x16x32_bf16 v[108:111], v[170:173], v[210:213], v[108:111]
	v_mfma_f32_16x16x32_bf16 v[100:103], v[178:181], v[210:213], v[100:103]
	v_mfma_f32_16x16x32_bf16 v[92:95], v[170:173], v[218:221], v[92:95]
	v_mfma_f32_16x16x32_bf16 v[84:87], v[178:181], v[218:221], v[84:87]
	v_mfma_f32_16x16x32_bf16 v[76:79], v[170:173], v[230:233], v[76:79]
	v_mfma_f32_16x16x32_bf16 v[68:71], v[178:181], v[230:233], v[68:71]
	s_setprio 0
	s_setprio 1
	v_mfma_f32_16x16x32_bf16 v[120:123], v[182:185], v[198:201], v[120:123]
	v_mfma_f32_16x16x32_bf16 v[112:115], v[190:193], v[198:201], v[112:115]
	v_mfma_f32_16x16x32_bf16 v[104:107], v[182:185], v[206:209], v[104:107]
	v_mfma_f32_16x16x32_bf16 v[96:99], v[190:193], v[206:209], v[96:99]
	v_mfma_f32_16x16x32_bf16 v[88:91], v[182:185], v[214:217], v[88:91]
	v_mfma_f32_16x16x32_bf16 v[80:83], v[190:193], v[214:217], v[80:83]
	v_mfma_f32_16x16x32_bf16 v[72:75], v[182:185], v[222:225], v[72:75]
	v_mfma_f32_16x16x32_bf16 v[64:67], v[190:193], v[222:225], v[64:67]
	v_mfma_f32_16x16x32_bf16 v[120:123], v[186:189], v[202:205], v[120:123]
	v_mfma_f32_16x16x32_bf16 v[112:115], v[194:197], v[202:205], v[112:115]
	v_mfma_f32_16x16x32_bf16 v[104:107], v[186:189], v[210:213], v[104:107]
	v_mfma_f32_16x16x32_bf16 v[96:99], v[194:197], v[210:213], v[96:99]
	v_mfma_f32_16x16x32_bf16 v[88:91], v[186:189], v[218:221], v[88:91]
	v_mfma_f32_16x16x32_bf16 v[80:83], v[194:197], v[218:221], v[80:83]
	v_mfma_f32_16x16x32_bf16 v[72:75], v[186:189], v[230:233], v[72:75]
	v_mfma_f32_16x16x32_bf16 v[64:67], v[194:197], v[230:233], v[64:67]
	s_setprio 0
	s_barrier
	s_add_i32 s72, s64, s3
	ds_read_b128 v[198:201], v163 offset:16384
	ds_read_b128 v[202:205], v163 offset:17408
	ds_read_b128 v[206:209], v163 offset:18432
	ds_read_b128 v[210:213], v163 offset:19456
	ds_read_b128 v[214:217], v163 offset:20480
	ds_read_b128 v[218:221], v163 offset:21504
	ds_read_b128 v[222:225], v163 offset:22528
	ds_read_b128 v[230:233], v163 offset:23552
	s_mov_b32 m0, s72
	s_nop 0
	global_load_lds_dwordx4 v157, s[62:63]
	s_add_i32 m0, s72, 0x2000
	s_add_u32 s72, s62, 0x80000
	global_load_lds_dwordx4 v159, s[62:63]
	s_addc_u32 s73, s63, 0
	s_add_i32 s83, s65, s3
	s_mov_b32 m0, s83
	s_nop 0
	global_load_lds_dwordx4 v157, s[72:73]
	s_add_i32 m0, s83, 0x2000
	s_nop 0
	global_load_lds_dwordx4 v159, s[72:73]
	s_mov_b32 m0, s22
	s_nop 0
	global_load_lds_dwordx4 v156, s[60:61]
	s_mov_b32 m0, s23
	s_nop 0
	global_load_lds_dwordx4 v158, s[60:61]
	s_waitcnt vmcnt(8)
	s_waitcnt lgkmcnt(0)
	s_barrier
	s_setprio 1
	s_waitcnt lgkmcnt(0)
	v_mfma_f32_16x16x32_bf16 v[60:63], v[166:169], v[198:201], v[60:63]
	v_mfma_f32_16x16x32_bf16 v[52:55], v[174:177], v[198:201], v[52:55]
	v_mfma_f32_16x16x32_bf16 v[44:47], v[166:169], v[206:209], v[44:47]
	v_mfma_f32_16x16x32_bf16 v[36:39], v[174:177], v[206:209], v[36:39]
	v_mfma_f32_16x16x32_bf16 v[28:31], v[166:169], v[214:217], v[28:31]
	v_mfma_f32_16x16x32_bf16 v[20:23], v[174:177], v[214:217], v[20:23]
	v_mfma_f32_16x16x32_bf16 v[12:15], v[166:169], v[222:225], v[12:15]
	v_mfma_f32_16x16x32_bf16 v[4:7], v[174:177], v[222:225], v[4:7]
	v_mfma_f32_16x16x32_bf16 v[60:63], v[170:173], v[202:205], v[60:63]
	v_mfma_f32_16x16x32_bf16 v[52:55], v[178:181], v[202:205], v[52:55]
	v_mfma_f32_16x16x32_bf16 v[44:47], v[170:173], v[210:213], v[44:47]
	v_mfma_f32_16x16x32_bf16 v[36:39], v[178:181], v[210:213], v[36:39]
	v_mfma_f32_16x16x32_bf16 v[28:31], v[170:173], v[218:221], v[28:31]
	v_mfma_f32_16x16x32_bf16 v[20:23], v[178:181], v[218:221], v[20:23]
	v_mfma_f32_16x16x32_bf16 v[12:15], v[170:173], v[230:233], v[12:15]
	v_mfma_f32_16x16x32_bf16 v[4:7], v[178:181], v[230:233], v[4:7]
	s_setprio 0
	s_setprio 1
	v_mfma_f32_16x16x32_bf16 v[56:59], v[182:185], v[198:201], v[56:59]
	v_mfma_f32_16x16x32_bf16 v[48:51], v[190:193], v[198:201], v[48:51]
	v_mfma_f32_16x16x32_bf16 v[40:43], v[182:185], v[206:209], v[40:43]
	v_mfma_f32_16x16x32_bf16 v[32:35], v[190:193], v[206:209], v[32:35]
	v_mfma_f32_16x16x32_bf16 v[24:27], v[182:185], v[214:217], v[24:27]
	v_mfma_f32_16x16x32_bf16 v[16:19], v[190:193], v[214:217], v[16:19]
	v_mfma_f32_16x16x32_bf16 v[8:11], v[182:185], v[222:225], v[8:11]
	v_mfma_f32_16x16x32_bf16 v[0:3], v[190:193], v[222:225], v[0:3]
	v_mfma_f32_16x16x32_bf16 v[56:59], v[186:189], v[202:205], v[56:59]
	v_mfma_f32_16x16x32_bf16 v[48:51], v[194:197], v[202:205], v[48:51]
	v_mfma_f32_16x16x32_bf16 v[40:43], v[186:189], v[210:213], v[40:43]
	v_mfma_f32_16x16x32_bf16 v[32:35], v[194:197], v[210:213], v[32:35]
	v_mfma_f32_16x16x32_bf16 v[24:27], v[186:189], v[218:221], v[24:27]
	v_mfma_f32_16x16x32_bf16 v[16:19], v[194:197], v[218:221], v[16:19]
	v_mfma_f32_16x16x32_bf16 v[8:11], v[186:189], v[230:233], v[8:11]
	v_mfma_f32_16x16x32_bf16 v[0:3], v[194:197], v[230:233], v[0:3]
	s_setprio 0
	s_barrier
; #define PG8_STAGE(bufoff, gbase, voff) do { _Pragma("unroll") for (int _i = 0; _i < 2; ++_i) \
;         { unsigned _vo = (voff)[_i]; asm volatile("" : "+v"(_vo));     \
;         __builtin_amdgcn_global_load_lds((const unsigned*)((const char*)(gbase) + _vo), (PG8_LAS unsigned*)(lds + (bufoff) + ldsw + _i * 8192), 16, 0, 0); } } while (0)
; #define PG8_LDA(dst, b, h) do { _Pragma("unroll") for (int m = 0; m < 4; ++m) _Pragma("unroll") for (int k = 0; k < 2; ++k) dst[m][k] = *(const PG8_LAS bf16x8*)(lds + PG8_SA(b, h) + aoff + m * 2048 + k * 1024); } while (0)
; #define PG8_BAR __builtin_amdgcn_s_barrier()
; template <class Epi, class Sched, bool ALIGN_EPI = false, bool SP2 = false, bool ABLK = false, bool F8 = false>
; __device__ __forceinline__ void gemm_phase(PG8_LAS unsigned char* lds, const Gemm g, const Sched& S, const Epi& E, const int wave_s) {
;     ...
;         for (int t = 0; t < nt; t += 2) {
;             const bool last = (t == nt - 2);
;             const char* a1 = cA + (size_t)(t + 1) * kstepA;
;             const char* a2 = last ? nA : cA + (size_t)(t + 2) * kstepA; const char* b2 = last ? nB : cB + (size_t)(t + 2) * kstep;
;             const char* a3 = a2 + kstepA; const char* b3 = b2 + kstep;
;             if (last && has_next) { S.a_ready(nxt); if constexpr (Epi::PREF) E.prefetch(nxt, wid, lane); }
;             if constexpr (SP2) {
;             PG8_LDB(B0, 0, 0); PG8_LDB(B1, 0, 1); PG8_SCHED; PG8_LDA(At, 0, 0); PG8_STAGE(PG8_SA(1, 1), a1 + hstepA, voffA);
;             PG8_WAIT_V(8); PG8_WAIT_L(0); PG8_BAR; PG8_MMA(0, 0, At, B0); PG8_MMA(0, 1, At, B1); PG8_BAR; PG8_SCHED;
;             PG8_LDA(At, 0, 1); PG8_STAGE(PG8_SB(0, 0), b2, voffB); PG8_STAGE(PG8_SB(0, 1), b2 + hstep, voffB); PG8_STAGE(PG8_SA(0, 0), a2, voffA);
;             PG8_WAIT_V(8); PG8_WAIT_L(0); PG8_BAR; PG8_MMA(1, 0, At, B0); PG8_MMA(1, 1, At, B1); PG8_BAR; PG8_SCHED;
;             PG8_LDB(B0, 1, 0); PG8_LDB(B1, 1, 1); PG8_SCHED; PG8_LDA(At, 1, 0); PG8_STAGE(PG8_SA(0, 1), a2 + hstepA, voffA);
;             PG8_WAIT_V(8); PG8_WAIT_L(0); PG8_BAR; PG8_MMA(0, 0, At, B0); PG8_MMA(0, 1, At, B1); PG8_BAR; PG8_SCHED;
;             PG8_LDA(At, 1, 1); PG8_STAGE(PG8_SB(1, 0), b3, voffB); PG8_STAGE(PG8_SB(1, 1), b3 + hstep, voffB); PG8_STAGE(PG8_SA(1, 0), a3, voffA);
;             PG8_WAIT_V(8); PG8_WAIT_L(0); PG8_BAR; PG8_MMA(1, 0, At, B0); PG8_MMA(1, 1, At, B1); PG8_BAR; PG8_SCHED;
	s_add_i32 s83, 0, 0x18000
	v_add_u32_e32 v128, s83, v160
	s_add_i32 s84, 0, 0x1c000
	ds_read_b128 v[166:169], v128
	ds_read_b128 v[170:173], v128 offset:1024
	ds_read_b128 v[174:177], v128 offset:2048
	ds_read_b128 v[178:181], v128 offset:3072
	v_add_u32_e32 v128, s84, v160
	ds_read_b128 v[182:185], v128
	ds_read_b128 v[186:189], v128 offset:1024
	ds_read_b128 v[190:193], v128 offset:2048
	ds_read_b128 v[194:197], v128 offset:3072
	s_add_u32 s72, s60, 0x80000
	s_mov_b32 m0, s46
	ds_read_b128 v[198:201], v163 offset:32768
	ds_read_b128 v[202:205], v163 offset:33792
	ds_read_b128 v[206:209], v163 offset:34816
	ds_read_b128 v[210:213], v163 offset:35840
	ds_read_b128 v[214:217], v163 offset:36864
	ds_read_b128 v[218:221], v163 offset:37888
	ds_read_b128 v[222:225], v163 offset:38912
	ds_read_b128 v[230:233], v163 offset:39936
	s_addc_u32 s73, s61, 0
	s_nop 0
	global_load_lds_dwordx4 v156, s[72:73]
	s_mov_b32 m0, s47
	s_nop 0
	global_load_lds_dwordx4 v158, s[72:73]
	s_waitcnt vmcnt(8)
	s_waitcnt lgkmcnt(0)
	s_barrier
	s_setprio 1
	s_waitcnt lgkmcnt(0)
	v_mfma_f32_16x16x32_bf16 v[124:127], v[166:169], v[198:201], v[124:127]
	v_mfma_f32_16x16x32_bf16 v[116:119], v[174:177], v[198:201], v[116:119]
	v_mfma_f32_16x16x32_bf16 v[108:111], v[166:169], v[206:209], v[108:111]
	v_mfma_f32_16x16x32_bf16 v[100:103], v[174:177], v[206:209], v[100:103]
	v_mfma_f32_16x16x32_bf16 v[92:95], v[166:169], v[214:217], v[92:95]
	v_mfma_f32_16x16x32_bf16 v[84:87], v[174:177], v[214:217], v[84:87]
	v_mfma_f32_16x16x32_bf16 v[76:79], v[166:169], v[222:225], v[76:79]
	v_mfma_f32_16x16x32_bf16 v[68:71], v[174:177], v[222:225], v[68:71]
	v_mfma_f32_16x16x32_bf16 v[124:127], v[170:173], v[202:205], v[124:127]
	v_mfma_f32_16x16x32_bf16 v[116:119], v[178:181], v[202:205], v[116:119]
	v_mfma_f32_16x16x32_bf16 v[108:111], v[170:173], v[210:213], v[108:111]
	v_mfma_f32_16x16x32_bf16 v[100:103], v[178:181], v[210:213], v[100:103]
	v_mfma_f32_16x16x32_bf16 v[92:95], v[170:173], v[218:221], v[92:95]
	v_mfma_f32_16x16x32_bf16 v[84:87], v[178:181], v[218:221], v[84:87]
	v_mfma_f32_16x16x32_bf16 v[76:79], v[170:173], v[230:233], v[76:79]
	v_mfma_f32_16x16x32_bf16 v[68:71], v[178:181], v[230:233], v[68:71]
	s_setprio 0
	s_setprio 1
	v_mfma_f32_16x16x32_bf16 v[120:123], v[182:185], v[198:201], v[120:123]
	v_mfma_f32_16x16x32_bf16 v[112:115], v[190:193], v[198:201], v[112:115]
	v_mfma_f32_16x16x32_bf16 v[104:107], v[182:185], v[206:209], v[104:107]
	v_mfma_f32_16x16x32_bf16 v[96:99], v[190:193], v[206:209], v[96:99]
	v_mfma_f32_16x16x32_bf16 v[88:91], v[182:185], v[214:217], v[88:91]
	v_mfma_f32_16x16x32_bf16 v[80:83], v[190:193], v[214:217], v[80:83]
	v_mfma_f32_16x16x32_bf16 v[72:75], v[182:185], v[222:225], v[72:75]
	v_mfma_f32_16x16x32_bf16 v[64:67], v[190:193], v[222:225], v[64:67]
	v_mfma_f32_16x16x32_bf16 v[120:123], v[186:189], v[202:205], v[120:123]
	v_mfma_f32_16x16x32_bf16 v[112:115], v[194:197], v[202:205], v[112:115]
	v_mfma_f32_16x16x32_bf16 v[104:107], v[186:189], v[210:213], v[104:107]
	v_mfma_f32_16x16x32_bf16 v[96:99], v[194:197], v[210:213], v[96:99]
	v_mfma_f32_16x16x32_bf16 v[88:91], v[186:189], v[218:221], v[88:91]
	v_mfma_f32_16x16x32_bf16 v[80:83], v[194:197], v[218:221], v[80:83]
	v_mfma_f32_16x16x32_bf16 v[72:75], v[186:189], v[230:233], v[72:75]
	v_mfma_f32_16x16x32_bf16 v[64:67], v[194:197], v[230:233], v[64:67]
	s_setprio 0
	s_barrier
	ds_read_b128 v[198:201], v163 offset:49152
	ds_read_b128 v[202:205], v163 offset:50176
	ds_read_b128 v[206:209], v163 offset:51200
	ds_read_b128 v[210:213], v163 offset:52224
	ds_read_b128 v[214:217], v163 offset:53248
	ds_read_b128 v[218:221], v163 offset:54272
	ds_read_b128 v[222:225], v163 offset:55296
	ds_read_b128 v[230:233], v163 offset:56320
	s_add_i32 s72, s83, s3
	s_add_u32 vcc_lo, s62, s14
	s_addc_u32 vcc_hi, s63, s15
	s_mov_b32 m0, s72
	s_nop 0
	global_load_lds_dwordx4 v157, vcc
	s_add_i32 m0, s72, 0x2000
	s_nop 0
	s_add_u32 vcc_lo, s62, s14
	s_addc_u32 vcc_hi, s63, s15
	s_add_u32 s62, s62, 0x80080
	s_addc_u32 s63, s63, 0
	s_add_i32 s72, s84, s3
	global_load_lds_dwordx4 v159, vcc
	s_mov_b32 m0, s72
	s_nop 0
	global_load_lds_dwordx4 v157, s[62:63]
	s_add_i32 m0, s72, 0x2000
	s_nop 0
	global_load_lds_dwordx4 v159, s[62:63]
	s_mov_b32 m0, s55
	s_add_u32 vcc_lo, s60, s14
	s_addc_u32 vcc_hi, s61, s15
	v_mov_b32_e32 v128, v158
	global_load_lds_dwordx4 v156, vcc
	s_mov_b32 m0, s57
	s_add_u32 vcc_lo, s60, s14
	s_addc_u32 vcc_hi, s61, s15
	global_load_lds_dwordx4 v158, vcc
	s_waitcnt vmcnt(8)
	s_waitcnt lgkmcnt(0)
	s_barrier
	s_setprio 1
	s_waitcnt lgkmcnt(0)
	v_mfma_f32_16x16x32_bf16 v[60:63], v[166:169], v[198:201], v[60:63]
	v_mfma_f32_16x16x32_bf16 v[52:55], v[174:177], v[198:201], v[52:55]
	v_mfma_f32_16x16x32_bf16 v[44:47], v[166:169], v[206:209], v[44:47]
	v_mfma_f32_16x16x32_bf16 v[36:39], v[174:177], v[206:209], v[36:39]
	v_mfma_f32_16x16x32_bf16 v[28:31], v[166:169], v[214:217], v[28:31]
	v_mfma_f32_16x16x32_bf16 v[20:23], v[174:177], v[214:217], v[20:23]
	v_mfma_f32_16x16x32_bf16 v[12:15], v[166:169], v[222:225], v[12:15]
	v_mfma_f32_16x16x32_bf16 v[4:7], v[174:177], v[222:225], v[4:7]
	v_mfma_f32_16x16x32_bf16 v[60:63], v[170:173], v[202:205], v[60:63]
	v_mfma_f32_16x16x32_bf16 v[52:55], v[178:181], v[202:205], v[52:55]
	v_mfma_f32_16x16x32_bf16 v[44:47], v[170:173], v[210:213], v[44:47]
	v_mfma_f32_16x16x32_bf16 v[36:39], v[178:181], v[210:213], v[36:39]
	v_mfma_f32_16x16x32_bf16 v[28:31], v[170:173], v[218:221], v[28:31]
	v_mfma_f32_16x16x32_bf16 v[20:23], v[178:181], v[218:221], v[20:23]
	v_mfma_f32_16x16x32_bf16 v[12:15], v[170:173], v[230:233], v[12:15]
	v_mfma_f32_16x16x32_bf16 v[4:7], v[178:181], v[230:233], v[4:7]
	s_setprio 0
	s_setprio 1
	v_mfma_f32_16x16x32_bf16 v[56:59], v[182:185], v[198:201], v[56:59]
	v_mfma_f32_16x16x32_bf16 v[48:51], v[190:193], v[198:201], v[48:51]
	v_mfma_f32_16x16x32_bf16 v[40:43], v[182:185], v[206:209], v[40:43]
	v_mfma_f32_16x16x32_bf16 v[32:35], v[190:193], v[206:209], v[32:35]
	v_mfma_f32_16x16x32_bf16 v[24:27], v[182:185], v[214:217], v[24:27]
	v_mfma_f32_16x16x32_bf16 v[16:19], v[190:193], v[214:217], v[16:19]
	v_mfma_f32_16x16x32_bf16 v[8:11], v[182:185], v[222:225], v[8:11]
	v_mfma_f32_16x16x32_bf16 v[0:3], v[190:193], v[222:225], v[0:3]
	v_mfma_f32_16x16x32_bf16 v[56:59], v[186:189], v[202:205], v[56:59]
	v_mfma_f32_16x16x32_bf16 v[48:51], v[194:197], v[202:205], v[48:51]
	v_mfma_f32_16x16x32_bf16 v[40:43], v[186:189], v[210:213], v[40:43]
	v_mfma_f32_16x16x32_bf16 v[32:35], v[194:197], v[210:213], v[32:35]
	v_mfma_f32_16x16x32_bf16 v[24:27], v[186:189], v[218:221], v[24:27]
	v_mfma_f32_16x16x32_bf16 v[16:19], v[194:197], v[218:221], v[16:19]
	v_mfma_f32_16x16x32_bf16 v[8:11], v[186:189], v[230:233], v[8:11]
	v_mfma_f32_16x16x32_bf16 v[0:3], v[194:197], v[230:233], v[0:3]
	s_setprio 0
	s_barrier
	s_add_i32 s81, s81, 2
	s_add_u32 s58, s58, 0x100
	s_addc_u32 s59, s59, 0
	s_add_u32 s79, s79, 0x100
	s_addc_u32 s80, s80, 0
	s_cmp_gt_u32 s81, 29
	s_cbranch_scc1 .LBB0_226

;     __device__ bool next(int i, Unit& u) const { const bool r = base.next(i >> 1, u); u.kh = i & 1; return r; }
; #define PG8_LDA(dst, b, h) do { _Pragma("unroll") for (int m = 0; m < 4; ++m) _Pragma("unroll") for (int k = 0; k < 2; ++k) dst[m][k] = *(const PG8_LAS bf16x8*)(lds + PG8_SA(b, h) + aoff + m * 2048 + k * 1024); } while (0)
; template <class Epi, class Sched, bool ALIGN_EPI = false, bool SP2 = false, bool ABLK = false, bool F8 = false>
; __device__ __forceinline__ void gemm_phase(PG8_LAS unsigned char* lds, const Gemm g, const Sched& S, const Epi& E, const int wave_s) {
;     ...
;         const bool has_next = S.next(ui + 1, nxt); nxt.par = (ui + 1) & 1;
;         const char* nA = has_next ? (const char*)g.A + (size_t)nxt.pm * tstep + nxt.kh * khbA : cA; const char* nB = has_next ? (const char*)g.Bt + (size_t)nxt.pn * tstep + nxt.kh * khb : cB;
;         for (int t = 0; t < nt; t += 2) {
;             const bool last = (t == nt - 2);
;             const char* a1 = cA + (size_t)(t + 1) * kstepA;
;             const char* a2 = last ? nA : cA + (size_t)(t + 2) * kstepA; const char* b2 = last ? nB : cB + (size_t)(t + 2) * kstep;
;             const char* a3 = a2 + kstepA; const char* b3 = b2 + kstep;
;             if (last && has_next) { S.a_ready(nxt); if constexpr (Epi::PREF) E.prefetch(nxt, wid, lane); }
;             if constexpr (SP2) {
;             PG8_LDB(B0, 0, 0); PG8_LDB(B1, 0, 1); PG8_SCHED; PG8_LDA(At, 0, 0); PG8_STAGE(PG8_SA(1, 1), a1 + hstepA, voffA);
;             PG8_WAIT_V(8); PG8_WAIT_L(0); PG8_BAR; PG8_MMA(0, 0, At, B0); PG8_MMA(0, 1, At, B1); PG8_BAR; PG8_SCHED;
;             PG8_LDA(At, 0, 1); PG8_STAGE(PG8_SB(0, 0), b2, voffB); PG8_STAGE(PG8_SB(0, 1), b2 + hstep, voffB); PG8_STAGE(PG8_SA(0, 0), a2, voffA);
;             PG8_WAIT_V(8); PG8_WAIT_L(0); PG8_BAR; PG8_MMA(1, 0, At, B0); PG8_MMA(1, 1, At, B1); PG8_BAR; PG8_SCHED;
;             PG8_LDB(B0, 1, 0); PG8_LDB(B1, 1, 1); PG8_SCHED; PG8_LDA(At, 1, 0); PG8_STAGE(PG8_SA(0, 1), a2 + hstepA, voffA);
;             PG8_WAIT_V(8); PG8_WAIT_L(0); PG8_BAR; PG8_MMA(0, 0, At, B0); PG8_MMA(0, 1, At, B1); PG8_BAR; PG8_SCHED;
;             PG8_LDA(At, 1, 1); PG8_STAGE(PG8_SB(1, 0), b3, voffB); PG8_STAGE(PG8_SB(1, 1), b3 + hstep, voffB); PG8_STAGE(PG8_SA(1, 0), a3, voffA);
;             PG8_WAIT_V(8); PG8_WAIT_L(0); PG8_BAR; PG8_MMA(1, 0, At, B0); PG8_MMA(1, 1, At, B1); PG8_BAR; PG8_SCHED;
.LBB0_304:
	ds_read_b128 v[104:107], v230
	ds_read_b128 v[116:119], v230 offset:1024
	ds_read_b128 v[128:131], v230 offset:2048
	ds_read_b128 v[140:143], v230 offset:3072
	ds_read_b128 v[144:147], v231
	ds_read_b128 v[148:151], v231 offset:1024
	ds_read_b128 v[152:155], v231 offset:2048
	ds_read_b128 v[156:159], v231 offset:3072
	s_add_u32 s52, s50, 0x4000
	s_addc_u32 s53, s51, 0
	s_cmpk_eq_i32 s77, 0x54
	s_cselect_b32 s56, s12, s52
	s_cselect_b32 s57, s13, s53
	s_cselect_b32 s54, s48, s67
	s_cselect_b32 s55, s49, s76
	s_add_u32 s52, s56, 0x8000
	s_addc_u32 s53, s57, 0
	ds_read_b128 v[160:163], v232
	ds_read_b128 v[164:167], v232 offset:1024
	ds_read_b128 v[168:171], v232 offset:2048
	ds_read_b128 v[172:175], v232 offset:3072
	ds_read_b128 v[176:179], v232 offset:4096
	ds_read_b128 v[180:183], v232 offset:5120
	ds_read_b128 v[190:193], v232 offset:6144
	ds_read_b128 v[194:197], v232 offset:7168
	s_add_i32 m0, s22, 0xc000
	s_nop 0
	global_load_lds_dwordx4 v222, s[50:51]
	s_add_i32 m0, s22, 0xe000
	s_nop 0
	global_load_lds_dwordx4 v224, s[50:51]
	s_waitcnt vmcnt(8)
	s_waitcnt lgkmcnt(0)
	s_barrier
	s_setprio 1
	s_waitcnt lgkmcnt(0)
	v_mfma_f32_16x16x32_bf16 v[136:139], v[104:107], v[160:163], v[136:139]
	v_mfma_f32_16x16x32_bf16 v[132:135], v[128:131], v[160:163], v[132:135]
	v_mfma_f32_16x16x32_bf16 v[112:115], v[104:107], v[168:171], v[112:115]
	v_mfma_f32_16x16x32_bf16 v[108:111], v[128:131], v[168:171], v[108:111]
	v_mfma_f32_16x16x32_bf16 v[92:95], v[104:107], v[176:179], v[92:95]
	v_mfma_f32_16x16x32_bf16 v[88:91], v[128:131], v[176:179], v[88:91]
	v_mfma_f32_16x16x32_bf16 v[76:79], v[104:107], v[190:193], v[76:79]
	v_mfma_f32_16x16x32_bf16 v[72:75], v[128:131], v[190:193], v[72:75]
	v_mfma_f32_16x16x32_bf16 v[136:139], v[116:119], v[164:167], v[136:139]
	v_mfma_f32_16x16x32_bf16 v[132:135], v[140:143], v[164:167], v[132:135]
	v_mfma_f32_16x16x32_bf16 v[112:115], v[116:119], v[172:175], v[112:115]
	v_mfma_f32_16x16x32_bf16 v[108:111], v[140:143], v[172:175], v[108:111]
	v_mfma_f32_16x16x32_bf16 v[92:95], v[116:119], v[180:183], v[92:95]
	v_mfma_f32_16x16x32_bf16 v[88:91], v[140:143], v[180:183], v[88:91]
	v_mfma_f32_16x16x32_bf16 v[76:79], v[116:119], v[194:197], v[76:79]
	v_mfma_f32_16x16x32_bf16 v[72:75], v[140:143], v[194:197], v[72:75]
	s_setprio 0
	s_setprio 1
	v_mfma_f32_16x16x32_bf16 v[124:127], v[144:147], v[160:163], v[124:127]
	v_mfma_f32_16x16x32_bf16 v[120:123], v[152:155], v[160:163], v[120:123]
	v_mfma_f32_16x16x32_bf16 v[100:103], v[144:147], v[168:171], v[100:103]
	v_mfma_f32_16x16x32_bf16 v[96:99], v[152:155], v[168:171], v[96:99]
	v_mfma_f32_16x16x32_bf16 v[84:87], v[144:147], v[176:179], v[84:87]
	v_mfma_f32_16x16x32_bf16 v[80:83], v[152:155], v[176:179], v[80:83]
	v_mfma_f32_16x16x32_bf16 v[68:71], v[144:147], v[190:193], v[68:71]
	v_mfma_f32_16x16x32_bf16 v[64:67], v[152:155], v[190:193], v[64:67]
	v_mfma_f32_16x16x32_bf16 v[124:127], v[148:151], v[164:167], v[124:127]
	v_mfma_f32_16x16x32_bf16 v[120:123], v[156:159], v[164:167], v[120:123]
	v_mfma_f32_16x16x32_bf16 v[100:103], v[148:151], v[172:175], v[100:103]
	v_mfma_f32_16x16x32_bf16 v[96:99], v[156:159], v[172:175], v[96:99]
	v_mfma_f32_16x16x32_bf16 v[84:87], v[148:151], v[180:183], v[84:87]
	v_mfma_f32_16x16x32_bf16 v[80:83], v[156:159], v[180:183], v[80:83]
	v_mfma_f32_16x16x32_bf16 v[68:71], v[148:151], v[194:197], v[68:71]
	v_mfma_f32_16x16x32_bf16 v[64:67], v[156:159], v[194:197], v[64:67]
	s_setprio 0
	s_barrier
	s_add_i32 s72, s61, s3
	ds_read_b128 v[160:163], v232 offset:16384
	ds_read_b128 v[164:167], v232 offset:17408
	ds_read_b128 v[168:171], v232 offset:18432
	ds_read_b128 v[172:175], v232 offset:19456
	ds_read_b128 v[176:179], v232 offset:20480
	ds_read_b128 v[180:183], v232 offset:21504
	ds_read_b128 v[190:193], v232 offset:22528
	ds_read_b128 v[194:197], v232 offset:23552
	s_mov_b32 m0, s72
	s_nop 0
	global_load_lds_dwordx4 v223, s[54:55]
	s_add_i32 m0, s72, 0x2000
	s_add_u32 s72, s54, 0x160000
	global_load_lds_dwordx4 v225, s[54:55]
	s_addc_u32 s73, s55, 0
	s_add_i32 s78, s62, s3
	s_mov_b32 m0, s78
	s_nop 0
	global_load_lds_dwordx4 v223, s[72:73]
	s_add_i32 m0, s78, 0x2000
	s_nop 0
	global_load_lds_dwordx4 v225, s[72:73]
	s_mov_b32 m0, s22
	s_nop 0
	global_load_lds_dwordx4 v222, s[56:57]
	s_mov_b32 m0, s23
	s_nop 0
	global_load_lds_dwordx4 v224, s[56:57]
	s_waitcnt vmcnt(8)
	s_waitcnt lgkmcnt(0)
	s_barrier
	s_setprio 1
	s_waitcnt lgkmcnt(0)
	v_mfma_f32_16x16x32_bf16 v[60:63], v[104:107], v[160:163], v[60:63]
	v_mfma_f32_16x16x32_bf16 v[56:59], v[128:131], v[160:163], v[56:59]
	v_mfma_f32_16x16x32_bf16 v[44:47], v[104:107], v[168:171], v[44:47]
	v_mfma_f32_16x16x32_bf16 v[40:43], v[128:131], v[168:171], v[40:43]
	v_mfma_f32_16x16x32_bf16 v[28:31], v[104:107], v[176:179], v[28:31]
	v_mfma_f32_16x16x32_bf16 v[24:27], v[128:131], v[176:179], v[24:27]
	v_mfma_f32_16x16x32_bf16 v[12:15], v[104:107], v[190:193], v[12:15]
	v_mfma_f32_16x16x32_bf16 v[8:11], v[128:131], v[190:193], v[8:11]
	v_mfma_f32_16x16x32_bf16 v[60:63], v[116:119], v[164:167], v[60:63]
	v_mfma_f32_16x16x32_bf16 v[56:59], v[140:143], v[164:167], v[56:59]
	v_mfma_f32_16x16x32_bf16 v[44:47], v[116:119], v[172:175], v[44:47]
	v_mfma_f32_16x16x32_bf16 v[40:43], v[140:143], v[172:175], v[40:43]
	v_mfma_f32_16x16x32_bf16 v[28:31], v[116:119], v[180:183], v[28:31]
	v_mfma_f32_16x16x32_bf16 v[24:27], v[140:143], v[180:183], v[24:27]
	v_mfma_f32_16x16x32_bf16 v[12:15], v[116:119], v[194:197], v[12:15]
	v_mfma_f32_16x16x32_bf16 v[8:11], v[140:143], v[194:197], v[8:11]
	s_setprio 0
	s_setprio 1
	v_mfma_f32_16x16x32_bf16 v[52:55], v[144:147], v[160:163], v[52:55]
	v_mfma_f32_16x16x32_bf16 v[48:51], v[152:155], v[160:163], v[48:51]
	v_mfma_f32_16x16x32_bf16 v[36:39], v[144:147], v[168:171], v[36:39]
	v_mfma_f32_16x16x32_bf16 v[32:35], v[152:155], v[168:171], v[32:35]
	v_mfma_f32_16x16x32_bf16 v[20:23], v[144:147], v[176:179], v[20:23]
	v_mfma_f32_16x16x32_bf16 v[16:19], v[152:155], v[176:179], v[16:19]
	v_mfma_f32_16x16x32_bf16 v[4:7], v[144:147], v[190:193], v[4:7]
	v_mfma_f32_16x16x32_bf16 v[0:3], v[152:155], v[190:193], v[0:3]
	v_mfma_f32_16x16x32_bf16 v[52:55], v[148:151], v[164:167], v[52:55]
	v_mfma_f32_16x16x32_bf16 v[48:51], v[156:159], v[164:167], v[48:51]
	v_mfma_f32_16x16x32_bf16 v[36:39], v[148:151], v[172:175], v[36:39]
	v_mfma_f32_16x16x32_bf16 v[32:35], v[156:159], v[172:175], v[32:35]
	v_mfma_f32_16x16x32_bf16 v[20:23], v[148:151], v[180:183], v[20:23]
	v_mfma_f32_16x16x32_bf16 v[16:19], v[156:159], v[180:183], v[16:19]
	v_mfma_f32_16x16x32_bf16 v[4:7], v[148:151], v[194:197], v[4:7]
	v_mfma_f32_16x16x32_bf16 v[0:3], v[156:159], v[194:197], v[0:3]
	s_setprio 0
	s_barrier
; #define PG8_STAGE(bufoff, gbase, voff) do { _Pragma("unroll") for (int _i = 0; _i < 2; ++_i) \
;         { unsigned _vo = (voff)[_i]; asm volatile("" : "+v"(_vo));     \
;         __builtin_amdgcn_global_load_lds((const unsigned*)((const char*)(gbase) + _vo), (PG8_LAS unsigned*)(lds + (bufoff) + ldsw + _i * 8192), 16, 0, 0); } } while (0)
; #define PG8_LDA(dst, b, h) do { _Pragma("unroll") for (int m = 0; m < 4; ++m) _Pragma("unroll") for (int k = 0; k < 2; ++k) dst[m][k] = *(const PG8_LAS bf16x8*)(lds + PG8_SA(b, h) + aoff + m * 2048 + k * 1024); } while (0)
; #define PG8_BAR __builtin_amdgcn_s_barrier()
; template <class Epi, class Sched, bool ALIGN_EPI = false, bool SP2 = false, bool ABLK = false, bool F8 = false>
; __device__ __forceinline__ void gemm_phase(PG8_LAS unsigned char* lds, const Gemm g, const Sched& S, const Epi& E, const int wave_s) {
;     ...
;         for (int t = 0; t < nt; t += 2) {
;             const bool last = (t == nt - 2);
;             const char* a1 = cA + (size_t)(t + 1) * kstepA;
;             const char* a2 = last ? nA : cA + (size_t)(t + 2) * kstepA; const char* b2 = last ? nB : cB + (size_t)(t + 2) * kstep;
;             const char* a3 = a2 + kstepA; const char* b3 = b2 + kstep;
;             if (last && has_next) { S.a_ready(nxt); if constexpr (Epi::PREF) E.prefetch(nxt, wid, lane); }
;             if constexpr (SP2) {
;             PG8_LDB(B0, 0, 0); PG8_LDB(B1, 0, 1); PG8_SCHED; PG8_LDA(At, 0, 0); PG8_STAGE(PG8_SA(1, 1), a1 + hstepA, voffA);
;             PG8_WAIT_V(8); PG8_WAIT_L(0); PG8_BAR; PG8_MMA(0, 0, At, B0); PG8_MMA(0, 1, At, B1); PG8_BAR; PG8_SCHED;
;             PG8_LDA(At, 0, 1); PG8_STAGE(PG8_SB(0, 0), b2, voffB); PG8_STAGE(PG8_SB(0, 1), b2 + hstep, voffB); PG8_STAGE(PG8_SA(0, 0), a2, voffA);
;             PG8_WAIT_V(8); PG8_WAIT_L(0); PG8_BAR; PG8_MMA(1, 0, At, B0); PG8_MMA(1, 1, At, B1); PG8_BAR; PG8_SCHED;
;             PG8_LDB(B0, 1, 0); PG8_LDB(B1, 1, 1); PG8_SCHED; PG8_LDA(At, 1, 0); PG8_STAGE(PG8_SA(0, 1), a2 + hstepA, voffA);
;             PG8_WAIT_V(8); PG8_WAIT_L(0); PG8_BAR; PG8_MMA(0, 0, At, B0); PG8_MMA(0, 1, At, B1); PG8_BAR; PG8_SCHED;
;             PG8_LDA(At, 1, 1); PG8_STAGE(PG8_SB(1, 0), b3, voffB); PG8_STAGE(PG8_SB(1, 1), b3 + hstep, voffB); PG8_STAGE(PG8_SA(1, 0), a3, voffA);
;             PG8_WAIT_V(8); PG8_WAIT_L(0); PG8_BAR; PG8_MMA(1, 0, At, B0); PG8_MMA(1, 1, At, B1); PG8_BAR; PG8_SCHED;
	s_add_i32 s72, 0, 0x18000
	s_add_i32 s73, 0, 0x1c000
	v_add_u32_e32 v140, s72, v227
	v_add_u32_e32 v156, s73, v227
	ds_read_b128 v[104:107], v140
	ds_read_b128 v[116:119], v140 offset:1024
	ds_read_b128 v[128:131], v140 offset:2048
	ds_read_b128 v[140:143], v140 offset:3072
	ds_read_b128 v[144:147], v156
	ds_read_b128 v[148:151], v156 offset:1024
	ds_read_b128 v[152:155], v156 offset:2048
	ds_read_b128 v[156:159], v156 offset:3072
	s_add_u32 s56, s56, 0x4000
	s_mov_b32 m0, s46
	ds_read_b128 v[160:163], v232 offset:32768
	ds_read_b128 v[164:167], v232 offset:33792
	ds_read_b128 v[168:171], v232 offset:34816
	ds_read_b128 v[172:175], v232 offset:35840
	ds_read_b128 v[176:179], v232 offset:36864
	ds_read_b128 v[180:183], v232 offset:37888
	ds_read_b128 v[190:193], v232 offset:38912
	ds_read_b128 v[194:197], v232 offset:39936
	s_addc_u32 s57, s57, 0
	s_nop 0
	global_load_lds_dwordx4 v222, s[56:57]
	s_mov_b32 m0, s47
	s_nop 0
	global_load_lds_dwordx4 v224, s[56:57]
	s_waitcnt vmcnt(8)
	s_waitcnt lgkmcnt(0)
	s_barrier
	s_setprio 1
	s_waitcnt lgkmcnt(0)
	v_mfma_f32_16x16x32_bf16 v[136:139], v[104:107], v[160:163], v[136:139]
	v_mfma_f32_16x16x32_bf16 v[132:135], v[128:131], v[160:163], v[132:135]
	v_mfma_f32_16x16x32_bf16 v[112:115], v[104:107], v[168:171], v[112:115]
	v_mfma_f32_16x16x32_bf16 v[108:111], v[128:131], v[168:171], v[108:111]
	v_mfma_f32_16x16x32_bf16 v[92:95], v[104:107], v[176:179], v[92:95]
	v_mfma_f32_16x16x32_bf16 v[88:91], v[128:131], v[176:179], v[88:91]
	v_mfma_f32_16x16x32_bf16 v[76:79], v[104:107], v[190:193], v[76:79]
	v_mfma_f32_16x16x32_bf16 v[72:75], v[128:131], v[190:193], v[72:75]
	v_mfma_f32_16x16x32_bf16 v[136:139], v[116:119], v[164:167], v[136:139]
	v_mfma_f32_16x16x32_bf16 v[132:135], v[140:143], v[164:167], v[132:135]
	v_mfma_f32_16x16x32_bf16 v[112:115], v[116:119], v[172:175], v[112:115]
	v_mfma_f32_16x16x32_bf16 v[108:111], v[140:143], v[172:175], v[108:111]
	v_mfma_f32_16x16x32_bf16 v[92:95], v[116:119], v[180:183], v[92:95]
	v_mfma_f32_16x16x32_bf16 v[88:91], v[140:143], v[180:183], v[88:91]
	v_mfma_f32_16x16x32_bf16 v[76:79], v[116:119], v[194:197], v[76:79]
	v_mfma_f32_16x16x32_bf16 v[72:75], v[140:143], v[194:197], v[72:75]
	s_setprio 0
	s_setprio 1
	v_mfma_f32_16x16x32_bf16 v[124:127], v[144:147], v[160:163], v[124:127]
	v_mfma_f32_16x16x32_bf16 v[120:123], v[152:155], v[160:163], v[120:123]
	v_mfma_f32_16x16x32_bf16 v[100:103], v[144:147], v[168:171], v[100:103]
	v_mfma_f32_16x16x32_bf16 v[96:99], v[152:155], v[168:171], v[96:99]
	v_mfma_f32_16x16x32_bf16 v[84:87], v[144:147], v[176:179], v[84:87]
	v_mfma_f32_16x16x32_bf16 v[80:83], v[152:155], v[176:179], v[80:83]
	v_mfma_f32_16x16x32_bf16 v[68:71], v[144:147], v[190:193], v[68:71]
	v_mfma_f32_16x16x32_bf16 v[64:67], v[152:155], v[190:193], v[64:67]
	v_mfma_f32_16x16x32_bf16 v[124:127], v[148:151], v[164:167], v[124:127]
	v_mfma_f32_16x16x32_bf16 v[120:123], v[156:159], v[164:167], v[120:123]
	v_mfma_f32_16x16x32_bf16 v[100:103], v[148:151], v[172:175], v[100:103]
	v_mfma_f32_16x16x32_bf16 v[96:99], v[156:159], v[172:175], v[96:99]
	v_mfma_f32_16x16x32_bf16 v[84:87], v[148:151], v[180:183], v[84:87]
	v_mfma_f32_16x16x32_bf16 v[80:83], v[156:159], v[180:183], v[80:83]
	v_mfma_f32_16x16x32_bf16 v[68:71], v[148:151], v[194:197], v[68:71]
	v_mfma_f32_16x16x32_bf16 v[64:67], v[156:159], v[194:197], v[64:67]
	s_setprio 0
	s_barrier
	ds_read_b128 v[160:163], v232 offset:49152
	ds_read_b128 v[164:167], v232 offset:50176
	ds_read_b128 v[168:171], v232 offset:51200
	ds_read_b128 v[172:175], v232 offset:52224
	ds_read_b128 v[176:179], v232 offset:53248
	ds_read_b128 v[180:183], v232 offset:54272
	ds_read_b128 v[190:193], v232 offset:55296
	ds_read_b128 v[194:197], v232 offset:56320
	s_add_i32 s56, s72, s3
	s_add_u32 vcc_lo, s54, s14
	s_addc_u32 vcc_hi, s55, s15
	s_mov_b32 m0, s56
	s_nop 0
	global_load_lds_dwordx4 v223, vcc
	s_add_i32 m0, s56, 0x2000
	s_nop 0
	s_add_u32 vcc_lo, s54, s14
	s_addc_u32 vcc_hi, s55, s15
	s_add_u32 s54, s54, 0x160080
	s_addc_u32 s55, s55, 0
	s_add_i32 s56, s73, s3
	global_load_lds_dwordx4 v225, vcc
	s_mov_b32 m0, s56
	s_nop 0
	global_load_lds_dwordx4 v223, s[54:55]
	s_add_i32 m0, s56, 0x2000
	s_nop 0
	global_load_lds_dwordx4 v225, s[54:55]
	s_mov_b32 m0, s59
	s_nop 0
	global_load_lds_dwordx4 v222, s[52:53]
	v_mov_b32_e32 v184, v224
	s_mov_b32 m0, s60
	s_nop 0
	global_load_lds_dwordx4 v224, s[52:53]
	s_waitcnt vmcnt(8)
	s_waitcnt lgkmcnt(0)
	s_barrier
	s_setprio 1
	s_waitcnt lgkmcnt(0)
	v_mfma_f32_16x16x32_bf16 v[60:63], v[104:107], v[160:163], v[60:63]
	v_mfma_f32_16x16x32_bf16 v[56:59], v[128:131], v[160:163], v[56:59]
	v_mfma_f32_16x16x32_bf16 v[44:47], v[104:107], v[168:171], v[44:47]
	v_mfma_f32_16x16x32_bf16 v[40:43], v[128:131], v[168:171], v[40:43]
	v_mfma_f32_16x16x32_bf16 v[28:31], v[104:107], v[176:179], v[28:31]
	v_mfma_f32_16x16x32_bf16 v[24:27], v[128:131], v[176:179], v[24:27]
	v_mfma_f32_16x16x32_bf16 v[12:15], v[104:107], v[190:193], v[12:15]
	v_mfma_f32_16x16x32_bf16 v[8:11], v[128:131], v[190:193], v[8:11]
	v_mfma_f32_16x16x32_bf16 v[60:63], v[116:119], v[164:167], v[60:63]
	v_mfma_f32_16x16x32_bf16 v[56:59], v[140:143], v[164:167], v[56:59]
	v_mfma_f32_16x16x32_bf16 v[44:47], v[116:119], v[172:175], v[44:47]
	v_mfma_f32_16x16x32_bf16 v[40:43], v[140:143], v[172:175], v[40:43]
	v_mfma_f32_16x16x32_bf16 v[28:31], v[116:119], v[180:183], v[28:31]
	v_mfma_f32_16x16x32_bf16 v[24:27], v[140:143], v[180:183], v[24:27]
	v_mfma_f32_16x16x32_bf16 v[12:15], v[116:119], v[194:197], v[12:15]
	v_mfma_f32_16x16x32_bf16 v[8:11], v[140:143], v[194:197], v[8:11]
	s_setprio 0
	s_setprio 1
	v_mfma_f32_16x16x32_bf16 v[52:55], v[144:147], v[160:163], v[52:55]
	v_mfma_f32_16x16x32_bf16 v[48:51], v[152:155], v[160:163], v[48:51]
	v_mfma_f32_16x16x32_bf16 v[36:39], v[144:147], v[168:171], v[36:39]
	v_mfma_f32_16x16x32_bf16 v[32:35], v[152:155], v[168:171], v[32:35]
	v_mfma_f32_16x16x32_bf16 v[20:23], v[144:147], v[176:179], v[20:23]
	v_mfma_f32_16x16x32_bf16 v[16:19], v[152:155], v[176:179], v[16:19]
	v_mfma_f32_16x16x32_bf16 v[4:7], v[144:147], v[190:193], v[4:7]
	v_mfma_f32_16x16x32_bf16 v[0:3], v[152:155], v[190:193], v[0:3]
	v_mfma_f32_16x16x32_bf16 v[52:55], v[148:151], v[164:167], v[52:55]
	v_mfma_f32_16x16x32_bf16 v[48:51], v[156:159], v[164:167], v[48:51]
	v_mfma_f32_16x16x32_bf16 v[36:39], v[148:151], v[172:175], v[36:39]
	v_mfma_f32_16x16x32_bf16 v[32:35], v[156:159], v[172:175], v[32:35]
	v_mfma_f32_16x16x32_bf16 v[20:23], v[148:151], v[180:183], v[20:23]
	v_mfma_f32_16x16x32_bf16 v[16:19], v[156:159], v[180:183], v[16:19]
	v_mfma_f32_16x16x32_bf16 v[4:7], v[148:151], v[194:197], v[4:7]
	v_mfma_f32_16x16x32_bf16 v[0:3], v[156:159], v[194:197], v[0:3]
	s_setprio 0
	s_barrier
	s_add_i32 s77, s77, 2
	s_add_u32 s67, s67, 0x100
	s_addc_u32 s76, s76, 0
	s_add_u32 s50, s50, 0x10000
	s_addc_u32 s51, s51, 0
	s_cmpk_gt_u32 s77, 0x55
	s_cbranch_scc0 .LBB0_304
	s_and_b64 vcc, exec, s[36:37]
	s_cbranch_vccz .LBB0_307
	s_barrier

;     __device__ bool next(int i, Unit& u) const { const bool r = base.next(i >> 1, u); u.kh = i & 1; return r; }
; #define PG8_LDA(dst, b, h) do { _Pragma("unroll") for (int m = 0; m < 4; ++m) _Pragma("unroll") for (int k = 0; k < 2; ++k) dst[m][k] = *(const PG8_LAS bf16x8*)(lds + PG8_SA(b, h) + aoff + m * 2048 + k * 1024); } while (0)
; template <class Epi, class Sched, bool ALIGN_EPI = false, bool SP2 = false, bool ABLK = false, bool F8 = false>
; __device__ __forceinline__ void gemm_phase(PG8_LAS unsigned char* lds, const Gemm g, const Sched& S, const Epi& E, const int wave_s) {
;     ...
;         const bool has_next = S.next(ui + 1, nxt); nxt.par = (ui + 1) & 1;
;         const char* nA = has_next ? (const char*)g.A + (size_t)nxt.pm * tstep + nxt.kh * khbA : cA; const char* nB = has_next ? (const char*)g.Bt + (size_t)nxt.pn * tstep + nxt.kh * khb : cB;
;         for (int t = 0; t < nt; t += 2) {
;             const bool last = (t == nt - 2);
;             const char* a1 = cA + (size_t)(t + 1) * kstepA;
;             const char* a2 = last ? nA : cA + (size_t)(t + 2) * kstepA; const char* b2 = last ? nB : cB + (size_t)(t + 2) * kstep;
;             const char* a3 = a2 + kstepA; const char* b3 = b2 + kstep;
;             if (last && has_next) { S.a_ready(nxt); if constexpr (Epi::PREF) E.prefetch(nxt, wid, lane); }
;             if constexpr (SP2) {
;             PG8_LDB(B0, 0, 0); PG8_LDB(B1, 0, 1); PG8_SCHED; PG8_LDA(At, 0, 0); PG8_STAGE(PG8_SA(1, 1), a1 + hstepA, voffA);
;             PG8_WAIT_V(8); PG8_WAIT_L(0); PG8_BAR; PG8_MMA(0, 0, At, B0); PG8_MMA(0, 1, At, B1); PG8_BAR; PG8_SCHED;
;             PG8_LDA(At, 0, 1); PG8_STAGE(PG8_SB(0, 0), b2, voffB); PG8_STAGE(PG8_SB(0, 1), b2 + hstep, voffB); PG8_STAGE(PG8_SA(0, 0), a2, voffA);
;             PG8_WAIT_V(8); PG8_WAIT_L(0); PG8_BAR; PG8_MMA(1, 0, At, B0); PG8_MMA(1, 1, At, B1); PG8_BAR; PG8_SCHED;
;             PG8_LDB(B0, 1, 0); PG8_LDB(B1, 1, 1); PG8_SCHED; PG8_LDA(At, 1, 0); PG8_STAGE(PG8_SA(0, 1), a2 + hstepA, voffA);
;             PG8_WAIT_V(8); PG8_WAIT_L(0); PG8_BAR; PG8_MMA(0, 0, At, B0); PG8_MMA(0, 1, At, B1); PG8_BAR; PG8_SCHED;
;             PG8_LDA(At, 1, 1); PG8_STAGE(PG8_SB(1, 0), b3, voffB); PG8_STAGE(PG8_SB(1, 1), b3 + hstep, voffB); PG8_STAGE(PG8_SA(1, 0), a3, voffA);
;             PG8_WAIT_V(8); PG8_WAIT_L(0); PG8_BAR; PG8_MMA(1, 0, At, B0); PG8_MMA(1, 1, At, B1); PG8_BAR; PG8_SCHED;
.LBB0_395:
	ds_read_b128 v[140:143], v176
	ds_read_b128 v[144:147], v176 offset:1024
	ds_read_b128 v[148:151], v176 offset:2048
	ds_read_b128 v[152:155], v176 offset:3072
	ds_read_b128 v[188:191], v177
	ds_read_b128 v[192:195], v177 offset:1024
	ds_read_b128 v[196:199], v177 offset:2048
	ds_read_b128 v[200:203], v177 offset:3072
	s_add_u32 s64, s62, 0xfff80080
	s_addc_u32 s65, s63, -1
	s_cmp_eq_u32 vcc_lo, 28
	s_cselect_b32 s65, s20, s65
	s_cselect_b32 s64, s23, s64
	s_cselect_b32 s67, s51, s61
	s_cselect_b32 s66, s53, s59
	ds_read_b128 v[204:207], v178
	ds_read_b128 v[208:211], v178 offset:1024
	ds_read_b128 v[212:215], v178 offset:2048
	ds_read_b128 v[216:219], v178 offset:3072
	ds_read_b128 v[220:223], v178 offset:4096
	ds_read_b128 v[224:227], v178 offset:5120
	ds_read_b128 v[230:233], v178 offset:6144
	ds_read_b128 v[234:237], v178 offset:7168
	s_add_i32 m0, s78, 0xc000
	s_nop 0
	global_load_lds_dwordx4 v158, s[62:63]
	s_add_i32 m0, s78, 0xe000
	s_nop 0
	global_load_lds_dwordx4 v160, s[62:63]
	s_waitcnt vmcnt(8)
	s_waitcnt lgkmcnt(0)
	s_barrier
	s_setprio 1
	s_waitcnt lgkmcnt(0)
	v_mfma_f32_16x16x32_bf16 v[124:127], v[140:143], v[204:207], v[124:127]
	v_mfma_f32_16x16x32_bf16 v[120:123], v[148:151], v[204:207], v[120:123]
	v_mfma_f32_16x16x32_bf16 v[108:111], v[140:143], v[212:215], v[108:111]
	v_mfma_f32_16x16x32_bf16 v[104:107], v[148:151], v[212:215], v[104:107]
	v_mfma_f32_16x16x32_bf16 v[92:95], v[140:143], v[220:223], v[92:95]
	v_mfma_f32_16x16x32_bf16 v[88:91], v[148:151], v[220:223], v[88:91]
	v_mfma_f32_16x16x32_bf16 v[76:79], v[140:143], v[230:233], v[76:79]
	v_mfma_f32_16x16x32_bf16 v[72:75], v[148:151], v[230:233], v[72:75]
	v_mfma_f32_16x16x32_bf16 v[124:127], v[144:147], v[208:211], v[124:127]
	v_mfma_f32_16x16x32_bf16 v[120:123], v[152:155], v[208:211], v[120:123]
	v_mfma_f32_16x16x32_bf16 v[108:111], v[144:147], v[216:219], v[108:111]
	v_mfma_f32_16x16x32_bf16 v[104:107], v[152:155], v[216:219], v[104:107]
	v_mfma_f32_16x16x32_bf16 v[92:95], v[144:147], v[224:227], v[92:95]
	v_mfma_f32_16x16x32_bf16 v[88:91], v[152:155], v[224:227], v[88:91]
	v_mfma_f32_16x16x32_bf16 v[76:79], v[144:147], v[234:237], v[76:79]
	v_mfma_f32_16x16x32_bf16 v[72:75], v[152:155], v[234:237], v[72:75]
	s_setprio 0
	s_setprio 1
	v_mfma_f32_16x16x32_bf16 v[116:119], v[188:191], v[204:207], v[116:119]
	v_mfma_f32_16x16x32_bf16 v[112:115], v[196:199], v[204:207], v[112:115]
	v_mfma_f32_16x16x32_bf16 v[100:103], v[188:191], v[212:215], v[100:103]
	v_mfma_f32_16x16x32_bf16 v[96:99], v[196:199], v[212:215], v[96:99]
	v_mfma_f32_16x16x32_bf16 v[84:87], v[188:191], v[220:223], v[84:87]
	v_mfma_f32_16x16x32_bf16 v[80:83], v[196:199], v[220:223], v[80:83]
	v_mfma_f32_16x16x32_bf16 v[68:71], v[188:191], v[230:233], v[68:71]
	v_mfma_f32_16x16x32_bf16 v[64:67], v[196:199], v[230:233], v[64:67]
	v_mfma_f32_16x16x32_bf16 v[116:119], v[192:195], v[208:211], v[116:119]
	v_mfma_f32_16x16x32_bf16 v[112:115], v[200:203], v[208:211], v[112:115]
	v_mfma_f32_16x16x32_bf16 v[100:103], v[192:195], v[216:219], v[100:103]
	v_mfma_f32_16x16x32_bf16 v[96:99], v[200:203], v[216:219], v[96:99]
	v_mfma_f32_16x16x32_bf16 v[84:87], v[192:195], v[224:227], v[84:87]
	v_mfma_f32_16x16x32_bf16 v[80:83], v[200:203], v[224:227], v[80:83]
	v_mfma_f32_16x16x32_bf16 v[68:71], v[192:195], v[234:237], v[68:71]
	v_mfma_f32_16x16x32_bf16 v[64:67], v[200:203], v[234:237], v[64:67]
	s_setprio 0
	s_barrier
	s_add_i32 s72, s21, s3
	ds_read_b128 v[204:207], v178 offset:16384
	ds_read_b128 v[208:211], v178 offset:17408
	ds_read_b128 v[212:215], v178 offset:18432
	ds_read_b128 v[216:219], v178 offset:19456
	ds_read_b128 v[220:223], v178 offset:20480
	ds_read_b128 v[224:227], v178 offset:21504
	ds_read_b128 v[230:233], v178 offset:22528
	ds_read_b128 v[234:237], v178 offset:23552
	s_mov_b32 m0, s72
	s_nop 0
	global_load_lds_dwordx4 v159, s[66:67]
	s_add_i32 m0, s72, 0x2000
	s_add_u32 s72, s66, 0x80000
	global_load_lds_dwordx4 v161, s[66:67]
	s_addc_u32 s73, s67, 0
	s_add_i32 s96, s22, s3
	s_mov_b32 m0, s96
	s_nop 0
	global_load_lds_dwordx4 v159, s[72:73]
	s_add_i32 m0, s96, 0x2000
	s_nop 0
	global_load_lds_dwordx4 v161, s[72:73]
	s_mov_b32 m0, s78
	s_nop 0
	global_load_lds_dwordx4 v158, s[64:65]
	s_mov_b32 m0, s79
	s_nop 0
	global_load_lds_dwordx4 v160, s[64:65]
	s_waitcnt vmcnt(8)
	s_waitcnt lgkmcnt(0)
	s_barrier
	s_setprio 1
	s_waitcnt lgkmcnt(0)
	v_mfma_f32_16x16x32_bf16 v[60:63], v[140:143], v[204:207], v[60:63]
	v_mfma_f32_16x16x32_bf16 v[56:59], v[148:151], v[204:207], v[56:59]
	v_mfma_f32_16x16x32_bf16 v[44:47], v[140:143], v[212:215], v[44:47]
	v_mfma_f32_16x16x32_bf16 v[40:43], v[148:151], v[212:215], v[40:43]
	v_mfma_f32_16x16x32_bf16 v[28:31], v[140:143], v[220:223], v[28:31]
	v_mfma_f32_16x16x32_bf16 v[24:27], v[148:151], v[220:223], v[24:27]
	v_mfma_f32_16x16x32_bf16 v[12:15], v[140:143], v[230:233], v[12:15]
	v_mfma_f32_16x16x32_bf16 v[8:11], v[148:151], v[230:233], v[8:11]
	v_mfma_f32_16x16x32_bf16 v[60:63], v[144:147], v[208:211], v[60:63]
	v_mfma_f32_16x16x32_bf16 v[56:59], v[152:155], v[208:211], v[56:59]
	v_mfma_f32_16x16x32_bf16 v[44:47], v[144:147], v[216:219], v[44:47]
	v_mfma_f32_16x16x32_bf16 v[40:43], v[152:155], v[216:219], v[40:43]
	v_mfma_f32_16x16x32_bf16 v[28:31], v[144:147], v[224:227], v[28:31]
	v_mfma_f32_16x16x32_bf16 v[24:27], v[152:155], v[224:227], v[24:27]
	v_mfma_f32_16x16x32_bf16 v[12:15], v[144:147], v[234:237], v[12:15]
	v_mfma_f32_16x16x32_bf16 v[8:11], v[152:155], v[234:237], v[8:11]
	s_setprio 0
	s_setprio 1
	v_mfma_f32_16x16x32_bf16 v[52:55], v[188:191], v[204:207], v[52:55]
	v_mfma_f32_16x16x32_bf16 v[48:51], v[196:199], v[204:207], v[48:51]
	v_mfma_f32_16x16x32_bf16 v[36:39], v[188:191], v[212:215], v[36:39]
	v_mfma_f32_16x16x32_bf16 v[32:35], v[196:199], v[212:215], v[32:35]
	v_mfma_f32_16x16x32_bf16 v[20:23], v[188:191], v[220:223], v[20:23]
	v_mfma_f32_16x16x32_bf16 v[16:19], v[196:199], v[220:223], v[16:19]
	v_mfma_f32_16x16x32_bf16 v[4:7], v[188:191], v[230:233], v[4:7]
	v_mfma_f32_16x16x32_bf16 v[0:3], v[196:199], v[230:233], v[0:3]
	v_mfma_f32_16x16x32_bf16 v[52:55], v[192:195], v[208:211], v[52:55]
	v_mfma_f32_16x16x32_bf16 v[48:51], v[200:203], v[208:211], v[48:51]
	v_mfma_f32_16x16x32_bf16 v[36:39], v[192:195], v[216:219], v[36:39]
	v_mfma_f32_16x16x32_bf16 v[32:35], v[200:203], v[216:219], v[32:35]
	v_mfma_f32_16x16x32_bf16 v[20:23], v[192:195], v[224:227], v[20:23]
	v_mfma_f32_16x16x32_bf16 v[16:19], v[200:203], v[224:227], v[16:19]
	v_mfma_f32_16x16x32_bf16 v[4:7], v[192:195], v[234:237], v[4:7]
	v_mfma_f32_16x16x32_bf16 v[0:3], v[200:203], v[234:237], v[0:3]
	s_setprio 0
	s_barrier
; #define PG8_STAGE(bufoff, gbase, voff) do { _Pragma("unroll") for (int _i = 0; _i < 2; ++_i) \
;         { unsigned _vo = (voff)[_i]; asm volatile("" : "+v"(_vo));     \
;         __builtin_amdgcn_global_load_lds((const unsigned*)((const char*)(gbase) + _vo), (PG8_LAS unsigned*)(lds + (bufoff) + ldsw + _i * 8192), 16, 0, 0); } } while (0)
; #define PG8_LDA(dst, b, h) do { _Pragma("unroll") for (int m = 0; m < 4; ++m) _Pragma("unroll") for (int k = 0; k < 2; ++k) dst[m][k] = *(const PG8_LAS bf16x8*)(lds + PG8_SA(b, h) + aoff + m * 2048 + k * 1024); } while (0)
; #define PG8_LDB(dst, b, h) do { _Pragma("unroll") for (int n = 0; n < 2; ++n) _Pragma("unroll") for (int k = 0; k < 2; ++k) dst[n][k] = *(const PG8_LAS bf16x8*)(lds + PG8_SB(b, h) + boff + n * 2048 + k * 1024); } while (0)
; #define PG8_WAIT_V(n) asm volatile("s_waitcnt vmcnt(" #n ")" ::: "memory")
; #define PG8_WAIT_L(n) asm volatile("s_waitcnt lgkmcnt(" #n ")" ::: "memory")
; #define PG8_BAR __builtin_amdgcn_s_barrier()
; #define PG8_SCHED __builtin_amdgcn_sched_barrier(0)
; template <class Epi, class Sched, bool ALIGN_EPI = false, bool SP2 = false, bool ABLK = false, bool F8 = false>
; __device__ __forceinline__ void gemm_phase(PG8_LAS unsigned char* lds, const Gemm g, const Sched& S, const Epi& E, const int wave_s) {
;     ...
;             PG8_LDB(B0, 0, 0); PG8_LDB(B1, 0, 1); PG8_SCHED; PG8_LDA(At, 0, 0); PG8_STAGE(PG8_SA(1, 1), a1 + hstepA, voffA);
;             PG8_WAIT_V(8); PG8_WAIT_L(0); PG8_BAR; PG8_MMA(0, 0, At, B0); PG8_MMA(0, 1, At, B1); PG8_BAR; PG8_SCHED;
;             PG8_LDA(At, 0, 1); PG8_STAGE(PG8_SB(0, 0), b2, voffB); PG8_STAGE(PG8_SB(0, 1), b2 + hstep, voffB); PG8_STAGE(PG8_SA(0, 0), a2, voffA);
;             PG8_WAIT_V(8); PG8_WAIT_L(0); PG8_BAR; PG8_MMA(1, 0, At, B0); PG8_MMA(1, 1, At, B1); PG8_BAR; PG8_SCHED;
;             PG8_LDB(B0, 1, 0); PG8_LDB(B1, 1, 1); PG8_SCHED; PG8_LDA(At, 1, 0); PG8_STAGE(PG8_SA(0, 1), a2 + hstepA, voffA);
;             PG8_WAIT_V(8); PG8_WAIT_L(0); PG8_BAR; PG8_MMA(0, 0, At, B0); PG8_MMA(0, 1, At, B1); PG8_BAR; PG8_SCHED;
;             PG8_LDA(At, 1, 1); PG8_STAGE(PG8_SB(1, 0), b3, voffB); PG8_STAGE(PG8_SB(1, 1), b3 + hstep, voffB); PG8_STAGE(PG8_SA(1, 0), a3, voffA);
;             PG8_WAIT_V(8); PG8_WAIT_L(0); PG8_BAR; PG8_MMA(1, 0, At, B0); PG8_MMA(1, 1, At, B1); PG8_BAR; PG8_SCHED;
	s_add_i32 s96, 0, 0x18000
	v_add_u32_e32 v128, s96, v165
	s_add_i32 vcc_hi, 0, 0x1c000
	ds_read_b128 v[140:143], v128
	ds_read_b128 v[144:147], v128 offset:1024
	ds_read_b128 v[148:151], v128 offset:2048
	ds_read_b128 v[152:155], v128 offset:3072
	v_add_u32_e32 v128, vcc_hi, v165
	ds_read_b128 v[188:191], v128
	ds_read_b128 v[192:195], v128 offset:1024
	ds_read_b128 v[196:199], v128 offset:2048
	ds_read_b128 v[200:203], v128 offset:3072
	s_add_u32 s72, s64, 0x80000
	s_mov_b32 m0, s80
	ds_read_b128 v[204:207], v178 offset:32768
	ds_read_b128 v[208:211], v178 offset:33792
	ds_read_b128 v[212:215], v178 offset:34816
	ds_read_b128 v[216:219], v178 offset:35840
	ds_read_b128 v[220:223], v178 offset:36864
	ds_read_b128 v[224:227], v178 offset:37888
	ds_read_b128 v[230:233], v178 offset:38912
	ds_read_b128 v[234:237], v178 offset:39936
	s_addc_u32 s73, s65, 0
	s_nop 0
	global_load_lds_dwordx4 v158, s[72:73]
	s_mov_b32 m0, s81
	s_nop 0
	global_load_lds_dwordx4 v160, s[72:73]
	s_waitcnt vmcnt(8)
	s_waitcnt lgkmcnt(0)
	s_barrier
	s_setprio 1
	s_waitcnt lgkmcnt(0)
	v_mfma_f32_16x16x32_bf16 v[124:127], v[140:143], v[204:207], v[124:127]
	v_mfma_f32_16x16x32_bf16 v[120:123], v[148:151], v[204:207], v[120:123]
	v_mfma_f32_16x16x32_bf16 v[108:111], v[140:143], v[212:215], v[108:111]
	v_mfma_f32_16x16x32_bf16 v[104:107], v[148:151], v[212:215], v[104:107]
	v_mfma_f32_16x16x32_bf16 v[92:95], v[140:143], v[220:223], v[92:95]
	v_mfma_f32_16x16x32_bf16 v[88:91], v[148:151], v[220:223], v[88:91]
	v_mfma_f32_16x16x32_bf16 v[76:79], v[140:143], v[230:233], v[76:79]
	v_mfma_f32_16x16x32_bf16 v[72:75], v[148:151], v[230:233], v[72:75]
	v_mfma_f32_16x16x32_bf16 v[124:127], v[144:147], v[208:211], v[124:127]
	v_mfma_f32_16x16x32_bf16 v[120:123], v[152:155], v[208:211], v[120:123]
	v_mfma_f32_16x16x32_bf16 v[108:111], v[144:147], v[216:219], v[108:111]
	v_mfma_f32_16x16x32_bf16 v[104:107], v[152:155], v[216:219], v[104:107]
	v_mfma_f32_16x16x32_bf16 v[92:95], v[144:147], v[224:227], v[92:95]
	v_mfma_f32_16x16x32_bf16 v[88:91], v[152:155], v[224:227], v[88:91]
	v_mfma_f32_16x16x32_bf16 v[76:79], v[144:147], v[234:237], v[76:79]
	v_mfma_f32_16x16x32_bf16 v[72:75], v[152:155], v[234:237], v[72:75]
	s_setprio 0
	s_setprio 1
	v_mfma_f32_16x16x32_bf16 v[116:119], v[188:191], v[204:207], v[116:119]
	v_mfma_f32_16x16x32_bf16 v[112:115], v[196:199], v[204:207], v[112:115]
	v_mfma_f32_16x16x32_bf16 v[100:103], v[188:191], v[212:215], v[100:103]
	v_mfma_f32_16x16x32_bf16 v[96:99], v[196:199], v[212:215], v[96:99]
	v_mfma_f32_16x16x32_bf16 v[84:87], v[188:191], v[220:223], v[84:87]
	v_mfma_f32_16x16x32_bf16 v[80:83], v[196:199], v[220:223], v[80:83]
	v_mfma_f32_16x16x32_bf16 v[68:71], v[188:191], v[230:233], v[68:71]
	v_mfma_f32_16x16x32_bf16 v[64:67], v[196:199], v[230:233], v[64:67]
	v_mfma_f32_16x16x32_bf16 v[116:119], v[192:195], v[208:211], v[116:119]
	v_mfma_f32_16x16x32_bf16 v[112:115], v[200:203], v[208:211], v[112:115]
	v_mfma_f32_16x16x32_bf16 v[100:103], v[192:195], v[216:219], v[100:103]
	v_mfma_f32_16x16x32_bf16 v[96:99], v[200:203], v[216:219], v[96:99]
	v_mfma_f32_16x16x32_bf16 v[84:87], v[192:195], v[224:227], v[84:87]
	v_mfma_f32_16x16x32_bf16 v[80:83], v[200:203], v[224:227], v[80:83]
	v_mfma_f32_16x16x32_bf16 v[68:71], v[192:195], v[234:237], v[68:71]
	v_mfma_f32_16x16x32_bf16 v[64:67], v[200:203], v[234:237], v[64:67]
	s_setprio 0
	s_barrier
; #define PG8_STAGE(bufoff, gbase, voff) do { _Pragma("unroll") for (int _i = 0; _i < 2; ++_i) \
;         { unsigned _vo = (voff)[_i]; asm volatile("" : "+v"(_vo));     \
;         __builtin_amdgcn_global_load_lds((const unsigned*)((const char*)(gbase) + _vo), (PG8_LAS unsigned*)(lds + (bufoff) + ldsw + _i * 8192), 16, 0, 0); } } while (0)
; #define PG8_LDA(dst, b, h) do { _Pragma("unroll") for (int m = 0; m < 4; ++m) _Pragma("unroll") for (int k = 0; k < 2; ++k) dst[m][k] = *(const PG8_LAS bf16x8*)(lds + PG8_SA(b, h) + aoff + m * 2048 + k * 1024); } while (0)
; #define PG8_BAR __builtin_amdgcn_s_barrier()
; template <class Epi, class Sched, bool ALIGN_EPI = false, bool SP2 = false, bool ABLK = false, bool F8 = false>
; __device__ __forceinline__ void gemm_phase(PG8_LAS unsigned char* lds, const Gemm g, const Sched& S, const Epi& E, const int wave_s) {
;     ...
;         for (int t = 0; t < nt; t += 2) {
;             const bool last = (t == nt - 2);
;             const char* a1 = cA + (size_t)(t + 1) * kstepA;
;             const char* a2 = last ? nA : cA + (size_t)(t + 2) * kstepA; const char* b2 = last ? nB : cB + (size_t)(t + 2) * kstep;
;             const char* a3 = a2 + kstepA; const char* b3 = b2 + kstep;
;             if (last && has_next) { S.a_ready(nxt); if constexpr (Epi::PREF) E.prefetch(nxt, wid, lane); }
;             if constexpr (SP2) {
;             PG8_LDB(B0, 0, 0); PG8_LDB(B1, 0, 1); PG8_SCHED; PG8_LDA(At, 0, 0); PG8_STAGE(PG8_SA(1, 1), a1 + hstepA, voffA);
;             PG8_WAIT_V(8); PG8_WAIT_L(0); PG8_BAR; PG8_MMA(0, 0, At, B0); PG8_MMA(0, 1, At, B1); PG8_BAR; PG8_SCHED;
;             PG8_LDA(At, 0, 1); PG8_STAGE(PG8_SB(0, 0), b2, voffB); PG8_STAGE(PG8_SB(0, 1), b2 + hstep, voffB); PG8_STAGE(PG8_SA(0, 0), a2, voffA);
;             PG8_WAIT_V(8); PG8_WAIT_L(0); PG8_BAR; PG8_MMA(1, 0, At, B0); PG8_MMA(1, 1, At, B1); PG8_BAR; PG8_SCHED;
;             PG8_LDB(B0, 1, 0); PG8_LDB(B1, 1, 1); PG8_SCHED; PG8_LDA(At, 1, 0); PG8_STAGE(PG8_SA(0, 1), a2 + hstepA, voffA);
;             PG8_WAIT_V(8); PG8_WAIT_L(0); PG8_BAR; PG8_MMA(0, 0, At, B0); PG8_MMA(0, 1, At, B1); PG8_BAR; PG8_SCHED;
;             PG8_LDA(At, 1, 1); PG8_STAGE(PG8_SB(1, 0), b3, voffB); PG8_STAGE(PG8_SB(1, 1), b3 + hstep, voffB); PG8_STAGE(PG8_SA(1, 0), a3, voffA);
;             PG8_WAIT_V(8); PG8_WAIT_L(0); PG8_BAR; PG8_MMA(1, 0, At, B0); PG8_MMA(1, 1, At, B1); PG8_BAR; PG8_SCHED;
	v_mov_b32_e32 v128, v159
	ds_read_b128 v[204:207], v178 offset:49152
	ds_read_b128 v[208:211], v178 offset:50176
	ds_read_b128 v[212:215], v178 offset:51200
	ds_read_b128 v[216:219], v178 offset:52224
	ds_read_b128 v[220:223], v178 offset:53248
	ds_read_b128 v[224:227], v178 offset:54272
	ds_read_b128 v[230:233], v178 offset:55296
	ds_read_b128 v[234:237], v178 offset:56320
	s_add_i32 s72, s96, s3
	v_lshl_add_u64 v[156:157], s[66:67], 0, v[128:129]
	v_lshl_add_u64 v[156:157], v[156:157], 0, s[12:13]
	s_mov_b32 m0, s72
	v_mov_b32_e32 v128, v161
	global_load_lds_dwordx4 v[156:157], off
	s_add_i32 m0, s72, 0x2000
	s_nop 0
	v_lshl_add_u64 v[156:157], s[66:67], 0, v[128:129]
	s_add_u32 s66, s66, 0x80080
	v_lshl_add_u64 v[156:157], v[156:157], 0, s[12:13]
	s_addc_u32 s67, s67, 0
	s_add_i32 s72, vcc_hi, s3
	global_load_lds_dwordx4 v[156:157], off
	s_mov_b32 m0, s72
	s_nop 0
	global_load_lds_dwordx4 v159, s[66:67]
	s_add_i32 m0, s72, 0x2000
	s_nop 0
	global_load_lds_dwordx4 v161, s[66:67]
	v_mov_b32_e32 v128, v158
	s_mov_b32 m0, s46
	v_lshl_add_u64 v[156:157], s[64:65], 0, v[128:129]
	v_lshl_add_u64 v[156:157], v[156:157], 0, s[12:13]
	v_mov_b32_e32 v128, v160
	global_load_lds_dwordx4 v[156:157], off
	s_mov_b32 m0, s47
	v_lshl_add_u64 v[156:157], s[64:65], 0, v[128:129]
	v_lshl_add_u64 v[156:157], v[156:157], 0, s[12:13]
	global_load_lds_dwordx4 v[156:157], off
	s_waitcnt vmcnt(8)
	s_waitcnt lgkmcnt(0)
	s_barrier
	s_setprio 1
	s_waitcnt lgkmcnt(0)
	v_mfma_f32_16x16x32_bf16 v[60:63], v[140:143], v[204:207], v[60:63]
	v_mfma_f32_16x16x32_bf16 v[56:59], v[148:151], v[204:207], v[56:59]
	v_mfma_f32_16x16x32_bf16 v[44:47], v[140:143], v[212:215], v[44:47]
	v_mfma_f32_16x16x32_bf16 v[40:43], v[148:151], v[212:215], v[40:43]
	v_mfma_f32_16x16x32_bf16 v[28:31], v[140:143], v[220:223], v[28:31]
	v_mfma_f32_16x16x32_bf16 v[24:27], v[148:151], v[220:223], v[24:27]
	v_mfma_f32_16x16x32_bf16 v[12:15], v[140:143], v[230:233], v[12:15]
	v_mfma_f32_16x16x32_bf16 v[8:11], v[148:151], v[230:233], v[8:11]
	v_mfma_f32_16x16x32_bf16 v[60:63], v[144:147], v[208:211], v[60:63]
	v_mfma_f32_16x16x32_bf16 v[56:59], v[152:155], v[208:211], v[56:59]
	v_mfma_f32_16x16x32_bf16 v[44:47], v[144:147], v[216:219], v[44:47]
	v_mfma_f32_16x16x32_bf16 v[40:43], v[152:155], v[216:219], v[40:43]
	v_mfma_f32_16x16x32_bf16 v[28:31], v[144:147], v[224:227], v[28:31]
	v_mfma_f32_16x16x32_bf16 v[24:27], v[152:155], v[224:227], v[24:27]
	v_mfma_f32_16x16x32_bf16 v[12:15], v[144:147], v[234:237], v[12:15]
	v_mfma_f32_16x16x32_bf16 v[8:11], v[152:155], v[234:237], v[8:11]
	s_setprio 0
	s_setprio 1
	v_mfma_f32_16x16x32_bf16 v[52:55], v[188:191], v[204:207], v[52:55]
	v_mfma_f32_16x16x32_bf16 v[48:51], v[196:199], v[204:207], v[48:51]
	v_mfma_f32_16x16x32_bf16 v[36:39], v[188:191], v[212:215], v[36:39]
	v_mfma_f32_16x16x32_bf16 v[32:35], v[196:199], v[212:215], v[32:35]
	v_mfma_f32_16x16x32_bf16 v[20:23], v[188:191], v[220:223], v[20:23]
	v_mfma_f32_16x16x32_bf16 v[16:19], v[196:199], v[220:223], v[16:19]
	v_mfma_f32_16x16x32_bf16 v[4:7], v[188:191], v[230:233], v[4:7]
	v_mfma_f32_16x16x32_bf16 v[0:3], v[196:199], v[230:233], v[0:3]
	v_mfma_f32_16x16x32_bf16 v[52:55], v[192:195], v[208:211], v[52:55]
	v_mfma_f32_16x16x32_bf16 v[48:51], v[200:203], v[208:211], v[48:51]
	v_mfma_f32_16x16x32_bf16 v[36:39], v[192:195], v[216:219], v[36:39]
	v_mfma_f32_16x16x32_bf16 v[32:35], v[200:203], v[216:219], v[32:35]
	v_mfma_f32_16x16x32_bf16 v[20:23], v[192:195], v[224:227], v[20:23]
	v_mfma_f32_16x16x32_bf16 v[16:19], v[200:203], v[224:227], v[16:19]
	v_mfma_f32_16x16x32_bf16 v[4:7], v[192:195], v[234:237], v[4:7]
	v_mfma_f32_16x16x32_bf16 v[0:3], v[200:203], v[234:237], v[0:3]
	s_setprio 0
	s_barrier
	s_add_i32 vcc_lo, vcc_lo, 2
	s_add_u32 s62, s62, 0x100
	s_addc_u32 s63, s63, 0
	s_add_u32 s59, s59, 0x100
	s_addc_u32 s61, s61, 0
	s_cmp_gt_u32 vcc_lo, 29
	s_cbranch_scc0 .LBB0_395
	s_and_b64 vcc, exec, s[36:37]
	s_cbranch_vccz .LBB0_398
	s_barrier

;     __device__ bool next(int i, Unit& u) const { const bool r = base.next(i >> 1, u); u.kh = i & 1; return r; }
; #define PG8_LDA(dst, b, h) do { _Pragma("unroll") for (int m = 0; m < 4; ++m) _Pragma("unroll") for (int k = 0; k < 2; ++k) dst[m][k] = *(const PG8_LAS bf16x8*)(lds + PG8_SA(b, h) + aoff + m * 2048 + k * 1024); } while (0)
; template <class Epi, class Sched, bool ALIGN_EPI = false, bool SP2 = false, bool ABLK = false, bool F8 = false>
; __device__ __forceinline__ void gemm_phase(PG8_LAS unsigned char* lds, const Gemm g, const Sched& S, const Epi& E, const int wave_s) {
;     ...
;         const bool has_next = S.next(ui + 1, nxt); nxt.par = (ui + 1) & 1;
;         const char* nA = has_next ? (const char*)g.A + (size_t)nxt.pm * tstep + nxt.kh * khbA : cA; const char* nB = has_next ? (const char*)g.Bt + (size_t)nxt.pn * tstep + nxt.kh * khb : cB;
;         for (int t = 0; t < nt; t += 2) {
;             const bool last = (t == nt - 2);
;             const char* a1 = cA + (size_t)(t + 1) * kstepA;
;             const char* a2 = last ? nA : cA + (size_t)(t + 2) * kstepA; const char* b2 = last ? nB : cB + (size_t)(t + 2) * kstep;
;             const char* a3 = a2 + kstepA; const char* b3 = b2 + kstep;
;             if (last && has_next) { S.a_ready(nxt); if constexpr (Epi::PREF) E.prefetch(nxt, wid, lane); }
;             if constexpr (SP2) {
;             PG8_LDB(B0, 0, 0); PG8_LDB(B1, 0, 1); PG8_SCHED; PG8_LDA(At, 0, 0); PG8_STAGE(PG8_SA(1, 1), a1 + hstepA, voffA);
;             PG8_WAIT_V(8); PG8_WAIT_L(0); PG8_BAR; PG8_MMA(0, 0, At, B0); PG8_MMA(0, 1, At, B1); PG8_BAR; PG8_SCHED;
;             PG8_LDA(At, 0, 1); PG8_STAGE(PG8_SB(0, 0), b2, voffB); PG8_STAGE(PG8_SB(0, 1), b2 + hstep, voffB); PG8_STAGE(PG8_SA(0, 0), a2, voffA);
;             PG8_WAIT_V(8); PG8_WAIT_L(0); PG8_BAR; PG8_MMA(1, 0, At, B0); PG8_MMA(1, 1, At, B1); PG8_BAR; PG8_SCHED;
;             PG8_LDB(B0, 1, 0); PG8_LDB(B1, 1, 1); PG8_SCHED; PG8_LDA(At, 1, 0); PG8_STAGE(PG8_SA(0, 1), a2 + hstepA, voffA);
;             PG8_WAIT_V(8); PG8_WAIT_L(0); PG8_BAR; PG8_MMA(0, 0, At, B0); PG8_MMA(0, 1, At, B1); PG8_BAR; PG8_SCHED;
;             PG8_LDA(At, 1, 1); PG8_STAGE(PG8_SB(1, 0), b3, voffB); PG8_STAGE(PG8_SB(1, 1), b3 + hstep, voffB); PG8_STAGE(PG8_SA(1, 0), a3, voffA);
;             PG8_WAIT_V(8); PG8_WAIT_L(0); PG8_BAR; PG8_MMA(1, 0, At, B0); PG8_MMA(1, 1, At, B1); PG8_BAR; PG8_SCHED;
.LBB0_592:
	ds_read_b128 v[64:67], v236
	ds_read_b128 v[68:71], v236 offset:1024
	ds_read_b128 v[76:79], v236 offset:2048
	ds_read_b128 v[80:83], v236 offset:3072
	ds_read_b128 v[88:91], v237
	ds_read_b128 v[100:103], v237 offset:1024
	ds_read_b128 v[112:115], v237 offset:2048
	ds_read_b128 v[124:127], v237 offset:3072
	s_add_u32 s62, s60, 0xfffc0080
	s_addc_u32 s63, s61, -1
	s_cmp_eq_u32 s76, 12
	s_cselect_b32 s63, s51, s63
	s_cselect_b32 s62, s57, s62
	s_cselect_b32 s65, s49, s75
	s_cselect_b32 s64, s67, s74
	ds_read_b128 v[136:139], v238
	ds_read_b128 v[144:147], v238 offset:1024
	ds_read_b128 v[160:163], v238 offset:2048
	ds_read_b128 v[164:167], v238 offset:3072
	ds_read_b128 v[176:179], v238 offset:4096
	ds_read_b128 v[180:183], v238 offset:5120
	ds_read_b128 v[184:187], v238 offset:6144
	ds_read_b128 v[188:191], v238 offset:7168
	s_add_i32 m0, s20, 0xc000
	s_nop 0
	global_load_lds_dwordx4 v229, s[60:61]
	s_add_i32 m0, s20, 0xe000
	s_nop 0
	global_load_lds_dwordx4 v231, s[60:61]
	s_waitcnt vmcnt(8)
	s_waitcnt lgkmcnt(0)
	s_barrier
	s_setprio 1
	s_waitcnt lgkmcnt(0)
	v_mfma_f32_16x16x32_bf16 v[172:175], v[64:67], v[136:139], v[172:175]
	v_mfma_f32_16x16x32_bf16 v[168:171], v[76:79], v[136:139], v[168:171]
	v_mfma_f32_16x16x32_bf16 v[148:151], v[64:67], v[160:163], v[148:151]
	v_mfma_f32_16x16x32_bf16 v[140:143], v[76:79], v[160:163], v[140:143]
	v_mfma_f32_16x16x32_bf16 v[120:123], v[64:67], v[176:179], v[120:123]
	v_mfma_f32_16x16x32_bf16 v[116:119], v[76:79], v[176:179], v[116:119]
	v_mfma_f32_16x16x32_bf16 v[96:99], v[64:67], v[184:187], v[96:99]
	v_mfma_f32_16x16x32_bf16 v[92:95], v[76:79], v[184:187], v[92:95]
	v_mfma_f32_16x16x32_bf16 v[172:175], v[68:71], v[144:147], v[172:175]
	v_mfma_f32_16x16x32_bf16 v[168:171], v[80:83], v[144:147], v[168:171]
	v_mfma_f32_16x16x32_bf16 v[148:151], v[68:71], v[164:167], v[148:151]
	v_mfma_f32_16x16x32_bf16 v[140:143], v[80:83], v[164:167], v[140:143]
	v_mfma_f32_16x16x32_bf16 v[120:123], v[68:71], v[180:183], v[120:123]
	v_mfma_f32_16x16x32_bf16 v[116:119], v[80:83], v[180:183], v[116:119]
	v_mfma_f32_16x16x32_bf16 v[96:99], v[68:71], v[188:191], v[96:99]
	v_mfma_f32_16x16x32_bf16 v[92:95], v[80:83], v[188:191], v[92:95]
	s_setprio 0
	s_setprio 1
	v_mfma_f32_16x16x32_bf16 v[156:159], v[88:91], v[136:139], v[156:159]
	v_mfma_f32_16x16x32_bf16 v[132:135], v[88:91], v[160:163], v[132:135]
	v_mfma_f32_16x16x32_bf16 v[128:131], v[112:115], v[160:163], v[128:131]
	v_mfma_f32_16x16x32_bf16 v[108:111], v[88:91], v[176:179], v[108:111]
	v_mfma_f32_16x16x32_bf16 v[104:107], v[112:115], v[176:179], v[104:107]
	v_mfma_f32_16x16x32_bf16 v[84:87], v[88:91], v[184:187], v[84:87]
	v_mfma_f32_16x16x32_bf16 v[72:75], v[112:115], v[184:187], v[72:75]
	v_mfma_f32_16x16x32_bf16 v[156:159], v[100:103], v[144:147], v[156:159]
	v_mfma_f32_16x16x32_bf16 v[136:139], v[112:115], v[136:139], v[152:155]
	v_mfma_f32_16x16x32_bf16 v[132:135], v[100:103], v[164:167], v[132:135]
	v_mfma_f32_16x16x32_bf16 v[128:131], v[124:127], v[164:167], v[128:131]
	v_mfma_f32_16x16x32_bf16 v[108:111], v[100:103], v[180:183], v[108:111]
	v_mfma_f32_16x16x32_bf16 v[104:107], v[124:127], v[180:183], v[104:107]
	v_mfma_f32_16x16x32_bf16 v[84:87], v[100:103], v[188:191], v[84:87]
	v_mfma_f32_16x16x32_bf16 v[72:75], v[124:127], v[188:191], v[72:75]
	v_mfma_f32_16x16x32_bf16 v[136:139], v[124:127], v[144:147], v[136:139]
	s_setprio 0
	s_barrier
	s_add_i32 s72, s59, s3
	ds_read_b128 v[144:147], v238 offset:16384
	ds_read_b128 v[152:155], v238 offset:17408
	ds_read_b128 v[160:163], v238 offset:18432
	ds_read_b128 v[164:167], v238 offset:19456
	ds_read_b128 v[176:179], v238 offset:20480
	ds_read_b128 v[180:183], v238 offset:21504
	ds_read_b128 v[184:187], v238 offset:22528
	ds_read_b128 v[188:191], v238 offset:23552
	s_mov_b32 m0, s72
	s_nop 0
	global_load_lds_dwordx4 v230, s[64:65]
	s_add_i32 m0, s72, 0x2000
	s_add_u32 s72, s64, 0x40000
	global_load_lds_dwordx4 v232, s[64:65]
	s_addc_u32 s73, s65, 0
	s_add_i32 s77, s66, s3
	s_mov_b32 m0, s77
	s_nop 0
	global_load_lds_dwordx4 v230, s[72:73]
	s_add_i32 m0, s77, 0x2000
	s_nop 0
	global_load_lds_dwordx4 v232, s[72:73]
	s_mov_b32 m0, s20
	s_nop 0
	global_load_lds_dwordx4 v229, s[62:63]
	s_mov_b32 m0, s21
	s_nop 0
	global_load_lds_dwordx4 v231, s[62:63]
	s_waitcnt vmcnt(8)
	s_waitcnt lgkmcnt(0)
	s_barrier
	s_setprio 1
	s_waitcnt lgkmcnt(0)
	v_mfma_f32_16x16x32_bf16 v[60:63], v[64:67], v[144:147], v[60:63]
	v_mfma_f32_16x16x32_bf16 v[56:59], v[76:79], v[144:147], v[56:59]
	v_mfma_f32_16x16x32_bf16 v[44:47], v[64:67], v[160:163], v[44:47]
	v_mfma_f32_16x16x32_bf16 v[40:43], v[76:79], v[160:163], v[40:43]
	v_mfma_f32_16x16x32_bf16 v[28:31], v[64:67], v[176:179], v[28:31]
	v_mfma_f32_16x16x32_bf16 v[24:27], v[76:79], v[176:179], v[24:27]
	v_mfma_f32_16x16x32_bf16 v[12:15], v[64:67], v[184:187], v[12:15]
	v_mfma_f32_16x16x32_bf16 v[8:11], v[76:79], v[184:187], v[8:11]
	v_mfma_f32_16x16x32_bf16 v[60:63], v[68:71], v[152:155], v[60:63]
	v_mfma_f32_16x16x32_bf16 v[56:59], v[80:83], v[152:155], v[56:59]
	v_mfma_f32_16x16x32_bf16 v[44:47], v[68:71], v[164:167], v[44:47]
	v_mfma_f32_16x16x32_bf16 v[40:43], v[80:83], v[164:167], v[40:43]
	v_mfma_f32_16x16x32_bf16 v[28:31], v[68:71], v[180:183], v[28:31]
	v_mfma_f32_16x16x32_bf16 v[24:27], v[80:83], v[180:183], v[24:27]
	v_mfma_f32_16x16x32_bf16 v[12:15], v[68:71], v[188:191], v[12:15]
	v_mfma_f32_16x16x32_bf16 v[8:11], v[80:83], v[188:191], v[8:11]
	s_setprio 0
	s_setprio 1
	v_mfma_f32_16x16x32_bf16 v[52:55], v[88:91], v[144:147], v[52:55]
	v_mfma_f32_16x16x32_bf16 v[48:51], v[112:115], v[144:147], v[48:51]
	v_mfma_f32_16x16x32_bf16 v[36:39], v[88:91], v[160:163], v[36:39]
	v_mfma_f32_16x16x32_bf16 v[32:35], v[112:115], v[160:163], v[32:35]
	v_mfma_f32_16x16x32_bf16 v[20:23], v[88:91], v[176:179], v[20:23]
	v_mfma_f32_16x16x32_bf16 v[16:19], v[112:115], v[176:179], v[16:19]
	v_mfma_f32_16x16x32_bf16 v[4:7], v[88:91], v[184:187], v[4:7]
	v_mfma_f32_16x16x32_bf16 v[0:3], v[112:115], v[184:187], v[0:3]
	v_mfma_f32_16x16x32_bf16 v[52:55], v[100:103], v[152:155], v[52:55]
	v_mfma_f32_16x16x32_bf16 v[48:51], v[124:127], v[152:155], v[48:51]
	v_mfma_f32_16x16x32_bf16 v[36:39], v[100:103], v[164:167], v[36:39]
	v_mfma_f32_16x16x32_bf16 v[32:35], v[124:127], v[164:167], v[32:35]
	v_mfma_f32_16x16x32_bf16 v[20:23], v[100:103], v[180:183], v[20:23]
	v_mfma_f32_16x16x32_bf16 v[16:19], v[124:127], v[180:183], v[16:19]
	v_mfma_f32_16x16x32_bf16 v[4:7], v[100:103], v[188:191], v[4:7]
	v_mfma_f32_16x16x32_bf16 v[0:3], v[124:127], v[188:191], v[0:3]
	s_setprio 0
	s_barrier
; #define PG8_STAGE(bufoff, gbase, voff) do { _Pragma("unroll") for (int _i = 0; _i < 2; ++_i) \
;         { unsigned _vo = (voff)[_i]; asm volatile("" : "+v"(_vo));     \
;         __builtin_amdgcn_global_load_lds((const unsigned*)((const char*)(gbase) + _vo), (PG8_LAS unsigned*)(lds + (bufoff) + ldsw + _i * 8192), 16, 0, 0); } } while (0)
; #define PG8_LDA(dst, b, h) do { _Pragma("unroll") for (int m = 0; m < 4; ++m) _Pragma("unroll") for (int k = 0; k < 2; ++k) dst[m][k] = *(const PG8_LAS bf16x8*)(lds + PG8_SA(b, h) + aoff + m * 2048 + k * 1024); } while (0)
; #define PG8_BAR __builtin_amdgcn_s_barrier()
; template <class Epi, class Sched, bool ALIGN_EPI = false, bool SP2 = false, bool ABLK = false, bool F8 = false>
; __device__ __forceinline__ void gemm_phase(PG8_LAS unsigned char* lds, const Gemm g, const Sched& S, const Epi& E, const int wave_s) {
;     ...
;         for (int t = 0; t < nt; t += 2) {
;             const bool last = (t == nt - 2);
;             const char* a1 = cA + (size_t)(t + 1) * kstepA;
;             const char* a2 = last ? nA : cA + (size_t)(t + 2) * kstepA; const char* b2 = last ? nB : cB + (size_t)(t + 2) * kstep;
;             const char* a3 = a2 + kstepA; const char* b3 = b2 + kstep;
;             if (last && has_next) { S.a_ready(nxt); if constexpr (Epi::PREF) E.prefetch(nxt, wid, lane); }
;             if constexpr (SP2) {
;             PG8_LDB(B0, 0, 0); PG8_LDB(B1, 0, 1); PG8_SCHED; PG8_LDA(At, 0, 0); PG8_STAGE(PG8_SA(1, 1), a1 + hstepA, voffA);
;             PG8_WAIT_V(8); PG8_WAIT_L(0); PG8_BAR; PG8_MMA(0, 0, At, B0); PG8_MMA(0, 1, At, B1); PG8_BAR; PG8_SCHED;
;             PG8_LDA(At, 0, 1); PG8_STAGE(PG8_SB(0, 0), b2, voffB); PG8_STAGE(PG8_SB(0, 1), b2 + hstep, voffB); PG8_STAGE(PG8_SA(0, 0), a2, voffA);
;             PG8_WAIT_V(8); PG8_WAIT_L(0); PG8_BAR; PG8_MMA(1, 0, At, B0); PG8_MMA(1, 1, At, B1); PG8_BAR; PG8_SCHED;
;             PG8_LDB(B0, 1, 0); PG8_LDB(B1, 1, 1); PG8_SCHED; PG8_LDA(At, 1, 0); PG8_STAGE(PG8_SA(0, 1), a2 + hstepA, voffA);
;             PG8_WAIT_V(8); PG8_WAIT_L(0); PG8_BAR; PG8_MMA(0, 0, At, B0); PG8_MMA(0, 1, At, B1); PG8_BAR; PG8_SCHED;
;             PG8_LDA(At, 1, 1); PG8_STAGE(PG8_SB(1, 0), b3, voffB); PG8_STAGE(PG8_SB(1, 1), b3 + hstep, voffB); PG8_STAGE(PG8_SA(1, 0), a3, voffA);
;             PG8_WAIT_V(8); PG8_WAIT_L(0); PG8_BAR; PG8_MMA(1, 0, At, B0); PG8_MMA(1, 1, At, B1); PG8_BAR; PG8_SCHED;
	s_add_i32 s77, 0, 0x18000
	s_add_i32 s78, 0, 0x1c000
	v_add_u32_e32 v80, s77, v234
	v_add_u32_e32 v124, s78, v234
	ds_read_b128 v[64:67], v80
	ds_read_b128 v[68:71], v80 offset:1024
	ds_read_b128 v[76:79], v80 offset:2048
	ds_read_b128 v[80:83], v80 offset:3072
	ds_read_b128 v[88:91], v124
	ds_read_b128 v[100:103], v124 offset:1024
	ds_read_b128 v[112:115], v124 offset:2048
	ds_read_b128 v[124:127], v124 offset:3072
	s_add_u32 s72, s62, 0x40000
	s_mov_b32 m0, s22
	ds_read_b128 v[144:147], v238 offset:32768
	ds_read_b128 v[152:155], v238 offset:33792
	ds_read_b128 v[160:163], v238 offset:34816
	ds_read_b128 v[164:167], v238 offset:35840
	ds_read_b128 v[176:179], v238 offset:36864
	ds_read_b128 v[180:183], v238 offset:37888
	ds_read_b128 v[184:187], v238 offset:38912
	ds_read_b128 v[188:191], v238 offset:39936
	s_addc_u32 s73, s63, 0
	s_nop 0
	global_load_lds_dwordx4 v229, s[72:73]
	s_mov_b32 m0, s23
	s_nop 0
	global_load_lds_dwordx4 v231, s[72:73]
	s_waitcnt vmcnt(8)
	s_waitcnt lgkmcnt(0)
	s_barrier
	s_setprio 1
	s_waitcnt lgkmcnt(0)
	v_mfma_f32_16x16x32_bf16 v[172:175], v[64:67], v[144:147], v[172:175]
	v_mfma_f32_16x16x32_bf16 v[168:171], v[76:79], v[144:147], v[168:171]
	v_mfma_f32_16x16x32_bf16 v[148:151], v[64:67], v[160:163], v[148:151]
	v_mfma_f32_16x16x32_bf16 v[140:143], v[76:79], v[160:163], v[140:143]
	v_mfma_f32_16x16x32_bf16 v[120:123], v[64:67], v[176:179], v[120:123]
	v_mfma_f32_16x16x32_bf16 v[116:119], v[76:79], v[176:179], v[116:119]
	v_mfma_f32_16x16x32_bf16 v[96:99], v[64:67], v[184:187], v[96:99]
	v_mfma_f32_16x16x32_bf16 v[92:95], v[76:79], v[184:187], v[92:95]
	v_mfma_f32_16x16x32_bf16 v[172:175], v[68:71], v[152:155], v[172:175]
	v_mfma_f32_16x16x32_bf16 v[168:171], v[80:83], v[152:155], v[168:171]
	v_mfma_f32_16x16x32_bf16 v[148:151], v[68:71], v[164:167], v[148:151]
	v_mfma_f32_16x16x32_bf16 v[140:143], v[80:83], v[164:167], v[140:143]
	v_mfma_f32_16x16x32_bf16 v[120:123], v[68:71], v[180:183], v[120:123]
	v_mfma_f32_16x16x32_bf16 v[116:119], v[80:83], v[180:183], v[116:119]
	v_mfma_f32_16x16x32_bf16 v[96:99], v[68:71], v[188:191], v[96:99]
	v_mfma_f32_16x16x32_bf16 v[92:95], v[80:83], v[188:191], v[92:95]
	s_setprio 0
	s_setprio 1
	v_mfma_f32_16x16x32_bf16 v[156:159], v[88:91], v[144:147], v[156:159]
	v_mfma_f32_16x16x32_bf16 v[136:139], v[112:115], v[144:147], v[136:139]
	v_mfma_f32_16x16x32_bf16 v[132:135], v[88:91], v[160:163], v[132:135]
	v_mfma_f32_16x16x32_bf16 v[128:131], v[112:115], v[160:163], v[128:131]
	v_mfma_f32_16x16x32_bf16 v[108:111], v[88:91], v[176:179], v[108:111]
	v_mfma_f32_16x16x32_bf16 v[104:107], v[112:115], v[176:179], v[104:107]
	v_mfma_f32_16x16x32_bf16 v[84:87], v[88:91], v[184:187], v[84:87]
	v_mfma_f32_16x16x32_bf16 v[72:75], v[112:115], v[184:187], v[72:75]
	v_mfma_f32_16x16x32_bf16 v[156:159], v[100:103], v[152:155], v[156:159]
	v_mfma_f32_16x16x32_bf16 v[152:155], v[124:127], v[152:155], v[136:139]
	v_mfma_f32_16x16x32_bf16 v[132:135], v[100:103], v[164:167], v[132:135]
	v_mfma_f32_16x16x32_bf16 v[128:131], v[124:127], v[164:167], v[128:131]
	v_mfma_f32_16x16x32_bf16 v[108:111], v[100:103], v[180:183], v[108:111]
	v_mfma_f32_16x16x32_bf16 v[104:107], v[124:127], v[180:183], v[104:107]
	v_mfma_f32_16x16x32_bf16 v[84:87], v[100:103], v[188:191], v[84:87]
	v_mfma_f32_16x16x32_bf16 v[72:75], v[124:127], v[188:191], v[72:75]
	s_setprio 0
	s_barrier
	ds_read_b128 v[136:139], v238 offset:49152
	ds_read_b128 v[144:147], v238 offset:50176
	ds_read_b128 v[160:163], v238 offset:51200
	ds_read_b128 v[164:167], v238 offset:52224
	ds_read_b128 v[176:179], v238 offset:53248
	ds_read_b128 v[180:183], v238 offset:54272
	ds_read_b128 v[184:187], v238 offset:55296
	ds_read_b128 v[188:191], v238 offset:56320
	s_add_i32 s72, s77, s3
	s_add_u32 vcc_lo, s64, s42
	s_addc_u32 vcc_hi, s65, s43
	s_mov_b32 m0, s72
	s_nop 0
	global_load_lds_dwordx4 v230, vcc
	s_add_i32 m0, s72, 0x2000
	s_add_u32 vcc_lo, s64, s42
	s_addc_u32 vcc_hi, s65, s43
	s_add_u32 s64, s64, 0x40080
	global_load_lds_dwordx4 v232, vcc
	s_addc_u32 s65, s65, 0
	s_add_i32 s72, s78, s3
	s_mov_b32 m0, s72
	s_nop 0
	global_load_lds_dwordx4 v230, s[64:65]
	v_mov_b32_e32 v192, v232
	s_add_i32 m0, s72, 0x2000
	s_nop 0
	global_load_lds_dwordx4 v232, s[64:65]
	s_mov_b32 m0, s46
	s_add_u32 vcc_lo, s62, s42
	s_addc_u32 vcc_hi, s63, s43
	v_mov_b32_e32 v200, v231
	global_load_lds_dwordx4 v229, vcc
	s_mov_b32 m0, s47
	s_add_u32 vcc_lo, s62, s42
	s_addc_u32 vcc_hi, s63, s43
	global_load_lds_dwordx4 v231, vcc
	s_waitcnt vmcnt(8)
	s_waitcnt lgkmcnt(0)
	s_barrier
	s_setprio 1
	s_waitcnt lgkmcnt(0)
	v_mfma_f32_16x16x32_bf16 v[60:63], v[64:67], v[136:139], v[60:63]
	v_mfma_f32_16x16x32_bf16 v[56:59], v[76:79], v[136:139], v[56:59]
	v_mfma_f32_16x16x32_bf16 v[44:47], v[64:67], v[160:163], v[44:47]
	v_mfma_f32_16x16x32_bf16 v[40:43], v[76:79], v[160:163], v[40:43]
	v_mfma_f32_16x16x32_bf16 v[28:31], v[64:67], v[176:179], v[28:31]
	v_mfma_f32_16x16x32_bf16 v[24:27], v[76:79], v[176:179], v[24:27]
	v_mfma_f32_16x16x32_bf16 v[12:15], v[64:67], v[184:187], v[12:15]
	v_mfma_f32_16x16x32_bf16 v[8:11], v[76:79], v[184:187], v[8:11]
	v_mfma_f32_16x16x32_bf16 v[60:63], v[68:71], v[144:147], v[60:63]
	v_mfma_f32_16x16x32_bf16 v[56:59], v[80:83], v[144:147], v[56:59]
	v_mfma_f32_16x16x32_bf16 v[44:47], v[68:71], v[164:167], v[44:47]
	v_mfma_f32_16x16x32_bf16 v[40:43], v[80:83], v[164:167], v[40:43]
	v_mfma_f32_16x16x32_bf16 v[28:31], v[68:71], v[180:183], v[28:31]
	v_mfma_f32_16x16x32_bf16 v[24:27], v[80:83], v[180:183], v[24:27]
	v_mfma_f32_16x16x32_bf16 v[12:15], v[68:71], v[188:191], v[12:15]
	v_mfma_f32_16x16x32_bf16 v[8:11], v[80:83], v[188:191], v[8:11]
	s_setprio 0
	s_setprio 1
	v_mfma_f32_16x16x32_bf16 v[52:55], v[88:91], v[136:139], v[52:55]
	v_mfma_f32_16x16x32_bf16 v[48:51], v[112:115], v[136:139], v[48:51]
	v_mfma_f32_16x16x32_bf16 v[36:39], v[88:91], v[160:163], v[36:39]
	v_mfma_f32_16x16x32_bf16 v[32:35], v[112:115], v[160:163], v[32:35]
	v_mfma_f32_16x16x32_bf16 v[20:23], v[88:91], v[176:179], v[20:23]
	v_mfma_f32_16x16x32_bf16 v[16:19], v[112:115], v[176:179], v[16:19]
	v_mfma_f32_16x16x32_bf16 v[4:7], v[88:91], v[184:187], v[4:7]
	v_mfma_f32_16x16x32_bf16 v[0:3], v[112:115], v[184:187], v[0:3]
	v_mfma_f32_16x16x32_bf16 v[52:55], v[100:103], v[144:147], v[52:55]
	v_mfma_f32_16x16x32_bf16 v[48:51], v[124:127], v[144:147], v[48:51]
	v_mfma_f32_16x16x32_bf16 v[36:39], v[100:103], v[164:167], v[36:39]
	v_mfma_f32_16x16x32_bf16 v[32:35], v[124:127], v[164:167], v[32:35]
	v_mfma_f32_16x16x32_bf16 v[20:23], v[100:103], v[180:183], v[20:23]
	v_mfma_f32_16x16x32_bf16 v[16:19], v[124:127], v[180:183], v[16:19]
	v_mfma_f32_16x16x32_bf16 v[4:7], v[100:103], v[188:191], v[4:7]
	v_mfma_f32_16x16x32_bf16 v[0:3], v[124:127], v[188:191], v[0:3]
	s_setprio 0
	s_barrier
	s_add_i32 s76, s76, 2
	s_add_u32 s60, s60, 0x100
	s_addc_u32 s61, s61, 0
	s_add_u32 s74, s74, 0x100
	s_addc_u32 s75, s75, 0
	s_cmp_gt_u32 s76, 13
	s_cbranch_scc0 .LBB0_592
	s_and_b64 vcc, exec, s[36:37]
	s_cbranch_vccz .LBB0_595
	s_barrier

; #define PG8_STAGE(bufoff, gbase, voff) do { _Pragma("unroll") for (int _i = 0; _i < 2; ++_i) \
;         { unsigned _vo = (voff)[_i]; asm volatile("" : "+v"(_vo));     \
;         __builtin_amdgcn_global_load_lds((const unsigned*)((const char*)(gbase) + _vo), (PG8_LAS unsigned*)(lds + (bufoff) + ldsw + _i * 8192), 16, 0, 0); } } while (0)
; #define PG8_LDA(dst, b, h) do { _Pragma("unroll") for (int m = 0; m < 4; ++m) _Pragma("unroll") for (int k = 0; k < 2; ++k) dst[m][k] = *(const PG8_LAS bf16x8*)(lds + PG8_SA(b, h) + aoff + m * 2048 + k * 1024); } while (0)
; #define PG8_LDB(dst, b, h) do { _Pragma("unroll") for (int n = 0; n < 2; ++n) _Pragma("unroll") for (int k = 0; k < 2; ++k) dst[n][k] = *(const PG8_LAS bf16x8*)(lds + PG8_SB(b, h) + boff + n * 2048 + k * 1024); } while (0)
; #define PG8_WAIT_V(n) asm volatile("s_waitcnt vmcnt(" #n ")" ::: "memory")
; #define PG8_WAIT_L(n) asm volatile("s_waitcnt lgkmcnt(" #n ")" ::: "memory")
; #define PG8_BAR __builtin_amdgcn_s_barrier()
; #define PG8_SCHED __builtin_amdgcn_sched_barrier(0)
; template <class Epi, class Sched, bool ALIGN_EPI = false, bool SP2 = false, bool ABLK = false, bool F8 = false>
; __device__ __forceinline__ void gemm_phase(PG8_LAS unsigned char* lds, const Gemm g, const Sched& S, const Epi& E, const int wave_s) {
;     ...
;             const bool last = (t == nt - 2);
;             const char* a1 = cA + (size_t)(t + 1) * kstepA;
;             const char* a2 = last ? nA : cA + (size_t)(t + 2) * kstepA; const char* b2 = last ? nB : cB + (size_t)(t + 2) * kstep;
;             const char* a3 = a2 + kstepA; const char* b3 = b2 + kstep;
;             if (last && has_next) { S.a_ready(nxt); if constexpr (Epi::PREF) E.prefetch(nxt, wid, lane); }
;             if constexpr (SP2) {
;             PG8_LDB(B0, 0, 0); PG8_LDB(B1, 0, 1); PG8_SCHED; PG8_LDA(At, 0, 0); PG8_STAGE(PG8_SA(1, 1), a1 + hstepA, voffA);
;             PG8_WAIT_V(8); PG8_WAIT_L(0); PG8_BAR; PG8_MMA(0, 0, At, B0); PG8_MMA(0, 1, At, B1); PG8_BAR; PG8_SCHED;
;             PG8_LDA(At, 0, 1); PG8_STAGE(PG8_SB(0, 0), b2, voffB); PG8_STAGE(PG8_SB(0, 1), b2 + hstep, voffB); PG8_STAGE(PG8_SA(0, 0), a2, voffA);
;             PG8_WAIT_V(8); PG8_WAIT_L(0); PG8_BAR; PG8_MMA(1, 0, At, B0); PG8_MMA(1, 1, At, B1); PG8_BAR; PG8_SCHED;
.LBB0_686:
	v_add_u32_e32 v0, s47, v166
	s_waitcnt lgkmcnt(0)
	ds_read_b128 v[136:139], v0
	ds_read_b128 v[140:143], v0 offset:1024
	ds_read_b128 v[144:147], v0 offset:2048
	ds_read_b128 v[148:151], v0 offset:3072
	v_add_u32_e32 v0, s74, v166
	ds_read_b128 v[152:155], v0
	ds_read_b128 v[156:159], v0 offset:1024
	ds_read_b128 v[172:175], v0 offset:2048
	ds_read_b128 v[176:179], v0 offset:3072
	s_add_u32 s64, s62, 0xfff80080
	s_addc_u32 s65, s63, -1
	s_cmp_eq_u32 s81, 12
	s_cselect_b32 s65, s13, s65
	s_cselect_b32 s64, s57, s64
	s_cselect_b32 s67, s55, s80
	s_cselect_b32 s66, s78, s79
	ds_read_b128 v[180:183], v167
	ds_read_b128 v[184:187], v167 offset:1024
	ds_read_b128 v[188:191], v167 offset:2048
	ds_read_b128 v[192:195], v167 offset:3072
	ds_read_b128 v[196:199], v167 offset:4096
	ds_read_b128 v[200:203], v167 offset:5120
	ds_read_b128 v[204:207], v167 offset:6144
	ds_read_b128 v[208:211], v167 offset:7168
	s_add_i32 m0, s20, 0xc000
	s_nop 0
	global_load_lds_dwordx4 v162, s[62:63]
	s_add_i32 m0, s20, 0xe000
	s_nop 0
	global_load_lds_dwordx4 v164, s[62:63]
	s_waitcnt vmcnt(8)
	s_waitcnt lgkmcnt(0)
	s_barrier
	s_setprio 1
	s_waitcnt lgkmcnt(0)
	v_mfma_f32_16x16x32_bf16 v[128:131], v[136:139], v[180:183], v[128:131]
	v_mfma_f32_16x16x32_bf16 v[124:127], v[144:147], v[180:183], v[124:127]
	v_mfma_f32_16x16x32_bf16 v[120:123], v[136:139], v[188:191], v[120:123]
	v_mfma_f32_16x16x32_bf16 v[116:119], v[144:147], v[188:191], v[116:119]
	v_mfma_f32_16x16x32_bf16 v[112:115], v[136:139], v[196:199], v[112:115]
	v_mfma_f32_16x16x32_bf16 v[108:111], v[144:147], v[196:199], v[108:111]
	v_mfma_f32_16x16x32_bf16 v[104:107], v[136:139], v[204:207], v[104:107]
	v_mfma_f32_16x16x32_bf16 v[100:103], v[144:147], v[204:207], v[100:103]
	v_mfma_f32_16x16x32_bf16 v[128:131], v[140:143], v[184:187], v[128:131]
	v_mfma_f32_16x16x32_bf16 v[124:127], v[148:151], v[184:187], v[124:127]
	v_mfma_f32_16x16x32_bf16 v[120:123], v[140:143], v[192:195], v[120:123]
	v_mfma_f32_16x16x32_bf16 v[116:119], v[148:151], v[192:195], v[116:119]
	v_mfma_f32_16x16x32_bf16 v[112:115], v[140:143], v[200:203], v[112:115]
	v_mfma_f32_16x16x32_bf16 v[108:111], v[148:151], v[200:203], v[108:111]
	v_mfma_f32_16x16x32_bf16 v[104:107], v[140:143], v[208:211], v[104:107]
	v_mfma_f32_16x16x32_bf16 v[100:103], v[148:151], v[208:211], v[100:103]
	s_setprio 0
	s_setprio 1
	v_mfma_f32_16x16x32_bf16 v[92:95], v[152:155], v[180:183], v[92:95]
	v_mfma_f32_16x16x32_bf16 v[84:87], v[172:175], v[180:183], v[84:87]
	v_mfma_f32_16x16x32_bf16 v[76:79], v[152:155], v[188:191], v[76:79]
	v_mfma_f32_16x16x32_bf16 v[68:71], v[172:175], v[188:191], v[68:71]
	v_mfma_f32_16x16x32_bf16 v[60:63], v[152:155], v[196:199], v[60:63]
	v_mfma_f32_16x16x32_bf16 v[52:55], v[172:175], v[196:199], v[52:55]
	v_mfma_f32_16x16x32_bf16 v[44:47], v[152:155], v[204:207], v[44:47]
	v_mfma_f32_16x16x32_bf16 v[36:39], v[172:175], v[204:207], v[36:39]
	v_mfma_f32_16x16x32_bf16 v[92:95], v[156:159], v[184:187], v[92:95]
	v_mfma_f32_16x16x32_bf16 v[84:87], v[176:179], v[184:187], v[84:87]
	v_mfma_f32_16x16x32_bf16 v[76:79], v[156:159], v[192:195], v[76:79]
	v_mfma_f32_16x16x32_bf16 v[68:71], v[176:179], v[192:195], v[68:71]
	v_mfma_f32_16x16x32_bf16 v[60:63], v[156:159], v[200:203], v[60:63]
	v_mfma_f32_16x16x32_bf16 v[52:55], v[176:179], v[200:203], v[52:55]
	v_mfma_f32_16x16x32_bf16 v[44:47], v[156:159], v[208:211], v[44:47]
	v_mfma_f32_16x16x32_bf16 v[36:39], v[176:179], v[208:211], v[36:39]
	s_setprio 0
	s_barrier
	s_add_i32 s72, s47, s3
	ds_read_b128 v[180:183], v167 offset:16384
	ds_read_b128 v[184:187], v167 offset:17408
	ds_read_b128 v[188:191], v167 offset:18432
	ds_read_b128 v[192:195], v167 offset:19456
	ds_read_b128 v[196:199], v167 offset:20480
	ds_read_b128 v[200:203], v167 offset:21504
	ds_read_b128 v[204:207], v167 offset:22528
	ds_read_b128 v[208:211], v167 offset:23552
	s_mov_b32 m0, s72
	s_nop 0
	global_load_lds_dwordx4 v163, s[66:67]
	s_add_i32 m0, s72, 0x2000
	s_add_u32 s72, s66, 0x80000
	global_load_lds_dwordx4 v165, s[66:67]
	s_addc_u32 s73, s67, 0
	s_add_i32 s82, s74, s3
	s_mov_b32 m0, s82
	s_nop 0
	global_load_lds_dwordx4 v163, s[72:73]
	s_add_i32 m0, s82, 0x2000
	s_nop 0
	global_load_lds_dwordx4 v165, s[72:73]
	s_mov_b32 m0, s20
	s_nop 0
	global_load_lds_dwordx4 v162, s[64:65]
	s_mov_b32 m0, s21
	s_nop 0
	global_load_lds_dwordx4 v164, s[64:65]
	s_waitcnt vmcnt(8)
	s_waitcnt lgkmcnt(0)
	s_barrier
	s_setprio 1
	s_waitcnt lgkmcnt(0)
	v_mfma_f32_16x16x32_bf16 v[96:99], v[136:139], v[180:183], v[96:99]
	v_mfma_f32_16x16x32_bf16 v[88:91], v[144:147], v[180:183], v[88:91]
	v_mfma_f32_16x16x32_bf16 v[80:83], v[136:139], v[188:191], v[80:83]
	v_mfma_f32_16x16x32_bf16 v[72:75], v[144:147], v[188:191], v[72:75]
	v_mfma_f32_16x16x32_bf16 v[64:67], v[136:139], v[196:199], v[64:67]
	v_mfma_f32_16x16x32_bf16 v[56:59], v[144:147], v[196:199], v[56:59]
	v_mfma_f32_16x16x32_bf16 v[48:51], v[136:139], v[204:207], v[48:51]
	v_mfma_f32_16x16x32_bf16 v[40:43], v[144:147], v[204:207], v[40:43]
	v_mfma_f32_16x16x32_bf16 v[96:99], v[140:143], v[184:187], v[96:99]
	v_mfma_f32_16x16x32_bf16 v[88:91], v[148:151], v[184:187], v[88:91]
	v_mfma_f32_16x16x32_bf16 v[80:83], v[140:143], v[192:195], v[80:83]
	v_mfma_f32_16x16x32_bf16 v[72:75], v[148:151], v[192:195], v[72:75]
	v_mfma_f32_16x16x32_bf16 v[64:67], v[140:143], v[200:203], v[64:67]
	v_mfma_f32_16x16x32_bf16 v[56:59], v[148:151], v[200:203], v[56:59]
	v_mfma_f32_16x16x32_bf16 v[48:51], v[140:143], v[208:211], v[48:51]
	v_mfma_f32_16x16x32_bf16 v[40:43], v[148:151], v[208:211], v[40:43]
	s_setprio 0
	s_setprio 1
	v_mfma_f32_16x16x32_bf16 v[32:35], v[152:155], v[180:183], v[32:35]
	v_mfma_f32_16x16x32_bf16 v[28:31], v[172:175], v[180:183], v[28:31]
	v_mfma_f32_16x16x32_bf16 v[24:27], v[152:155], v[188:191], v[24:27]
	v_mfma_f32_16x16x32_bf16 v[20:23], v[172:175], v[188:191], v[20:23]
	v_mfma_f32_16x16x32_bf16 v[16:19], v[152:155], v[196:199], v[16:19]
	v_mfma_f32_16x16x32_bf16 v[12:15], v[172:175], v[196:199], v[12:15]
	v_mfma_f32_16x16x32_bf16 v[8:11], v[152:155], v[204:207], v[8:11]
	v_mfma_f32_16x16x32_bf16 v[2:5], v[172:175], v[204:207], v[4:7]
	v_mfma_f32_16x16x32_bf16 v[32:35], v[156:159], v[184:187], v[32:35]
	v_mfma_f32_16x16x32_bf16 v[28:31], v[176:179], v[184:187], v[28:31]
	v_mfma_f32_16x16x32_bf16 v[24:27], v[156:159], v[192:195], v[24:27]
	v_mfma_f32_16x16x32_bf16 v[20:23], v[176:179], v[192:195], v[20:23]
	v_mfma_f32_16x16x32_bf16 v[16:19], v[156:159], v[200:203], v[16:19]
	v_mfma_f32_16x16x32_bf16 v[12:15], v[176:179], v[200:203], v[12:15]
	v_mfma_f32_16x16x32_bf16 v[8:11], v[156:159], v[208:211], v[8:11]
	v_mfma_f32_16x16x32_bf16 v[2:5], v[176:179], v[208:211], v[2:5]
	s_setprio 0
	s_barrier
; #define PG8_STAGE(bufoff, gbase, voff) do { _Pragma("unroll") for (int _i = 0; _i < 2; ++_i) \
;         { unsigned _vo = (voff)[_i]; asm volatile("" : "+v"(_vo));     \
;         __builtin_amdgcn_global_load_lds((const unsigned*)((const char*)(gbase) + _vo), (PG8_LAS unsigned*)(lds + (bufoff) + ldsw + _i * 8192), 16, 0, 0); } } while (0)
; #define PG8_LDA(dst, b, h) do { _Pragma("unroll") for (int m = 0; m < 4; ++m) _Pragma("unroll") for (int k = 0; k < 2; ++k) dst[m][k] = *(const PG8_LAS bf16x8*)(lds + PG8_SA(b, h) + aoff + m * 2048 + k * 1024); } while (0)
; #define PG8_LDB(dst, b, h) do { _Pragma("unroll") for (int n = 0; n < 2; ++n) _Pragma("unroll") for (int k = 0; k < 2; ++k) dst[n][k] = *(const PG8_LAS bf16x8*)(lds + PG8_SB(b, h) + boff + n * 2048 + k * 1024); } while (0)
; #define PG8_WAIT_V(n) asm volatile("s_waitcnt vmcnt(" #n ")" ::: "memory")
; #define PG8_WAIT_L(n) asm volatile("s_waitcnt lgkmcnt(" #n ")" ::: "memory")
; #define PG8_BAR __builtin_amdgcn_s_barrier()
; #define PG8_SCHED __builtin_amdgcn_sched_barrier(0)
; template <class Epi, class Sched, bool ALIGN_EPI = false, bool SP2 = false, bool ABLK = false, bool F8 = false>
; __device__ __forceinline__ void gemm_phase(PG8_LAS unsigned char* lds, const Gemm g, const Sched& S, const Epi& E, const int wave_s) {
;     ...
;             PG8_LDB(B0, 1, 0); PG8_LDB(B1, 1, 1); PG8_SCHED; PG8_LDA(At, 1, 0); PG8_STAGE(PG8_SA(0, 1), a2 + hstepA, voffA);
;             PG8_WAIT_V(8); PG8_WAIT_L(0); PG8_BAR; PG8_MMA(0, 0, At, B0); PG8_MMA(0, 1, At, B1); PG8_BAR; PG8_SCHED;
;             PG8_LDA(At, 1, 1); PG8_STAGE(PG8_SB(1, 0), b3, voffB); PG8_STAGE(PG8_SB(1, 1), b3 + hstep, voffB); PG8_STAGE(PG8_SA(1, 0), a3, voffA);
;             PG8_WAIT_V(8); PG8_WAIT_L(0); PG8_BAR; PG8_MMA(1, 0, At, B0); PG8_MMA(1, 1, At, B1); PG8_BAR; PG8_SCHED;
;     ...
;         if constexpr (ALIGN_EPI) { if (wr == 0) PG8_BAR; }
	s_add_i32 s82, 0, 0x18000
	v_add_u32_e32 v0, s82, v166
	s_add_i32 s83, 0, 0x1c000
	ds_read_b128 v[136:139], v0
	ds_read_b128 v[140:143], v0 offset:1024
	ds_read_b128 v[144:147], v0 offset:2048
	ds_read_b128 v[148:151], v0 offset:3072
	v_add_u32_e32 v0, s83, v166
	ds_read_b128 v[152:155], v0
	ds_read_b128 v[156:159], v0 offset:1024
	ds_read_b128 v[172:175], v0 offset:2048
	ds_read_b128 v[176:179], v0 offset:3072
	s_add_u32 s72, s64, 0x80000
	s_mov_b32 m0, s22
	ds_read_b128 v[180:183], v167 offset:32768
	ds_read_b128 v[184:187], v167 offset:33792
	ds_read_b128 v[188:191], v167 offset:34816
	ds_read_b128 v[192:195], v167 offset:35840
	ds_read_b128 v[196:199], v167 offset:36864
	ds_read_b128 v[200:203], v167 offset:37888
	ds_read_b128 v[204:207], v167 offset:38912
	ds_read_b128 v[208:211], v167 offset:39936
	s_addc_u32 s73, s65, 0
	s_nop 0
	global_load_lds_dwordx4 v162, s[72:73]
	s_mov_b32 m0, s23
	s_nop 0
	global_load_lds_dwordx4 v164, s[72:73]
	s_waitcnt vmcnt(8)
	s_waitcnt lgkmcnt(0)
	s_barrier
	s_setprio 1
	s_waitcnt lgkmcnt(0)
	v_mfma_f32_16x16x32_bf16 v[128:131], v[136:139], v[180:183], v[128:131]
	v_mfma_f32_16x16x32_bf16 v[124:127], v[144:147], v[180:183], v[124:127]
	v_mfma_f32_16x16x32_bf16 v[120:123], v[136:139], v[188:191], v[120:123]
	v_mfma_f32_16x16x32_bf16 v[116:119], v[144:147], v[188:191], v[116:119]
	v_mfma_f32_16x16x32_bf16 v[112:115], v[136:139], v[196:199], v[112:115]
	v_mfma_f32_16x16x32_bf16 v[108:111], v[144:147], v[196:199], v[108:111]
	v_mfma_f32_16x16x32_bf16 v[104:107], v[136:139], v[204:207], v[104:107]
	v_mfma_f32_16x16x32_bf16 v[100:103], v[144:147], v[204:207], v[100:103]
	v_mfma_f32_16x16x32_bf16 v[128:131], v[140:143], v[184:187], v[128:131]
	v_mfma_f32_16x16x32_bf16 v[124:127], v[148:151], v[184:187], v[124:127]
	v_mfma_f32_16x16x32_bf16 v[120:123], v[140:143], v[192:195], v[120:123]
	v_mfma_f32_16x16x32_bf16 v[116:119], v[148:151], v[192:195], v[116:119]
	v_mfma_f32_16x16x32_bf16 v[112:115], v[140:143], v[200:203], v[112:115]
	v_mfma_f32_16x16x32_bf16 v[108:111], v[148:151], v[200:203], v[108:111]
	v_mfma_f32_16x16x32_bf16 v[104:107], v[140:143], v[208:211], v[104:107]
	v_mfma_f32_16x16x32_bf16 v[100:103], v[148:151], v[208:211], v[100:103]
	s_setprio 0
	s_setprio 1
	v_mfma_f32_16x16x32_bf16 v[92:95], v[152:155], v[180:183], v[92:95]
	v_mfma_f32_16x16x32_bf16 v[84:87], v[172:175], v[180:183], v[84:87]
	v_mfma_f32_16x16x32_bf16 v[76:79], v[152:155], v[188:191], v[76:79]
	v_mfma_f32_16x16x32_bf16 v[68:71], v[172:175], v[188:191], v[68:71]
	v_mfma_f32_16x16x32_bf16 v[60:63], v[152:155], v[196:199], v[60:63]
	v_mfma_f32_16x16x32_bf16 v[52:55], v[172:175], v[196:199], v[52:55]
	v_mfma_f32_16x16x32_bf16 v[44:47], v[152:155], v[204:207], v[44:47]
	v_mfma_f32_16x16x32_bf16 v[36:39], v[172:175], v[204:207], v[36:39]
	v_mfma_f32_16x16x32_bf16 v[92:95], v[156:159], v[184:187], v[92:95]
	v_mfma_f32_16x16x32_bf16 v[84:87], v[176:179], v[184:187], v[84:87]
	v_mfma_f32_16x16x32_bf16 v[76:79], v[156:159], v[192:195], v[76:79]
	v_mfma_f32_16x16x32_bf16 v[68:71], v[176:179], v[192:195], v[68:71]
	v_mfma_f32_16x16x32_bf16 v[60:63], v[156:159], v[200:203], v[60:63]
	v_mfma_f32_16x16x32_bf16 v[52:55], v[176:179], v[200:203], v[52:55]
	v_mfma_f32_16x16x32_bf16 v[44:47], v[156:159], v[208:211], v[44:47]
	v_mfma_f32_16x16x32_bf16 v[36:39], v[176:179], v[208:211], v[36:39]
	s_setprio 0
	s_barrier
	ds_read_b128 v[180:183], v167 offset:49152
	ds_read_b128 v[184:187], v167 offset:50176
	ds_read_b128 v[188:191], v167 offset:51200
	ds_read_b128 v[192:195], v167 offset:52224
	ds_read_b128 v[196:199], v167 offset:53248
	ds_read_b128 v[200:203], v167 offset:54272
	ds_read_b128 v[204:207], v167 offset:55296
	ds_read_b128 v[208:211], v167 offset:56320
	s_add_i32 s72, s82, s3
	s_add_u32 vcc_lo, s66, s50
	s_addc_u32 vcc_hi, s67, s51
	s_mov_b32 m0, s72
	s_nop 0
	global_load_lds_dwordx4 v163, vcc
	s_add_i32 m0, s72, 0x2000
	s_nop 0
	s_add_u32 vcc_lo, s66, s50
	s_addc_u32 vcc_hi, s67, s51
	s_add_u32 s66, s66, 0x80080
	s_addc_u32 s67, s67, 0
	s_add_i32 s72, s83, s3
	global_load_lds_dwordx4 v165, vcc
	s_mov_b32 m0, s72
	s_nop 0
	global_load_lds_dwordx4 v163, s[66:67]
	s_add_i32 m0, s72, 0x2000
	s_nop 0
	global_load_lds_dwordx4 v165, s[66:67]
	s_mov_b32 m0, s33
	s_add_u32 vcc_lo, s64, s50
	s_addc_u32 vcc_hi, s65, s51
	v_mov_b32_e32 v0, v164
	global_load_lds_dwordx4 v162, vcc
	s_mov_b32 m0, s46
	s_add_u32 vcc_lo, s64, s50
	s_addc_u32 vcc_hi, s65, s51
	global_load_lds_dwordx4 v164, vcc
	s_waitcnt vmcnt(8)
	s_waitcnt lgkmcnt(0)
	s_barrier
	s_setprio 1
	s_waitcnt lgkmcnt(0)
	v_mfma_f32_16x16x32_bf16 v[96:99], v[136:139], v[180:183], v[96:99]
	v_mfma_f32_16x16x32_bf16 v[88:91], v[144:147], v[180:183], v[88:91]
	v_mfma_f32_16x16x32_bf16 v[80:83], v[136:139], v[188:191], v[80:83]
	v_mfma_f32_16x16x32_bf16 v[72:75], v[144:147], v[188:191], v[72:75]
	v_mfma_f32_16x16x32_bf16 v[64:67], v[136:139], v[196:199], v[64:67]
	v_mfma_f32_16x16x32_bf16 v[56:59], v[144:147], v[196:199], v[56:59]
	v_mfma_f32_16x16x32_bf16 v[48:51], v[136:139], v[204:207], v[48:51]
	v_mfma_f32_16x16x32_bf16 v[40:43], v[144:147], v[204:207], v[40:43]
	v_mfma_f32_16x16x32_bf16 v[96:99], v[140:143], v[184:187], v[96:99]
	v_mfma_f32_16x16x32_bf16 v[88:91], v[148:151], v[184:187], v[88:91]
	v_mfma_f32_16x16x32_bf16 v[80:83], v[140:143], v[192:195], v[80:83]
	v_mfma_f32_16x16x32_bf16 v[72:75], v[148:151], v[192:195], v[72:75]
	v_mfma_f32_16x16x32_bf16 v[64:67], v[140:143], v[200:203], v[64:67]
	v_mfma_f32_16x16x32_bf16 v[56:59], v[148:151], v[200:203], v[56:59]
	v_mfma_f32_16x16x32_bf16 v[48:51], v[140:143], v[208:211], v[48:51]
	v_mfma_f32_16x16x32_bf16 v[40:43], v[148:151], v[208:211], v[40:43]
	s_setprio 0
	s_setprio 1
	v_mfma_f32_16x16x32_bf16 v[32:35], v[152:155], v[180:183], v[32:35]
	v_mfma_f32_16x16x32_bf16 v[28:31], v[172:175], v[180:183], v[28:31]
	v_mfma_f32_16x16x32_bf16 v[24:27], v[152:155], v[188:191], v[24:27]
	v_mfma_f32_16x16x32_bf16 v[20:23], v[172:175], v[188:191], v[20:23]
	v_mfma_f32_16x16x32_bf16 v[16:19], v[152:155], v[196:199], v[16:19]
	v_mfma_f32_16x16x32_bf16 v[12:15], v[172:175], v[196:199], v[12:15]
	v_mfma_f32_16x16x32_bf16 v[6:9], v[152:155], v[204:207], v[8:11]
	v_mfma_f32_16x16x32_bf16 v[2:5], v[172:175], v[204:207], v[2:5]
	v_mfma_f32_16x16x32_bf16 v[32:35], v[156:159], v[184:187], v[32:35]
	v_mfma_f32_16x16x32_bf16 v[28:31], v[176:179], v[184:187], v[28:31]
	v_mfma_f32_16x16x32_bf16 v[24:27], v[156:159], v[192:195], v[24:27]
	v_mfma_f32_16x16x32_bf16 v[20:23], v[176:179], v[192:195], v[20:23]
	v_mfma_f32_16x16x32_bf16 v[16:19], v[156:159], v[200:203], v[16:19]
	v_mfma_f32_16x16x32_bf16 v[12:15], v[176:179], v[200:203], v[12:15]
	v_mfma_f32_16x16x32_bf16 v[8:11], v[156:159], v[208:211], v[6:9]
	v_mfma_f32_16x16x32_bf16 v[4:7], v[176:179], v[208:211], v[2:5]
	s_setprio 0
	s_barrier
	s_add_i32 s81, s81, 2
	s_add_u32 s62, s62, 0x100
	s_addc_u32 s63, s63, 0
	s_add_u32 s79, s79, 0x100
	s_addc_u32 s80, s80, 0
	s_cmp_gt_u32 s81, 13
	s_cbranch_scc0 .LBB0_686
	s_and_b64 vcc, exec, s[36:37]
	s_cbranch_vccz .LBB0_689
	s_barrier

; #define PG8_STAGE(bufoff, gbase, voff) do { _Pragma("unroll") for (int _i = 0; _i < 2; ++_i) \
;         { unsigned _vo = (voff)[_i]; asm volatile("" : "+v"(_vo));     \
;         __builtin_amdgcn_global_load_lds((const unsigned*)((const char*)(gbase) + _vo), (PG8_LAS unsigned*)(lds + (bufoff) + ldsw + _i * 8192), 16, 0, 0); } } while (0)
; #define PG8_LDA(dst, b, h) do { _Pragma("unroll") for (int m = 0; m < 4; ++m) _Pragma("unroll") for (int k = 0; k < 2; ++k) dst[m][k] = *(const PG8_LAS bf16x8*)(lds + PG8_SA(b, h) + aoff + m * 2048 + k * 1024); } while (0)
; #define PG8_LDB(dst, b, h) do { _Pragma("unroll") for (int n = 0; n < 2; ++n) _Pragma("unroll") for (int k = 0; k < 2; ++k) dst[n][k] = *(const PG8_LAS bf16x8*)(lds + PG8_SB(b, h) + boff + n * 2048 + k * 1024); } while (0)
; #define PG8_WAIT_V(n) asm volatile("s_waitcnt vmcnt(" #n ")" ::: "memory")
; #define PG8_WAIT_L(n) asm volatile("s_waitcnt lgkmcnt(" #n ")" ::: "memory")
; #define PG8_BAR __builtin_amdgcn_s_barrier()
; #define PG8_SCHED __builtin_amdgcn_sched_barrier(0)
; template <class Epi, class Sched, bool ALIGN_EPI = false, bool SP2 = false, bool ABLK = false, bool F8 = false>
; __device__ __forceinline__ void gemm_phase(PG8_LAS unsigned char* lds, const Gemm g, const Sched& S, const Epi& E, const int wave_s) {
;     ...
;             const bool last = (t == nt - 2);
;             const char* a1 = cA + (size_t)(t + 1) * kstepA;
;             const char* a2 = last ? nA : cA + (size_t)(t + 2) * kstepA; const char* b2 = last ? nB : cB + (size_t)(t + 2) * kstep;
;             const char* a3 = a2 + kstepA; const char* b3 = b2 + kstep;
;             if (last && has_next) { S.a_ready(nxt); if constexpr (Epi::PREF) E.prefetch(nxt, wid, lane); }
;             if constexpr (SP2) {
;             PG8_LDB(B0, 0, 0); PG8_LDB(B1, 0, 1); PG8_SCHED; PG8_LDA(At, 0, 0); PG8_STAGE(PG8_SA(1, 1), a1 + hstepA, voffA);
;             PG8_WAIT_V(8); PG8_WAIT_L(0); PG8_BAR; PG8_MMA(0, 0, At, B0); PG8_MMA(0, 1, At, B1); PG8_BAR; PG8_SCHED;
;             PG8_LDA(At, 0, 1); PG8_STAGE(PG8_SB(0, 0), b2, voffB); PG8_STAGE(PG8_SB(0, 1), b2 + hstep, voffB); PG8_STAGE(PG8_SA(0, 0), a2, voffA);
;             PG8_WAIT_V(8); PG8_WAIT_L(0); PG8_BAR; PG8_MMA(1, 0, At, B0); PG8_MMA(1, 1, At, B1); PG8_BAR; PG8_SCHED;
.LBB0_810:
	v_add_u32_e32 v128, s61, v142
	ds_read_b128 v[148:151], v128
	ds_read_b128 v[152:155], v128 offset:1024
	ds_read_b128 v[156:159], v128 offset:2048
	ds_read_b128 v[160:163], v128 offset:3072
	v_add_u32_e32 v128, s62, v142
	ds_read_b128 v[164:167], v128
	ds_read_b128 v[168:171], v128 offset:1024
	ds_read_b128 v[172:175], v128 offset:2048
	ds_read_b128 v[176:179], v128 offset:3072
	s_add_u32 s58, s54, 0xfffc0080
	s_addc_u32 s59, s55, -1
	s_and_b64 s[56:57], s[56:57], exec
	s_cselect_b32 s57, s59, s43
	s_cselect_b32 s56, s58, s66
	s_cselect_b32 s59, s73, s41
	s_cselect_b32 s58, s72, s67
	ds_read_b128 v[180:183], v143
	ds_read_b128 v[184:187], v143 offset:1024
	ds_read_b128 v[188:191], v143 offset:2048
	ds_read_b128 v[192:195], v143 offset:3072
	ds_read_b128 v[196:199], v143 offset:4096
	ds_read_b128 v[200:203], v143 offset:5120
	ds_read_b128 v[204:207], v143 offset:6144
	ds_read_b128 v[208:211], v143 offset:7168
	s_add_i32 m0, s20, 0xc000
	s_nop 0
	global_load_lds_dwordx4 v147, s[54:55]
	s_add_i32 m0, s20, 0xe000
	s_nop 0
	global_load_lds_dwordx4 v140, s[54:55]
	s_waitcnt vmcnt(8)
	s_waitcnt lgkmcnt(0)
	s_barrier
	s_setprio 1
	s_waitcnt lgkmcnt(0)
	v_mfma_scale_f32_16x16x128_f8f6f4 v[124:127], v[148:155], v[180:187], v[124:127], v144, v144 op_sel_hi:[0,0,0]
	v_mfma_scale_f32_16x16x128_f8f6f4 v[116:119], v[156:163], v[180:187], v[116:119], v144, v144 op_sel_hi:[0,0,0]
	v_mfma_scale_f32_16x16x128_f8f6f4 v[108:111], v[148:155], v[188:195], v[108:111], v144, v144 op_sel_hi:[0,0,0]
	v_mfma_scale_f32_16x16x128_f8f6f4 v[100:103], v[156:163], v[188:195], v[100:103], v144, v144 op_sel_hi:[0,0,0]
	v_mfma_scale_f32_16x16x128_f8f6f4 v[212:215], v[148:155], v[196:203], v[92:95], v144, v144 op_sel_hi:[0,0,0]
	v_mfma_scale_f32_16x16x128_f8f6f4 v[216:219], v[156:163], v[196:203], v[84:87], v144, v144 op_sel_hi:[0,0,0]
	v_mfma_scale_f32_16x16x128_f8f6f4 v[220:223], v[148:155], v[204:211], v[76:79], v144, v144 op_sel_hi:[0,0,0]
	v_mfma_scale_f32_16x16x128_f8f6f4 v[224:227], v[156:163], v[204:211], v[68:71], v144, v144 op_sel_hi:[0,0,0]
	s_setprio 0
	s_setprio 1
	v_mfma_scale_f32_16x16x128_f8f6f4 v[120:123], v[164:171], v[180:187], v[120:123], v144, v144 op_sel_hi:[0,0,0]
	v_mfma_scale_f32_16x16x128_f8f6f4 v[112:115], v[172:179], v[180:187], v[112:115], v144, v144 op_sel_hi:[0,0,0]
	v_mfma_scale_f32_16x16x128_f8f6f4 v[104:107], v[164:171], v[188:195], v[104:107], v144, v144 op_sel_hi:[0,0,0]
	v_mfma_scale_f32_16x16x128_f8f6f4 v[96:99], v[172:179], v[188:195], v[96:99], v144, v144 op_sel_hi:[0,0,0]
	v_mfma_scale_f32_16x16x128_f8f6f4 v[180:183], v[164:171], v[196:203], v[88:91], v144, v144 op_sel_hi:[0,0,0]
	v_mfma_scale_f32_16x16x128_f8f6f4 v[184:187], v[172:179], v[196:203], v[80:83], v144, v144 op_sel_hi:[0,0,0]
	v_mfma_scale_f32_16x16x128_f8f6f4 v[188:191], v[164:171], v[204:211], v[72:75], v144, v144 op_sel_hi:[0,0,0]
	v_mfma_scale_f32_16x16x128_f8f6f4 v[192:195], v[172:179], v[204:211], v[64:67], v144, v144 op_sel_hi:[0,0,0]
	s_setprio 0
	s_barrier
	s_add_i32 s76, s61, s3
	s_nop 2
	ds_read_b128 v[64:67], v143 offset:16384
	ds_read_b128 v[68:71], v143 offset:17408
	ds_read_b128 v[72:75], v143 offset:18432
	ds_read_b128 v[76:79], v143 offset:19456
	ds_read_b128 v[80:83], v143 offset:20480
	ds_read_b128 v[84:87], v143 offset:21504
	ds_read_b128 v[88:91], v143 offset:22528
	ds_read_b128 v[92:95], v143 offset:23552
	s_mov_b32 m0, s76
	s_nop 0
	global_load_lds_dwordx4 v254, s[58:59]
	s_add_i32 m0, s76, 0x2000
	s_add_u32 s76, s58, 0x40000
	global_load_lds_dwordx4 v141, s[58:59]
	s_addc_u32 s77, s59, 0
	s_add_i32 s78, s62, s3
	s_mov_b32 m0, s78
	s_nop 0
	global_load_lds_dwordx4 v254, s[76:77]
	s_add_i32 m0, s78, 0x2000
	s_nop 0
	global_load_lds_dwordx4 v141, s[76:77]
	s_mov_b32 m0, s20
	s_nop 0
	global_load_lds_dwordx4 v147, s[56:57]
	s_mov_b32 m0, s21
	s_nop 0
	global_load_lds_dwordx4 v140, s[56:57]
	s_waitcnt vmcnt(8)
	s_waitcnt lgkmcnt(0)
	s_barrier
	s_setprio 1
	s_waitcnt lgkmcnt(0)
	v_mfma_scale_f32_16x16x128_f8f6f4 v[60:63], v[148:155], v[64:71], v[60:63], v144, v144 op_sel_hi:[0,0,0]
	v_mfma_scale_f32_16x16x128_f8f6f4 v[52:55], v[156:163], v[64:71], v[52:55], v144, v144 op_sel_hi:[0,0,0]
	v_mfma_scale_f32_16x16x128_f8f6f4 v[44:47], v[148:155], v[72:79], v[44:47], v144, v144 op_sel_hi:[0,0,0]
	v_mfma_scale_f32_16x16x128_f8f6f4 v[204:207], v[156:163], v[72:79], v[36:39], v144, v144 op_sel_hi:[0,0,0]
	v_mfma_scale_f32_16x16x128_f8f6f4 v[208:211], v[148:155], v[80:87], v[28:31], v144, v144 op_sel_hi:[0,0,0]
	v_mfma_scale_f32_16x16x128_f8f6f4 v[230:233], v[156:163], v[80:87], v[20:23], v144, v144 op_sel_hi:[0,0,0]
	v_mfma_scale_f32_16x16x128_f8f6f4 v[234:237], v[148:155], v[88:95], v[12:15], v144, v144 op_sel_hi:[0,0,0]
	v_mfma_scale_f32_16x16x128_f8f6f4 v[238:241], v[156:163], v[88:95], v[4:7], v144, v144 op_sel_hi:[0,0,0]
	s_setprio 0
	s_setprio 1
	v_mfma_scale_f32_16x16x128_f8f6f4 v[56:59], v[164:171], v[64:71], v[56:59], v144, v144 op_sel_hi:[0,0,0]
	v_mfma_scale_f32_16x16x128_f8f6f4 v[48:51], v[172:179], v[64:71], v[48:51], v144, v144 op_sel_hi:[0,0,0]
	v_mfma_scale_f32_16x16x128_f8f6f4 v[40:43], v[164:171], v[72:79], v[40:43], v144, v144 op_sel_hi:[0,0,0]
	v_mfma_scale_f32_16x16x128_f8f6f4 v[242:245], v[172:179], v[72:79], v[32:35], v144, v144 op_sel_hi:[0,0,0]
	v_mfma_scale_f32_16x16x128_f8f6f4 v[246:249], v[164:171], v[80:87], v[24:27], v144, v144 op_sel_hi:[0,0,0]
	v_mfma_scale_f32_16x16x128_f8f6f4 v[250:253], v[172:179], v[80:87], v[16:19], v144, v144 op_sel_hi:[0,0,0]
	v_mfma_scale_f32_16x16x128_f8f6f4 v[132:135], v[164:171], v[88:95], v[8:11], v144, v144 op_sel_hi:[0,0,0]
	v_mfma_scale_f32_16x16x128_f8f6f4 v[136:139], v[172:179], v[88:95], v[0:3], v144, v144 op_sel_hi:[0,0,0]
	s_setprio 0
	s_barrier
; #define PG8_STAGE(bufoff, gbase, voff) do { _Pragma("unroll") for (int _i = 0; _i < 2; ++_i) \
;         { unsigned _vo = (voff)[_i]; asm volatile("" : "+v"(_vo));     \
;         __builtin_amdgcn_global_load_lds((const unsigned*)((const char*)(gbase) + _vo), (PG8_LAS unsigned*)(lds + (bufoff) + ldsw + _i * 8192), 16, 0, 0); } } while (0)
; #define PG8_LDA(dst, b, h) do { _Pragma("unroll") for (int m = 0; m < 4; ++m) _Pragma("unroll") for (int k = 0; k < 2; ++k) dst[m][k] = *(const PG8_LAS bf16x8*)(lds + PG8_SA(b, h) + aoff + m * 2048 + k * 1024); } while (0)
; #define PG8_LDB(dst, b, h) do { _Pragma("unroll") for (int n = 0; n < 2; ++n) _Pragma("unroll") for (int k = 0; k < 2; ++k) dst[n][k] = *(const PG8_LAS bf16x8*)(lds + PG8_SB(b, h) + boff + n * 2048 + k * 1024); } while (0)
; #define PG8_WAIT_V(n) asm volatile("s_waitcnt vmcnt(" #n ")" ::: "memory")
; #define PG8_WAIT_L(n) asm volatile("s_waitcnt lgkmcnt(" #n ")" ::: "memory")
; #define PG8_BAR __builtin_amdgcn_s_barrier()
; #define PG8_SCHED __builtin_amdgcn_sched_barrier(0)
; template <class Epi, class Sched, bool ALIGN_EPI = false, bool SP2 = false, bool ABLK = false, bool F8 = false>
; __device__ __forceinline__ void gemm_phase(PG8_LAS unsigned char* lds, const Gemm g, const Sched& S, const Epi& E, const int wave_s) {
;     ...
;             PG8_LDB(B0, 1, 0); PG8_LDB(B1, 1, 1); PG8_SCHED; PG8_LDA(At, 1, 0); PG8_STAGE(PG8_SA(0, 1), a2 + hstepA, voffA);
;             PG8_WAIT_V(8); PG8_WAIT_L(0); PG8_BAR; PG8_MMA(0, 0, At, B0); PG8_MMA(0, 1, At, B1); PG8_BAR; PG8_SCHED;
;             PG8_LDA(At, 1, 1); PG8_STAGE(PG8_SB(1, 0), b3, voffB); PG8_STAGE(PG8_SB(1, 1), b3 + hstep, voffB); PG8_STAGE(PG8_SA(1, 0), a3, voffA);
;             PG8_WAIT_V(8); PG8_WAIT_L(0); PG8_BAR; PG8_MMA(1, 0, At, B0); PG8_MMA(1, 1, At, B1); PG8_BAR; PG8_SCHED;
	s_add_i32 s78, 0, 0x18000
	s_nop 2
	v_add_u32_e32 v8, s78, v142
	s_add_i32 s79, 0, 0x1c000
	ds_read_b128 v[0:3], v8
	ds_read_b128 v[4:7], v8 offset:1024
	ds_read_b128 v[148:151], v8 offset:2048
	ds_read_b128 v[152:155], v8 offset:3072
	v_add_u32_e32 v8, s79, v142
	ds_read_b128 v[156:159], v8
	ds_read_b128 v[160:163], v8 offset:1024
	ds_read_b128 v[164:167], v8 offset:2048
	ds_read_b128 v[168:171], v8 offset:3072
	s_add_u32 s76, s56, 0x40000
	s_mov_b32 m0, s22
	ds_read_b128 v[8:11], v143 offset:32768
	ds_read_b128 v[12:15], v143 offset:33792
	ds_read_b128 v[16:19], v143 offset:34816
	ds_read_b128 v[20:23], v143 offset:35840
	ds_read_b128 v[24:27], v143 offset:36864
	ds_read_b128 v[28:31], v143 offset:37888
	ds_read_b128 v[32:35], v143 offset:38912
	ds_read_b128 v[36:39], v143 offset:39936
	s_addc_u32 s77, s57, 0
	s_nop 0
	global_load_lds_dwordx4 v147, s[76:77]
	s_mov_b32 m0, s23
	s_nop 0
	global_load_lds_dwordx4 v140, s[76:77]
	s_waitcnt vmcnt(8)
	s_waitcnt lgkmcnt(0)
	s_barrier
	s_setprio 1
	s_waitcnt lgkmcnt(0)
	v_mfma_scale_f32_16x16x128_f8f6f4 v[124:127], v[0:7], v[8:15], v[124:127], v144, v144 op_sel_hi:[0,0,0]
	v_mfma_scale_f32_16x16x128_f8f6f4 v[116:119], v[148:155], v[8:15], v[116:119], v144, v144 op_sel_hi:[0,0,0]
	v_mfma_scale_f32_16x16x128_f8f6f4 v[108:111], v[0:7], v[16:23], v[108:111], v144, v144 op_sel_hi:[0,0,0]
	v_mfma_scale_f32_16x16x128_f8f6f4 v[100:103], v[148:155], v[16:23], v[100:103], v144, v144 op_sel_hi:[0,0,0]
	v_mfma_scale_f32_16x16x128_f8f6f4 v[92:95], v[0:7], v[24:31], v[212:215], v144, v144 op_sel_hi:[0,0,0]
	v_mfma_scale_f32_16x16x128_f8f6f4 v[84:87], v[148:155], v[24:31], v[216:219], v144, v144 op_sel_hi:[0,0,0]
	v_mfma_scale_f32_16x16x128_f8f6f4 v[76:79], v[0:7], v[32:39], v[220:223], v144, v144 op_sel_hi:[0,0,0]
	v_mfma_scale_f32_16x16x128_f8f6f4 v[68:71], v[148:155], v[32:39], v[224:227], v144, v144 op_sel_hi:[0,0,0]
	s_setprio 0
	s_setprio 1
	v_mfma_scale_f32_16x16x128_f8f6f4 v[120:123], v[156:163], v[8:15], v[120:123], v144, v144 op_sel_hi:[0,0,0]
	v_mfma_scale_f32_16x16x128_f8f6f4 v[112:115], v[164:171], v[8:15], v[112:115], v144, v144 op_sel_hi:[0,0,0]
	v_mfma_scale_f32_16x16x128_f8f6f4 v[104:107], v[156:163], v[16:23], v[104:107], v144, v144 op_sel_hi:[0,0,0]
	v_mfma_scale_f32_16x16x128_f8f6f4 v[96:99], v[164:171], v[16:23], v[96:99], v144, v144 op_sel_hi:[0,0,0]
	v_mfma_scale_f32_16x16x128_f8f6f4 v[88:91], v[156:163], v[24:31], v[180:183], v144, v144 op_sel_hi:[0,0,0]
	v_mfma_scale_f32_16x16x128_f8f6f4 v[80:83], v[164:171], v[24:31], v[184:187], v144, v144 op_sel_hi:[0,0,0]
	v_mfma_scale_f32_16x16x128_f8f6f4 v[72:75], v[156:163], v[32:39], v[188:191], v144, v144 op_sel_hi:[0,0,0]
	v_mfma_scale_f32_16x16x128_f8f6f4 v[64:67], v[164:171], v[32:39], v[192:195], v144, v144 op_sel_hi:[0,0,0]
	s_setprio 0
	s_barrier
	ds_read_b128 v[172:175], v143 offset:49152
	ds_read_b128 v[176:179], v143 offset:50176
	ds_read_b128 v[180:183], v143 offset:51200
	ds_read_b128 v[184:187], v143 offset:52224
	ds_read_b128 v[188:191], v143 offset:53248
	ds_read_b128 v[192:195], v143 offset:54272
	ds_read_b128 v[196:199], v143 offset:55296
	ds_read_b128 v[200:203], v143 offset:56320
	s_add_i32 s76, s78, s3
	s_add_u32 vcc_lo, s58, s12
	s_addc_u32 vcc_hi, s59, s13
	s_mov_b32 m0, s76
	s_nop 0
	global_load_lds_dwordx4 v254, vcc
	s_add_i32 m0, s76, 0x2000
	s_add_u32 vcc_lo, s58, s12
	s_addc_u32 vcc_hi, s59, s13
	s_add_u32 s58, s58, 0x40080
	global_load_lds_dwordx4 v141, vcc
	s_addc_u32 s59, s59, 0
	s_add_i32 s76, s79, s3
	s_mov_b32 m0, s76
	s_nop 0
	global_load_lds_dwordx4 v254, s[58:59]
	s_add_i32 m0, s76, 0x2000
	s_nop 0
	global_load_lds_dwordx4 v141, s[58:59]
	s_mov_b32 m0, s33
	s_add_u32 vcc_lo, s56, s12
	s_addc_u32 vcc_hi, s57, s13
	v_mov_b32_e32 v128, v140
	global_load_lds_dwordx4 v147, vcc
	s_mov_b32 m0, s51
	s_add_u32 vcc_lo, s56, s12
	s_addc_u32 vcc_hi, s57, s13
	global_load_lds_dwordx4 v140, vcc
	s_waitcnt vmcnt(8)
	s_waitcnt lgkmcnt(0)
	s_barrier
	s_setprio 1
	s_waitcnt lgkmcnt(0)
	v_mfma_scale_f32_16x16x128_f8f6f4 v[60:63], v[0:7], v[172:179], v[60:63], v144, v144 op_sel_hi:[0,0,0]
	v_mfma_scale_f32_16x16x128_f8f6f4 v[52:55], v[148:155], v[172:179], v[52:55], v144, v144 op_sel_hi:[0,0,0]
	v_mfma_scale_f32_16x16x128_f8f6f4 v[44:47], v[0:7], v[180:187], v[44:47], v144, v144 op_sel_hi:[0,0,0]
	v_mfma_scale_f32_16x16x128_f8f6f4 v[36:39], v[148:155], v[180:187], v[204:207], v144, v144 op_sel_hi:[0,0,0]
	v_mfma_scale_f32_16x16x128_f8f6f4 v[28:31], v[0:7], v[188:195], v[208:211], v144, v144 op_sel_hi:[0,0,0]
	v_mfma_scale_f32_16x16x128_f8f6f4 v[20:23], v[148:155], v[188:195], v[230:233], v144, v144 op_sel_hi:[0,0,0]
	v_mfma_scale_f32_16x16x128_f8f6f4 v[12:15], v[0:7], v[196:203], v[234:237], v144, v144 op_sel_hi:[0,0,0]
	v_mfma_scale_f32_16x16x128_f8f6f4 v[4:7], v[148:155], v[196:203], v[238:241], v144, v144 op_sel_hi:[0,0,0]
	s_setprio 0
	s_setprio 1
	v_mfma_scale_f32_16x16x128_f8f6f4 v[56:59], v[156:163], v[172:179], v[56:59], v144, v144 op_sel_hi:[0,0,0]
	v_mfma_scale_f32_16x16x128_f8f6f4 v[48:51], v[164:171], v[172:179], v[48:51], v144, v144 op_sel_hi:[0,0,0]
	v_mfma_scale_f32_16x16x128_f8f6f4 v[40:43], v[156:163], v[180:187], v[40:43], v144, v144 op_sel_hi:[0,0,0]
	v_mfma_scale_f32_16x16x128_f8f6f4 v[32:35], v[164:171], v[180:187], v[242:245], v144, v144 op_sel_hi:[0,0,0]
	v_mfma_scale_f32_16x16x128_f8f6f4 v[24:27], v[156:163], v[188:195], v[246:249], v144, v144 op_sel_hi:[0,0,0]
	v_mfma_scale_f32_16x16x128_f8f6f4 v[16:19], v[164:171], v[188:195], v[250:253], v144, v144 op_sel_hi:[0,0,0]
	v_mfma_scale_f32_16x16x128_f8f6f4 v[8:11], v[156:163], v[196:203], v[132:135], v144, v144 op_sel_hi:[0,0,0]
	v_mfma_scale_f32_16x16x128_f8f6f4 v[0:3], v[164:171], v[196:203], v[136:139], v144, v144 op_sel_hi:[0,0,0]
	s_setprio 0
	s_barrier
	s_add_i32 s74, s74, 2
	s_add_u32 s54, s54, 0x100
	s_addc_u32 s55, s55, 0
	s_add_u32 s72, s72, 0x100
	s_addc_u32 s73, s73, 0
	s_cmp_gt_u32 s74, 13
	s_cbranch_scc1 .LBB0_813

; #define PG8_STAGE(bufoff, gbase, voff) do { _Pragma("unroll") for (int _i = 0; _i < 2; ++_i) \
;         { unsigned _vo = (voff)[_i]; asm volatile("" : "+v"(_vo));     \
;         __builtin_amdgcn_global_load_lds((const unsigned*)((const char*)(gbase) + _vo), (PG8_LAS unsigned*)(lds + (bufoff) + ldsw + _i * 8192), 16, 0, 0); } } while (0)
; #define PG8_LDA(dst, b, h) do { _Pragma("unroll") for (int m = 0; m < 4; ++m) _Pragma("unroll") for (int k = 0; k < 2; ++k) dst[m][k] = *(const PG8_LAS bf16x8*)(lds + PG8_SA(b, h) + aoff + m * 2048 + k * 1024); } while (0)
; #define PG8_LDB(dst, b, h) do { _Pragma("unroll") for (int n = 0; n < 2; ++n) _Pragma("unroll") for (int k = 0; k < 2; ++k) dst[n][k] = *(const PG8_LAS bf16x8*)(lds + PG8_SB(b, h) + boff + n * 2048 + k * 1024); } while (0)
; #define PG8_WAIT_V(n) asm volatile("s_waitcnt vmcnt(" #n ")" ::: "memory")
; #define PG8_WAIT_L(n) asm volatile("s_waitcnt lgkmcnt(" #n ")" ::: "memory")
; #define PG8_BAR __builtin_amdgcn_s_barrier()
; #define PG8_SCHED __builtin_amdgcn_sched_barrier(0)
; template <class Epi, class Sched, bool ALIGN_EPI = false, bool SP2 = false, bool ABLK = false, bool F8 = false>
; __device__ __forceinline__ void gemm_phase(PG8_LAS unsigned char* lds, const Gemm g, const Sched& S, const Epi& E, const int wave_s) {
;     ...
;             const bool last = (t == nt - 2);
;             const char* a1 = cA + (size_t)(t + 1) * kstepA;
;             const char* a2 = last ? nA : cA + (size_t)(t + 2) * kstepA; const char* b2 = last ? nB : cB + (size_t)(t + 2) * kstep;
;             const char* a3 = a2 + kstepA; const char* b3 = b2 + kstep;
;             if (last && has_next) { S.a_ready(nxt); if constexpr (Epi::PREF) E.prefetch(nxt, wid, lane); }
;             if constexpr (SP2) {
;             PG8_LDB(B0, 0, 0); PG8_LDB(B1, 0, 1); PG8_SCHED; PG8_LDA(At, 0, 0); PG8_STAGE(PG8_SA(1, 1), a1 + hstepA, voffA);
;             PG8_WAIT_V(8); PG8_WAIT_L(0); PG8_BAR; PG8_MMA(0, 0, At, B0); PG8_MMA(0, 1, At, B1); PG8_BAR; PG8_SCHED;
;             PG8_LDA(At, 0, 1); PG8_STAGE(PG8_SB(0, 0), b2, voffB); PG8_STAGE(PG8_SB(0, 1), b2 + hstep, voffB); PG8_STAGE(PG8_SA(0, 0), a2, voffA);
;             PG8_WAIT_V(8); PG8_WAIT_L(0); PG8_BAR; PG8_MMA(1, 0, At, B0); PG8_MMA(1, 1, At, B1); PG8_BAR; PG8_SCHED;
.LBB0_894:
	ds_read_b128 v[104:107], v230
	ds_read_b128 v[116:119], v230 offset:1024
	ds_read_b128 v[128:131], v230 offset:2048
	ds_read_b128 v[140:143], v230 offset:3072
	ds_read_b128 v[144:147], v231
	ds_read_b128 v[148:151], v231 offset:1024
	ds_read_b128 v[152:155], v231 offset:2048
	ds_read_b128 v[156:159], v231 offset:3072
	s_add_u32 s46, s44, 0x4000
	s_addc_u32 s47, s45, 0
	s_cmpk_eq_i32 s62, 0x54
	s_cselect_b32 s50, s12, s46
	s_cselect_b32 s51, s13, s47
	s_cselect_b32 s48, s42, s60
	s_cselect_b32 s49, s43, s61
	s_add_u32 s46, s50, 0x8000
	s_addc_u32 s47, s51, 0
	ds_read_b128 v[160:163], v232
	ds_read_b128 v[164:167], v232 offset:1024
	ds_read_b128 v[168:171], v232 offset:2048
	ds_read_b128 v[172:175], v232 offset:3072
	ds_read_b128 v[176:179], v232 offset:4096
	ds_read_b128 v[180:183], v232 offset:5120
	ds_read_b128 v[190:193], v232 offset:6144
	ds_read_b128 v[194:197], v232 offset:7168
	s_add_i32 m0, s20, 0xc000
	s_nop 0
	global_load_lds_dwordx4 v222, s[44:45]
	s_add_i32 m0, s20, 0xe000
	s_nop 0
	global_load_lds_dwordx4 v224, s[44:45]
	s_waitcnt vmcnt(8)
	s_waitcnt lgkmcnt(0)
	s_barrier
	s_setprio 1
	s_waitcnt lgkmcnt(0)
	v_mfma_f32_16x16x32_bf16 v[136:139], v[104:107], v[160:163], v[136:139]
	v_mfma_f32_16x16x32_bf16 v[132:135], v[128:131], v[160:163], v[132:135]
	v_mfma_f32_16x16x32_bf16 v[112:115], v[104:107], v[168:171], v[112:115]
	v_mfma_f32_16x16x32_bf16 v[108:111], v[128:131], v[168:171], v[108:111]
	v_mfma_f32_16x16x32_bf16 v[92:95], v[104:107], v[176:179], v[92:95]
	v_mfma_f32_16x16x32_bf16 v[88:91], v[128:131], v[176:179], v[88:91]
	v_mfma_f32_16x16x32_bf16 v[76:79], v[104:107], v[190:193], v[76:79]
	v_mfma_f32_16x16x32_bf16 v[72:75], v[128:131], v[190:193], v[72:75]
	v_mfma_f32_16x16x32_bf16 v[136:139], v[116:119], v[164:167], v[136:139]
	v_mfma_f32_16x16x32_bf16 v[132:135], v[140:143], v[164:167], v[132:135]
	v_mfma_f32_16x16x32_bf16 v[112:115], v[116:119], v[172:175], v[112:115]
	v_mfma_f32_16x16x32_bf16 v[108:111], v[140:143], v[172:175], v[108:111]
	v_mfma_f32_16x16x32_bf16 v[92:95], v[116:119], v[180:183], v[92:95]
	v_mfma_f32_16x16x32_bf16 v[88:91], v[140:143], v[180:183], v[88:91]
	v_mfma_f32_16x16x32_bf16 v[76:79], v[116:119], v[194:197], v[76:79]
	v_mfma_f32_16x16x32_bf16 v[72:75], v[140:143], v[194:197], v[72:75]
	s_setprio 0
	s_setprio 1
	v_mfma_f32_16x16x32_bf16 v[124:127], v[144:147], v[160:163], v[124:127]
	v_mfma_f32_16x16x32_bf16 v[120:123], v[152:155], v[160:163], v[120:123]
	v_mfma_f32_16x16x32_bf16 v[100:103], v[144:147], v[168:171], v[100:103]
	v_mfma_f32_16x16x32_bf16 v[96:99], v[152:155], v[168:171], v[96:99]
	v_mfma_f32_16x16x32_bf16 v[84:87], v[144:147], v[176:179], v[84:87]
	v_mfma_f32_16x16x32_bf16 v[80:83], v[152:155], v[176:179], v[80:83]
	v_mfma_f32_16x16x32_bf16 v[68:71], v[144:147], v[190:193], v[68:71]
	v_mfma_f32_16x16x32_bf16 v[64:67], v[152:155], v[190:193], v[64:67]
	v_mfma_f32_16x16x32_bf16 v[124:127], v[148:151], v[164:167], v[124:127]
	v_mfma_f32_16x16x32_bf16 v[120:123], v[156:159], v[164:167], v[120:123]
	v_mfma_f32_16x16x32_bf16 v[100:103], v[148:151], v[172:175], v[100:103]
	v_mfma_f32_16x16x32_bf16 v[96:99], v[156:159], v[172:175], v[96:99]
	v_mfma_f32_16x16x32_bf16 v[84:87], v[148:151], v[180:183], v[84:87]
	v_mfma_f32_16x16x32_bf16 v[80:83], v[156:159], v[180:183], v[80:83]
	v_mfma_f32_16x16x32_bf16 v[68:71], v[148:151], v[194:197], v[68:71]
	v_mfma_f32_16x16x32_bf16 v[64:67], v[156:159], v[194:197], v[64:67]
	s_setprio 0
	s_barrier
	s_add_i32 s63, s54, s3
	ds_read_b128 v[160:163], v232 offset:16384
	ds_read_b128 v[164:167], v232 offset:17408
	ds_read_b128 v[168:171], v232 offset:18432
	ds_read_b128 v[172:175], v232 offset:19456
	ds_read_b128 v[176:179], v232 offset:20480
	ds_read_b128 v[180:183], v232 offset:21504
	ds_read_b128 v[190:193], v232 offset:22528
	ds_read_b128 v[194:197], v232 offset:23552
	s_mov_b32 m0, s63
	s_nop 0
	global_load_lds_dwordx4 v223, s[48:49]
	s_add_i32 m0, s63, 0x2000
	s_add_u32 s64, s48, 0x160000
	global_load_lds_dwordx4 v225, s[48:49]
	s_addc_u32 s65, s49, 0
	s_add_i32 s63, s55, s3
	s_mov_b32 m0, s63
	s_nop 0
	global_load_lds_dwordx4 v223, s[64:65]
	s_add_i32 m0, s63, 0x2000
	s_nop 0
	global_load_lds_dwordx4 v225, s[64:65]
	s_mov_b32 m0, s20
	s_nop 0
	global_load_lds_dwordx4 v222, s[50:51]
	s_mov_b32 m0, s21
	s_nop 0
	global_load_lds_dwordx4 v224, s[50:51]
	s_waitcnt vmcnt(8)
	s_waitcnt lgkmcnt(0)
	s_barrier
	s_setprio 1
	s_waitcnt lgkmcnt(0)
	v_mfma_f32_16x16x32_bf16 v[60:63], v[104:107], v[160:163], v[60:63]
	v_mfma_f32_16x16x32_bf16 v[56:59], v[128:131], v[160:163], v[56:59]
	v_mfma_f32_16x16x32_bf16 v[44:47], v[104:107], v[168:171], v[44:47]
	v_mfma_f32_16x16x32_bf16 v[40:43], v[128:131], v[168:171], v[40:43]
	v_mfma_f32_16x16x32_bf16 v[28:31], v[104:107], v[176:179], v[28:31]
	v_mfma_f32_16x16x32_bf16 v[24:27], v[128:131], v[176:179], v[24:27]
	v_mfma_f32_16x16x32_bf16 v[12:15], v[104:107], v[190:193], v[12:15]
	v_mfma_f32_16x16x32_bf16 v[8:11], v[128:131], v[190:193], v[8:11]
	v_mfma_f32_16x16x32_bf16 v[60:63], v[116:119], v[164:167], v[60:63]
	v_mfma_f32_16x16x32_bf16 v[56:59], v[140:143], v[164:167], v[56:59]
	v_mfma_f32_16x16x32_bf16 v[44:47], v[116:119], v[172:175], v[44:47]
	v_mfma_f32_16x16x32_bf16 v[40:43], v[140:143], v[172:175], v[40:43]
	v_mfma_f32_16x16x32_bf16 v[28:31], v[116:119], v[180:183], v[28:31]
	v_mfma_f32_16x16x32_bf16 v[24:27], v[140:143], v[180:183], v[24:27]
	v_mfma_f32_16x16x32_bf16 v[12:15], v[116:119], v[194:197], v[12:15]
	v_mfma_f32_16x16x32_bf16 v[8:11], v[140:143], v[194:197], v[8:11]
	s_setprio 0
	s_setprio 1
	v_mfma_f32_16x16x32_bf16 v[52:55], v[144:147], v[160:163], v[52:55]
	v_mfma_f32_16x16x32_bf16 v[48:51], v[152:155], v[160:163], v[48:51]
	v_mfma_f32_16x16x32_bf16 v[36:39], v[144:147], v[168:171], v[36:39]
	v_mfma_f32_16x16x32_bf16 v[32:35], v[152:155], v[168:171], v[32:35]
	v_mfma_f32_16x16x32_bf16 v[20:23], v[144:147], v[176:179], v[20:23]
	v_mfma_f32_16x16x32_bf16 v[16:19], v[152:155], v[176:179], v[16:19]
	v_mfma_f32_16x16x32_bf16 v[4:7], v[144:147], v[190:193], v[4:7]
	v_mfma_f32_16x16x32_bf16 v[0:3], v[152:155], v[190:193], v[0:3]
	v_mfma_f32_16x16x32_bf16 v[52:55], v[148:151], v[164:167], v[52:55]
	v_mfma_f32_16x16x32_bf16 v[48:51], v[156:159], v[164:167], v[48:51]
	v_mfma_f32_16x16x32_bf16 v[36:39], v[148:151], v[172:175], v[36:39]
	v_mfma_f32_16x16x32_bf16 v[32:35], v[156:159], v[172:175], v[32:35]
	v_mfma_f32_16x16x32_bf16 v[20:23], v[148:151], v[180:183], v[20:23]
	v_mfma_f32_16x16x32_bf16 v[16:19], v[156:159], v[180:183], v[16:19]
	v_mfma_f32_16x16x32_bf16 v[4:7], v[148:151], v[194:197], v[4:7]
	v_mfma_f32_16x16x32_bf16 v[0:3], v[156:159], v[194:197], v[0:3]
	s_setprio 0
	s_barrier
; #define PG8_STAGE(bufoff, gbase, voff) do { _Pragma("unroll") for (int _i = 0; _i < 2; ++_i) \
;         { unsigned _vo = (voff)[_i]; asm volatile("" : "+v"(_vo));     \
;         __builtin_amdgcn_global_load_lds((const unsigned*)((const char*)(gbase) + _vo), (PG8_LAS unsigned*)(lds + (bufoff) + ldsw + _i * 8192), 16, 0, 0); } } while (0)
; #define PG8_LDA(dst, b, h) do { _Pragma("unroll") for (int m = 0; m < 4; ++m) _Pragma("unroll") for (int k = 0; k < 2; ++k) dst[m][k] = *(const PG8_LAS bf16x8*)(lds + PG8_SA(b, h) + aoff + m * 2048 + k * 1024); } while (0)
; #define PG8_LDB(dst, b, h) do { _Pragma("unroll") for (int n = 0; n < 2; ++n) _Pragma("unroll") for (int k = 0; k < 2; ++k) dst[n][k] = *(const PG8_LAS bf16x8*)(lds + PG8_SB(b, h) + boff + n * 2048 + k * 1024); } while (0)
; #define PG8_WAIT_V(n) asm volatile("s_waitcnt vmcnt(" #n ")" ::: "memory")
; #define PG8_WAIT_L(n) asm volatile("s_waitcnt lgkmcnt(" #n ")" ::: "memory")
; #define PG8_BAR __builtin_amdgcn_s_barrier()
; #define PG8_SCHED __builtin_amdgcn_sched_barrier(0)
; template <class Epi, class Sched, bool ALIGN_EPI = false, bool SP2 = false, bool ABLK = false, bool F8 = false>
; __device__ __forceinline__ void gemm_phase(PG8_LAS unsigned char* lds, const Gemm g, const Sched& S, const Epi& E, const int wave_s) {
;     ...
;             PG8_LDB(B0, 1, 0); PG8_LDB(B1, 1, 1); PG8_SCHED; PG8_LDA(At, 1, 0); PG8_STAGE(PG8_SA(0, 1), a2 + hstepA, voffA);
;             PG8_WAIT_V(8); PG8_WAIT_L(0); PG8_BAR; PG8_MMA(0, 0, At, B0); PG8_MMA(0, 1, At, B1); PG8_BAR; PG8_SCHED;
;             PG8_LDA(At, 1, 1); PG8_STAGE(PG8_SB(1, 0), b3, voffB); PG8_STAGE(PG8_SB(1, 1), b3 + hstep, voffB); PG8_STAGE(PG8_SA(1, 0), a3, voffA);
;             PG8_WAIT_V(8); PG8_WAIT_L(0); PG8_BAR; PG8_MMA(1, 0, At, B0); PG8_MMA(1, 1, At, B1); PG8_BAR; PG8_SCHED;
;     ...
;         if constexpr (ALIGN_EPI) { if (wr == 0) PG8_BAR; }
	s_add_i32 s63, 0, 0x18000
	s_add_i32 s64, 0, 0x1c000
	v_add_u32_e32 v140, s63, v227
	v_add_u32_e32 v156, s64, v227
	ds_read_b128 v[104:107], v140
	ds_read_b128 v[116:119], v140 offset:1024
	ds_read_b128 v[128:131], v140 offset:2048
	ds_read_b128 v[140:143], v140 offset:3072
	ds_read_b128 v[144:147], v156
	ds_read_b128 v[148:151], v156 offset:1024
	ds_read_b128 v[152:155], v156 offset:2048
	ds_read_b128 v[156:159], v156 offset:3072
	s_add_u32 s50, s50, 0x4000
	s_mov_b32 m0, s22
	ds_read_b128 v[160:163], v232 offset:32768
	ds_read_b128 v[164:167], v232 offset:33792
	ds_read_b128 v[168:171], v232 offset:34816
	ds_read_b128 v[172:175], v232 offset:35840
	ds_read_b128 v[176:179], v232 offset:36864
	ds_read_b128 v[180:183], v232 offset:37888
	ds_read_b128 v[190:193], v232 offset:38912
	ds_read_b128 v[194:197], v232 offset:39936
	s_addc_u32 s51, s51, 0
	s_nop 0
	global_load_lds_dwordx4 v222, s[50:51]
	s_mov_b32 m0, s23
	s_nop 0
	global_load_lds_dwordx4 v224, s[50:51]
	s_waitcnt vmcnt(8)
	s_waitcnt lgkmcnt(0)
	s_barrier
	s_setprio 1
	s_waitcnt lgkmcnt(0)
	v_mfma_f32_16x16x32_bf16 v[136:139], v[104:107], v[160:163], v[136:139]
	v_mfma_f32_16x16x32_bf16 v[132:135], v[128:131], v[160:163], v[132:135]
	v_mfma_f32_16x16x32_bf16 v[112:115], v[104:107], v[168:171], v[112:115]
	v_mfma_f32_16x16x32_bf16 v[108:111], v[128:131], v[168:171], v[108:111]
	v_mfma_f32_16x16x32_bf16 v[92:95], v[104:107], v[176:179], v[92:95]
	v_mfma_f32_16x16x32_bf16 v[88:91], v[128:131], v[176:179], v[88:91]
	v_mfma_f32_16x16x32_bf16 v[76:79], v[104:107], v[190:193], v[76:79]
	v_mfma_f32_16x16x32_bf16 v[72:75], v[128:131], v[190:193], v[72:75]
	v_mfma_f32_16x16x32_bf16 v[136:139], v[116:119], v[164:167], v[136:139]
	v_mfma_f32_16x16x32_bf16 v[132:135], v[140:143], v[164:167], v[132:135]
	v_mfma_f32_16x16x32_bf16 v[112:115], v[116:119], v[172:175], v[112:115]
	v_mfma_f32_16x16x32_bf16 v[108:111], v[140:143], v[172:175], v[108:111]
	v_mfma_f32_16x16x32_bf16 v[92:95], v[116:119], v[180:183], v[92:95]
	v_mfma_f32_16x16x32_bf16 v[88:91], v[140:143], v[180:183], v[88:91]
	v_mfma_f32_16x16x32_bf16 v[76:79], v[116:119], v[194:197], v[76:79]
	v_mfma_f32_16x16x32_bf16 v[72:75], v[140:143], v[194:197], v[72:75]
	s_setprio 0
	s_setprio 1
	v_mfma_f32_16x16x32_bf16 v[124:127], v[144:147], v[160:163], v[124:127]
	v_mfma_f32_16x16x32_bf16 v[120:123], v[152:155], v[160:163], v[120:123]
	v_mfma_f32_16x16x32_bf16 v[100:103], v[144:147], v[168:171], v[100:103]
	v_mfma_f32_16x16x32_bf16 v[96:99], v[152:155], v[168:171], v[96:99]
	v_mfma_f32_16x16x32_bf16 v[84:87], v[144:147], v[176:179], v[84:87]
	v_mfma_f32_16x16x32_bf16 v[80:83], v[152:155], v[176:179], v[80:83]
	v_mfma_f32_16x16x32_bf16 v[68:71], v[144:147], v[190:193], v[68:71]
	v_mfma_f32_16x16x32_bf16 v[64:67], v[152:155], v[190:193], v[64:67]
	v_mfma_f32_16x16x32_bf16 v[124:127], v[148:151], v[164:167], v[124:127]
	v_mfma_f32_16x16x32_bf16 v[120:123], v[156:159], v[164:167], v[120:123]
	v_mfma_f32_16x16x32_bf16 v[100:103], v[148:151], v[172:175], v[100:103]
	v_mfma_f32_16x16x32_bf16 v[96:99], v[156:159], v[172:175], v[96:99]
	v_mfma_f32_16x16x32_bf16 v[84:87], v[148:151], v[180:183], v[84:87]
	v_mfma_f32_16x16x32_bf16 v[80:83], v[156:159], v[180:183], v[80:83]
	v_mfma_f32_16x16x32_bf16 v[68:71], v[148:151], v[194:197], v[68:71]
	v_mfma_f32_16x16x32_bf16 v[64:67], v[156:159], v[194:197], v[64:67]
	s_setprio 0
	s_barrier
	ds_read_b128 v[160:163], v232 offset:49152
	ds_read_b128 v[164:167], v232 offset:50176
	ds_read_b128 v[168:171], v232 offset:51200
	ds_read_b128 v[172:175], v232 offset:52224
	ds_read_b128 v[176:179], v232 offset:53248
	ds_read_b128 v[180:183], v232 offset:54272
	ds_read_b128 v[190:193], v232 offset:55296
	ds_read_b128 v[194:197], v232 offset:56320
	s_add_i32 s50, s63, s3
	s_add_u32 vcc_lo, s48, s40
	s_addc_u32 vcc_hi, s49, s41
	s_mov_b32 m0, s50
	s_nop 0
	global_load_lds_dwordx4 v223, vcc
	s_add_i32 m0, s50, 0x2000
	s_nop 0
	s_add_u32 vcc_lo, s48, s40
	s_addc_u32 vcc_hi, s49, s41
	s_add_u32 s48, s48, 0x160080
	s_addc_u32 s49, s49, 0
	s_add_i32 s50, s64, s3
	global_load_lds_dwordx4 v225, vcc
	s_mov_b32 m0, s50
	s_nop 0
	global_load_lds_dwordx4 v223, s[48:49]
	s_add_i32 m0, s50, 0x2000
	s_nop 0
	global_load_lds_dwordx4 v225, s[48:49]
	s_mov_b32 m0, s52
	s_nop 0
	global_load_lds_dwordx4 v222, s[46:47]
	v_mov_b32_e32 v184, v224
	s_mov_b32 m0, s53
	s_nop 0
	global_load_lds_dwordx4 v224, s[46:47]
	s_waitcnt vmcnt(8)
	s_waitcnt lgkmcnt(0)
	s_barrier
	s_setprio 1
	s_waitcnt lgkmcnt(0)
	v_mfma_f32_16x16x32_bf16 v[60:63], v[104:107], v[160:163], v[60:63]
	v_mfma_f32_16x16x32_bf16 v[56:59], v[128:131], v[160:163], v[56:59]
	v_mfma_f32_16x16x32_bf16 v[44:47], v[104:107], v[168:171], v[44:47]
	v_mfma_f32_16x16x32_bf16 v[40:43], v[128:131], v[168:171], v[40:43]
	v_mfma_f32_16x16x32_bf16 v[28:31], v[104:107], v[176:179], v[28:31]
	v_mfma_f32_16x16x32_bf16 v[24:27], v[128:131], v[176:179], v[24:27]
	v_mfma_f32_16x16x32_bf16 v[12:15], v[104:107], v[190:193], v[12:15]
	v_mfma_f32_16x16x32_bf16 v[8:11], v[128:131], v[190:193], v[8:11]
	v_mfma_f32_16x16x32_bf16 v[60:63], v[116:119], v[164:167], v[60:63]
	v_mfma_f32_16x16x32_bf16 v[56:59], v[140:143], v[164:167], v[56:59]
	v_mfma_f32_16x16x32_bf16 v[44:47], v[116:119], v[172:175], v[44:47]
	v_mfma_f32_16x16x32_bf16 v[40:43], v[140:143], v[172:175], v[40:43]
	v_mfma_f32_16x16x32_bf16 v[28:31], v[116:119], v[180:183], v[28:31]
	v_mfma_f32_16x16x32_bf16 v[24:27], v[140:143], v[180:183], v[24:27]
	v_mfma_f32_16x16x32_bf16 v[12:15], v[116:119], v[194:197], v[12:15]
	v_mfma_f32_16x16x32_bf16 v[8:11], v[140:143], v[194:197], v[8:11]
	s_setprio 0
	s_setprio 1
	v_mfma_f32_16x16x32_bf16 v[52:55], v[144:147], v[160:163], v[52:55]
	v_mfma_f32_16x16x32_bf16 v[48:51], v[152:155], v[160:163], v[48:51]
	v_mfma_f32_16x16x32_bf16 v[36:39], v[144:147], v[168:171], v[36:39]
	v_mfma_f32_16x16x32_bf16 v[32:35], v[152:155], v[168:171], v[32:35]
	v_mfma_f32_16x16x32_bf16 v[20:23], v[144:147], v[176:179], v[20:23]
	v_mfma_f32_16x16x32_bf16 v[16:19], v[152:155], v[176:179], v[16:19]
	v_mfma_f32_16x16x32_bf16 v[4:7], v[144:147], v[190:193], v[4:7]
	v_mfma_f32_16x16x32_bf16 v[0:3], v[152:155], v[190:193], v[0:3]
	v_mfma_f32_16x16x32_bf16 v[52:55], v[148:151], v[164:167], v[52:55]
	v_mfma_f32_16x16x32_bf16 v[48:51], v[156:159], v[164:167], v[48:51]
	v_mfma_f32_16x16x32_bf16 v[36:39], v[148:151], v[172:175], v[36:39]
	v_mfma_f32_16x16x32_bf16 v[32:35], v[156:159], v[172:175], v[32:35]
	v_mfma_f32_16x16x32_bf16 v[20:23], v[148:151], v[180:183], v[20:23]
	v_mfma_f32_16x16x32_bf16 v[16:19], v[156:159], v[180:183], v[16:19]
	v_mfma_f32_16x16x32_bf16 v[4:7], v[148:151], v[194:197], v[4:7]
	v_mfma_f32_16x16x32_bf16 v[0:3], v[156:159], v[194:197], v[0:3]
	s_setprio 0
	s_barrier
	s_add_i32 s62, s62, 2
	s_add_u32 s60, s60, 0x100
	s_addc_u32 s61, s61, 0
	s_add_u32 s44, s44, 0x10000
	s_addc_u32 s45, s45, 0
	s_cmpk_gt_u32 s62, 0x55
	s_cbranch_scc0 .LBB0_894
	s_and_b64 vcc, exec, s[36:37]
	s_cbranch_vccz .LBB0_897
	s_barrier

;     __device__ bool next(int i, Unit& u) const { const bool r = base.next(i >> 1, u); u.kh = i & 1; return r; }
; #define PG8_STAGE(bufoff, gbase, voff) do { _Pragma("unroll") for (int _i = 0; _i < 2; ++_i) \
;         { unsigned _vo = (voff)[_i]; asm volatile("" : "+v"(_vo));     \
;         __builtin_amdgcn_global_load_lds((const unsigned*)((const char*)(gbase) + _vo), (PG8_LAS unsigned*)(lds + (bufoff) + ldsw + _i * 8192), 16, 0, 0); } } while (0)
; #define PG8_LDA(dst, b, h) do { _Pragma("unroll") for (int m = 0; m < 4; ++m) _Pragma("unroll") for (int k = 0; k < 2; ++k) dst[m][k] = *(const PG8_LAS bf16x8*)(lds + PG8_SA(b, h) + aoff + m * 2048 + k * 1024); } while (0)
; #define PG8_WAIT_V(n) asm volatile("s_waitcnt vmcnt(" #n ")" ::: "memory")
; #define PG8_WAIT_L(n) asm volatile("s_waitcnt lgkmcnt(" #n ")" ::: "memory")
; template <class Epi, class Sched, bool ALIGN_EPI = false, bool SP2 = false, bool ABLK = false, bool F8 = false>
; __device__ __forceinline__ void gemm_phase(PG8_LAS unsigned char* lds, const Gemm g, const Sched& S, const Epi& E, const int wave_s) {
;     ...
;         const bool has_next = S.next(ui + 1, nxt); nxt.par = (ui + 1) & 1;
;         const char* nA = has_next ? (const char*)g.A + (size_t)nxt.pm * tstep + nxt.kh * khbA : cA; const char* nB = has_next ? (const char*)g.Bt + (size_t)nxt.pn * tstep + nxt.kh * khb : cB;
;         for (int t = 0; t < nt; t += 2) {
;             const bool last = (t == nt - 2);
;             const char* a1 = cA + (size_t)(t + 1) * kstepA;
;             const char* a2 = last ? nA : cA + (size_t)(t + 2) * kstepA; const char* b2 = last ? nB : cB + (size_t)(t + 2) * kstep;
;             const char* a3 = a2 + kstepA; const char* b3 = b2 + kstep;
;             if (last && has_next) { S.a_ready(nxt); if constexpr (Epi::PREF) E.prefetch(nxt, wid, lane); }
;             if constexpr (SP2) {
;             PG8_LDB(B0, 0, 0); PG8_LDB(B1, 0, 1); PG8_SCHED; PG8_LDA(At, 0, 0); PG8_STAGE(PG8_SA(1, 1), a1 + hstepA, voffA);
;             PG8_WAIT_V(8); PG8_WAIT_L(0); PG8_BAR; PG8_MMA(0, 0, At, B0); PG8_MMA(0, 1, At, B1); PG8_BAR; PG8_SCHED;
;             PG8_LDA(At, 0, 1); PG8_STAGE(PG8_SB(0, 0), b2, voffB); PG8_STAGE(PG8_SB(0, 1), b2 + hstep, voffB); PG8_STAGE(PG8_SA(0, 0), a2, voffA);
;             PG8_WAIT_V(8); PG8_WAIT_L(0); PG8_BAR; PG8_MMA(1, 0, At, B0); PG8_MMA(1, 1, At, B1); PG8_BAR; PG8_SCHED;
.LBB0_985:
	ds_read_b128 v[0:3], v141
	ds_read_b128 v[4:7], v141 offset:1024
	ds_read_b128 v[8:11], v141 offset:2048
	ds_read_b128 v[12:15], v141 offset:3072
	ds_read_b128 v[16:19], v142
	ds_read_b128 v[20:23], v142 offset:1024
	ds_read_b128 v[24:27], v142 offset:2048
	ds_read_b128 v[28:31], v142 offset:3072
	s_ashr_i32 s53, s52, 31
	s_lshl_b64 s[54:55], s[52:53], 17
	s_add_u32 s54, s21, s54
	s_addc_u32 s55, s22, s55
	s_and_b64 s[56:57], s[8:9], exec
	s_cselect_b32 s63, s55, s61
	s_cselect_b32 s62, s54, s60
	s_ashr_i32 s51, s50, 31
	s_lshl_b64 s[56:57], s[50:51], 17
	s_add_u32 s56, s18, s56
	s_addc_u32 s57, s19, s57
	s_and_b64 s[66:67], s[8:9], exec
	s_cselect_b32 s67, s57, s65
	s_cselect_b32 s66, s56, s64
	s_add_u32 s84, s60, 0x10080
	s_mov_b32 m0, s77
	ds_read_b128 v[32:35], v143
	ds_read_b128 v[36:39], v143 offset:1024
	ds_read_b128 v[40:43], v143 offset:2048
	ds_read_b128 v[44:47], v143 offset:3072
	ds_read_b128 v[48:51], v143 offset:4096
	ds_read_b128 v[52:55], v143 offset:5120
	ds_read_b128 v[56:59], v143 offset:6144
	ds_read_b128 v[60:63], v143 offset:7168
	s_addc_u32 s85, s61, 0
	s_nop 0
	global_load_lds_dwordx4 v134, s[84:85]
	s_mov_b32 m0, s78
	s_nop 0
	global_load_lds_dwordx4 v136, s[84:85]
	s_waitcnt vmcnt(8)
	s_waitcnt lgkmcnt(0)
	s_barrier
	s_setprio 1
	s_waitcnt lgkmcnt(0)
	v_mfma_f32_16x16x32_bf16 v[64:67], v[0:3], v[32:35], 0
	v_mfma_f32_16x16x32_bf16 v[68:71], v[8:11], v[32:35], 0
	v_mfma_f32_16x16x32_bf16 v[72:75], v[0:3], v[40:43], 0
	v_mfma_f32_16x16x32_bf16 v[76:79], v[8:11], v[40:43], 0
	v_mfma_f32_16x16x32_bf16 v[80:83], v[0:3], v[48:51], 0
	v_mfma_f32_16x16x32_bf16 v[84:87], v[8:11], v[48:51], 0
	v_mfma_f32_16x16x32_bf16 v[88:91], v[0:3], v[56:59], 0
	v_mfma_f32_16x16x32_bf16 v[92:95], v[8:11], v[56:59], 0
	v_mfma_f32_16x16x32_bf16 v[64:67], v[4:7], v[36:39], v[64:67]
	v_mfma_f32_16x16x32_bf16 v[68:71], v[12:15], v[36:39], v[68:71]
	v_mfma_f32_16x16x32_bf16 v[72:75], v[4:7], v[44:47], v[72:75]
	v_mfma_f32_16x16x32_bf16 v[76:79], v[12:15], v[44:47], v[76:79]
	v_mfma_f32_16x16x32_bf16 v[80:83], v[4:7], v[52:55], v[80:83]
	v_mfma_f32_16x16x32_bf16 v[84:87], v[12:15], v[52:55], v[84:87]
	v_mfma_f32_16x16x32_bf16 v[88:91], v[4:7], v[60:63], v[88:91]
	v_mfma_f32_16x16x32_bf16 v[92:95], v[12:15], v[60:63], v[92:95]
	s_setprio 0
	s_setprio 1
	v_mfma_f32_16x16x32_bf16 v[96:99], v[16:19], v[32:35], 0
	v_mfma_f32_16x16x32_bf16 v[32:35], v[24:27], v[32:35], 0
	v_mfma_f32_16x16x32_bf16 v[96:99], v[20:23], v[36:39], v[96:99]
	v_mfma_f32_16x16x32_bf16 v[32:35], v[28:31], v[36:39], v[32:35]
	v_mfma_f32_16x16x32_bf16 v[36:39], v[16:19], v[40:43], 0
	v_mfma_f32_16x16x32_bf16 v[40:43], v[24:27], v[40:43], 0
	v_mfma_f32_16x16x32_bf16 v[36:39], v[20:23], v[44:47], v[36:39]
	v_mfma_f32_16x16x32_bf16 v[40:43], v[28:31], v[44:47], v[40:43]
	v_mfma_f32_16x16x32_bf16 v[44:47], v[16:19], v[48:51], 0
	v_mfma_f32_16x16x32_bf16 v[48:51], v[24:27], v[48:51], 0
	v_mfma_f32_16x16x32_bf16 v[44:47], v[20:23], v[52:55], v[44:47]
	v_mfma_f32_16x16x32_bf16 v[48:51], v[28:31], v[52:55], v[48:51]
	v_mfma_f32_16x16x32_bf16 v[52:55], v[16:19], v[56:59], 0
	v_mfma_f32_16x16x32_bf16 v[56:59], v[24:27], v[56:59], 0
	v_mfma_f32_16x16x32_bf16 v[52:55], v[20:23], v[60:63], v[52:55]
	v_mfma_f32_16x16x32_bf16 v[56:59], v[28:31], v[60:63], v[56:59]
	s_setprio 0
	s_barrier
	v_mov_b32_e32 v128, v135
	ds_read_b128 v[60:63], v143 offset:16384
	ds_read_b128 v[100:103], v143 offset:17408
	ds_read_b128 v[104:107], v143 offset:18432
	ds_read_b128 v[108:111], v143 offset:19456
	ds_read_b128 v[112:115], v143 offset:20480
	ds_read_b128 v[116:119], v143 offset:21504
	ds_read_b128 v[120:123], v143 offset:22528
	ds_read_b128 v[124:127], v143 offset:23552
	s_add_i32 s85, s75, s3
	v_lshl_add_u64 v[144:145], s[64:65], 0, v[128:129]
	v_lshl_add_u64 v[144:145], v[144:145], 0, s[40:41]
	s_mov_b32 m0, s85
	v_mov_b32_e32 v128, v137
	s_add_i32 s51, s85, 0x2000
	global_load_lds_dwordx4 v[144:145], off
	s_add_u32 s86, s64, 0x10100
	v_lshl_add_u64 v[144:145], s[64:65], 0, v[128:129]
	v_lshl_add_u64 v[144:145], v[144:145], 0, s[40:41]
	s_mov_b32 m0, s51
	s_addc_u32 s87, s65, 0
	s_add_i32 s53, s76, s3
	global_load_lds_dwordx4 v[144:145], off
	s_mov_b32 m0, s53
	s_add_i32 s84, s53, 0x2000
	global_load_lds_dwordx4 v135, s[86:87]
	s_mov_b32 m0, s84
	s_nop 0
	global_load_lds_dwordx4 v137, s[86:87]
	v_mov_b32_e32 v128, v134
	s_mov_b32 m0, s23
	v_lshl_add_u64 v[144:145], s[60:61], 0, v[128:129]
	v_lshl_add_u64 v[144:145], v[144:145], 0, s[40:41]
	v_mov_b32_e32 v128, v136
	global_load_lds_dwordx4 v[144:145], off
	s_mov_b32 m0, s33
	v_lshl_add_u64 v[144:145], s[60:61], 0, v[128:129]
	v_lshl_add_u64 v[144:145], v[144:145], 0, s[40:41]
	global_load_lds_dwordx4 v[144:145], off
	s_waitcnt vmcnt(8)
	s_waitcnt lgkmcnt(0)
	s_barrier
; #define PG8_STAGE(bufoff, gbase, voff) do { _Pragma("unroll") for (int _i = 0; _i < 2; ++_i) \
;         { unsigned _vo = (voff)[_i]; asm volatile("" : "+v"(_vo));     \
;         __builtin_amdgcn_global_load_lds((const unsigned*)((const char*)(gbase) + _vo), (PG8_LAS unsigned*)(lds + (bufoff) + ldsw + _i * 8192), 16, 0, 0); } } while (0)
; #define PG8_LDA(dst, b, h) do { _Pragma("unroll") for (int m = 0; m < 4; ++m) _Pragma("unroll") for (int k = 0; k < 2; ++k) dst[m][k] = *(const PG8_LAS bf16x8*)(lds + PG8_SA(b, h) + aoff + m * 2048 + k * 1024); } while (0)
; #define PG8_LDB(dst, b, h) do { _Pragma("unroll") for (int n = 0; n < 2; ++n) _Pragma("unroll") for (int k = 0; k < 2; ++k) dst[n][k] = *(const PG8_LAS bf16x8*)(lds + PG8_SB(b, h) + boff + n * 2048 + k * 1024); } while (0)
; #define PG8_WAIT_V(n) asm volatile("s_waitcnt vmcnt(" #n ")" ::: "memory")
; #define PG8_WAIT_L(n) asm volatile("s_waitcnt lgkmcnt(" #n ")" ::: "memory")
; #define PG8_BAR __builtin_amdgcn_s_barrier()
; #define PG8_SCHED __builtin_amdgcn_sched_barrier(0)
; template <class Epi, class Sched, bool ALIGN_EPI = false, bool SP2 = false, bool ABLK = false, bool F8 = false>
; __device__ __forceinline__ void gemm_phase(PG8_LAS unsigned char* lds, const Gemm g, const Sched& S, const Epi& E, const int wave_s) {
;     ...
;             PG8_WAIT_V(8); PG8_WAIT_L(0); PG8_BAR; PG8_MMA(0, 0, At, B0); PG8_MMA(0, 1, At, B1); PG8_BAR; PG8_SCHED;
;             PG8_LDA(At, 0, 1); PG8_STAGE(PG8_SB(0, 0), b2, voffB); PG8_STAGE(PG8_SB(0, 1), b2 + hstep, voffB); PG8_STAGE(PG8_SA(0, 0), a2, voffA);
;             PG8_WAIT_V(8); PG8_WAIT_L(0); PG8_BAR; PG8_MMA(1, 0, At, B0); PG8_MMA(1, 1, At, B1); PG8_BAR; PG8_SCHED;
;             PG8_LDB(B0, 1, 0); PG8_LDB(B1, 1, 1); PG8_SCHED; PG8_LDA(At, 1, 0); PG8_STAGE(PG8_SA(0, 1), a2 + hstepA, voffA);
;             PG8_WAIT_V(8); PG8_WAIT_L(0); PG8_BAR; PG8_MMA(0, 0, At, B0); PG8_MMA(0, 1, At, B1); PG8_BAR; PG8_SCHED;
	s_setprio 1
	s_waitcnt lgkmcnt(0)
	v_mfma_f32_16x16x32_bf16 v[144:147], v[0:3], v[60:63], 0
	v_mfma_f32_16x16x32_bf16 v[152:155], v[0:3], v[104:107], 0
	v_mfma_f32_16x16x32_bf16 v[160:163], v[0:3], v[112:115], 0
	v_mfma_f32_16x16x32_bf16 v[0:3], v[0:3], v[120:123], 0
	v_mfma_f32_16x16x32_bf16 v[144:147], v[4:7], v[100:103], v[144:147]
	v_mfma_f32_16x16x32_bf16 v[152:155], v[4:7], v[108:111], v[152:155]
	v_mfma_f32_16x16x32_bf16 v[160:163], v[4:7], v[116:119], v[160:163]
	v_mfma_f32_16x16x32_bf16 v[0:3], v[4:7], v[124:127], v[0:3]
	v_mfma_f32_16x16x32_bf16 v[4:7], v[8:11], v[120:123], 0
	v_mfma_f32_16x16x32_bf16 v[148:151], v[8:11], v[60:63], 0
	v_mfma_f32_16x16x32_bf16 v[156:159], v[8:11], v[104:107], 0
	v_mfma_f32_16x16x32_bf16 v[164:167], v[8:11], v[112:115], 0
	v_mfma_f32_16x16x32_bf16 v[4:7], v[12:15], v[124:127], v[4:7]
	v_mfma_f32_16x16x32_bf16 v[148:151], v[12:15], v[100:103], v[148:151]
	v_mfma_f32_16x16x32_bf16 v[156:159], v[12:15], v[108:111], v[156:159]
	v_mfma_f32_16x16x32_bf16 v[164:167], v[12:15], v[116:119], v[164:167]
	s_setprio 0
	s_setprio 1
	v_mfma_f32_16x16x32_bf16 v[8:11], v[16:19], v[60:63], 0
	v_mfma_f32_16x16x32_bf16 v[12:15], v[24:27], v[60:63], 0
	v_mfma_f32_16x16x32_bf16 v[8:11], v[20:23], v[100:103], v[8:11]
	v_mfma_f32_16x16x32_bf16 v[12:15], v[28:31], v[100:103], v[12:15]
	v_mfma_f32_16x16x32_bf16 v[60:63], v[16:19], v[104:107], 0
	v_mfma_f32_16x16x32_bf16 v[100:103], v[24:27], v[104:107], 0
	v_mfma_f32_16x16x32_bf16 v[104:107], v[16:19], v[112:115], 0
	v_mfma_f32_16x16x32_bf16 v[16:19], v[16:19], v[120:123], 0
	v_mfma_f32_16x16x32_bf16 v[60:63], v[20:23], v[108:111], v[60:63]
	v_mfma_f32_16x16x32_bf16 v[100:103], v[28:31], v[108:111], v[100:103]
	v_mfma_f32_16x16x32_bf16 v[104:107], v[20:23], v[116:119], v[104:107]
	v_mfma_f32_16x16x32_bf16 v[108:111], v[24:27], v[112:115], 0
	v_mfma_f32_16x16x32_bf16 v[16:19], v[20:23], v[124:127], v[16:19]
	v_mfma_f32_16x16x32_bf16 v[20:23], v[24:27], v[120:123], 0
	v_mfma_f32_16x16x32_bf16 v[108:111], v[28:31], v[116:119], v[108:111]
	v_mfma_f32_16x16x32_bf16 v[20:23], v[28:31], v[124:127], v[20:23]
	s_setprio 0
	s_barrier
	s_add_i32 s88, 0, 0x18000
	s_add_i32 s95, 0, 0x1c000
	v_add_u32_e32 v212, s88, v139
	v_add_u32_e32 v220, s95, v139
	ds_read_b128 v[24:27], v212
	ds_read_b128 v[28:31], v212 offset:1024
	ds_read_b128 v[112:115], v212 offset:2048
	ds_read_b128 v[116:119], v212 offset:3072
	ds_read_b128 v[120:123], v220
	ds_read_b128 v[124:127], v220 offset:1024
	ds_read_b128 v[168:171], v220 offset:2048
	ds_read_b128 v[172:175], v220 offset:3072
	s_add_u32 s86, s60, 0x10100
	s_mov_b32 m0, s59
	ds_read_b128 v[176:179], v143 offset:32768
	ds_read_b128 v[180:183], v143 offset:33792
	ds_read_b128 v[184:187], v143 offset:34816
	ds_read_b128 v[188:191], v143 offset:35840
	ds_read_b128 v[192:195], v143 offset:36864
	ds_read_b128 v[196:199], v143 offset:37888
	ds_read_b128 v[200:203], v143 offset:38912
	ds_read_b128 v[204:207], v143 offset:39936
	s_addc_u32 s87, s61, 0
	s_nop 0
	global_load_lds_dwordx4 v134, s[86:87]
	s_mov_b32 m0, s72
	s_nop 0
	global_load_lds_dwordx4 v136, s[86:87]
	s_waitcnt vmcnt(8)
	s_waitcnt lgkmcnt(0)
	s_barrier
	s_setprio 1
	s_waitcnt lgkmcnt(0)
	v_mfma_f32_16x16x32_bf16 v[64:67], v[24:27], v[176:179], v[64:67]
	v_mfma_f32_16x16x32_bf16 v[68:71], v[112:115], v[176:179], v[68:71]
	v_mfma_f32_16x16x32_bf16 v[72:75], v[24:27], v[184:187], v[72:75]
	v_mfma_f32_16x16x32_bf16 v[76:79], v[112:115], v[184:187], v[76:79]
	v_mfma_f32_16x16x32_bf16 v[80:83], v[24:27], v[192:195], v[80:83]
	v_mfma_f32_16x16x32_bf16 v[84:87], v[112:115], v[192:195], v[84:87]
	v_mfma_f32_16x16x32_bf16 v[88:91], v[24:27], v[200:203], v[88:91]
	v_mfma_f32_16x16x32_bf16 v[92:95], v[112:115], v[200:203], v[92:95]
	v_mfma_f32_16x16x32_bf16 v[64:67], v[28:31], v[180:183], v[64:67]
	v_mfma_f32_16x16x32_bf16 v[68:71], v[116:119], v[180:183], v[68:71]
	v_mfma_f32_16x16x32_bf16 v[72:75], v[28:31], v[188:191], v[72:75]
	v_mfma_f32_16x16x32_bf16 v[76:79], v[116:119], v[188:191], v[76:79]
	v_mfma_f32_16x16x32_bf16 v[80:83], v[28:31], v[196:199], v[80:83]
	v_mfma_f32_16x16x32_bf16 v[84:87], v[116:119], v[196:199], v[84:87]
	v_mfma_f32_16x16x32_bf16 v[88:91], v[28:31], v[204:207], v[88:91]
	v_mfma_f32_16x16x32_bf16 v[92:95], v[116:119], v[204:207], v[92:95]
	s_setprio 0
	s_setprio 1
	v_mfma_f32_16x16x32_bf16 v[96:99], v[120:123], v[176:179], v[96:99]
	v_mfma_f32_16x16x32_bf16 v[32:35], v[168:171], v[176:179], v[32:35]
	v_mfma_f32_16x16x32_bf16 v[36:39], v[120:123], v[184:187], v[36:39]
	v_mfma_f32_16x16x32_bf16 v[40:43], v[168:171], v[184:187], v[40:43]
	v_mfma_f32_16x16x32_bf16 v[44:47], v[120:123], v[192:195], v[44:47]
	v_mfma_f32_16x16x32_bf16 v[48:51], v[168:171], v[192:195], v[48:51]
	v_mfma_f32_16x16x32_bf16 v[52:55], v[120:123], v[200:203], v[52:55]
	v_mfma_f32_16x16x32_bf16 v[56:59], v[168:171], v[200:203], v[56:59]
	v_mfma_f32_16x16x32_bf16 v[96:99], v[124:127], v[180:183], v[96:99]
	v_mfma_f32_16x16x32_bf16 v[32:35], v[172:175], v[180:183], v[32:35]
	v_mfma_f32_16x16x32_bf16 v[36:39], v[124:127], v[188:191], v[36:39]
	v_mfma_f32_16x16x32_bf16 v[40:43], v[172:175], v[188:191], v[40:43]
	v_mfma_f32_16x16x32_bf16 v[44:47], v[124:127], v[196:199], v[44:47]
	v_mfma_f32_16x16x32_bf16 v[48:51], v[172:175], v[196:199], v[48:51]
	v_mfma_f32_16x16x32_bf16 v[52:55], v[124:127], v[204:207], v[52:55]
	v_mfma_f32_16x16x32_bf16 v[56:59], v[172:175], v[204:207], v[56:59]
	s_setprio 0
	s_barrier
; #define PG8_STAGE(bufoff, gbase, voff) do { _Pragma("unroll") for (int _i = 0; _i < 2; ++_i) \
;         { unsigned _vo = (voff)[_i]; asm volatile("" : "+v"(_vo));     \
;         __builtin_amdgcn_global_load_lds((const unsigned*)((const char*)(gbase) + _vo), (PG8_LAS unsigned*)(lds + (bufoff) + ldsw + _i * 8192), 16, 0, 0); } } while (0)
; #define PG8_LDA(dst, b, h) do { _Pragma("unroll") for (int m = 0; m < 4; ++m) _Pragma("unroll") for (int k = 0; k < 2; ++k) dst[m][k] = *(const PG8_LAS bf16x8*)(lds + PG8_SA(b, h) + aoff + m * 2048 + k * 1024); } while (0)
; #define PG8_LDB(dst, b, h) do { _Pragma("unroll") for (int n = 0; n < 2; ++n) _Pragma("unroll") for (int k = 0; k < 2; ++k) dst[n][k] = *(const PG8_LAS bf16x8*)(lds + PG8_SB(b, h) + boff + n * 2048 + k * 1024); } while (0)
; #define PG8_WAIT_V(n) asm volatile("s_waitcnt vmcnt(" #n ")" ::: "memory")
; #define PG8_WAIT_L(n) asm volatile("s_waitcnt lgkmcnt(" #n ")" ::: "memory")
; #define PG8_BAR __builtin_amdgcn_s_barrier()
; #define PG8_SCHED __builtin_amdgcn_sched_barrier(0)
; template <class Epi, class Sched, bool ALIGN_EPI = false, bool SP2 = false, bool ABLK = false, bool F8 = false>
; __device__ __forceinline__ void gemm_phase(PG8_LAS unsigned char* lds, const Gemm g, const Sched& S, const Epi& E, const int wave_s) {
;     ...
;             PG8_LDB(B0, 0, 0); PG8_LDB(B1, 0, 1); PG8_SCHED; PG8_LDA(At, 0, 0); PG8_STAGE(PG8_SA(1, 1), a1 + hstepA, voffA);
;             PG8_WAIT_V(8); PG8_WAIT_L(0); PG8_BAR; PG8_MMA(0, 0, At, B0); PG8_MMA(0, 1, At, B1); PG8_BAR; PG8_SCHED;
;             PG8_LDA(At, 0, 1); PG8_STAGE(PG8_SB(0, 0), b2, voffB); PG8_STAGE(PG8_SB(0, 1), b2 + hstep, voffB); PG8_STAGE(PG8_SA(0, 0), a2, voffA);
;             PG8_WAIT_V(8); PG8_WAIT_L(0); PG8_BAR; PG8_MMA(1, 0, At, B0); PG8_MMA(1, 1, At, B1); PG8_BAR; PG8_SCHED;
;             PG8_LDB(B0, 1, 0); PG8_LDB(B1, 1, 1); PG8_SCHED; PG8_LDA(At, 1, 0); PG8_STAGE(PG8_SA(0, 1), a2 + hstepA, voffA);
;             PG8_WAIT_V(8); PG8_WAIT_L(0); PG8_BAR; PG8_MMA(0, 0, At, B0); PG8_MMA(0, 1, At, B1); PG8_BAR; PG8_SCHED;
;             PG8_LDA(At, 1, 1); PG8_STAGE(PG8_SB(1, 0), b3, voffB); PG8_STAGE(PG8_SB(1, 1), b3 + hstep, voffB); PG8_STAGE(PG8_SA(1, 0), a3, voffA);
;             PG8_WAIT_V(8); PG8_WAIT_L(0); PG8_BAR; PG8_MMA(1, 0, At, B0); PG8_MMA(1, 1, At, B1); PG8_BAR; PG8_SCHED;
	v_mov_b32_e32 v128, v135
	ds_read_b128 v[176:179], v143 offset:49152
	ds_read_b128 v[180:183], v143 offset:50176
	ds_read_b128 v[184:187], v143 offset:51200
	ds_read_b128 v[188:191], v143 offset:52224
	ds_read_b128 v[192:195], v143 offset:53248
	ds_read_b128 v[196:199], v143 offset:54272
	ds_read_b128 v[200:203], v143 offset:55296
	ds_read_b128 v[204:207], v143 offset:56320
	s_add_i32 s87, s88, s3
	v_lshl_add_u64 v[208:209], s[64:65], 0, v[128:129]
	v_lshl_add_u64 v[208:209], v[208:209], 0, s[42:43]
	s_mov_b32 m0, s87
	v_mov_b32_e32 v128, v137
	s_add_i32 s86, s87, 0x2000
	global_load_lds_dwordx4 v[208:209], off
	s_add_u32 s88, s64, 0x10180
	v_lshl_add_u64 v[208:209], s[64:65], 0, v[128:129]
	v_lshl_add_u64 v[208:209], v[208:209], 0, s[42:43]
	s_mov_b32 m0, s86
	s_addc_u32 s89, s65, 0
	s_add_i32 s64, s95, s3
	global_load_lds_dwordx4 v[208:209], off
	s_mov_b32 m0, s64
	s_add_i32 s65, s64, 0x2000
	global_load_lds_dwordx4 v135, s[88:89]
	s_mov_b32 m0, s65
	s_nop 0
	global_load_lds_dwordx4 v137, s[88:89]
	v_mov_b32_e32 v128, v134
	s_mov_b32 m0, s73
	v_lshl_add_u64 v[208:209], s[60:61], 0, v[128:129]
	v_lshl_add_u64 v[208:209], v[208:209], 0, s[42:43]
	v_mov_b32_e32 v128, v136
	global_load_lds_dwordx4 v[208:209], off
	s_mov_b32 m0, s74
	v_lshl_add_u64 v[208:209], s[60:61], 0, v[128:129]
	v_lshl_add_u64 v[208:209], v[208:209], 0, s[42:43]
	global_load_lds_dwordx4 v[208:209], off
	s_waitcnt vmcnt(8)
	s_waitcnt lgkmcnt(0)
	s_barrier
	s_setprio 1
	s_waitcnt lgkmcnt(0)
	v_mfma_f32_16x16x32_bf16 v[0:3], v[24:27], v[200:203], v[0:3]
	v_mfma_f32_16x16x32_bf16 v[4:7], v[112:115], v[200:203], v[4:7]
	v_mfma_f32_16x16x32_bf16 v[144:147], v[24:27], v[176:179], v[144:147]
	v_mfma_f32_16x16x32_bf16 v[148:151], v[112:115], v[176:179], v[148:151]
	v_mfma_f32_16x16x32_bf16 v[152:155], v[24:27], v[184:187], v[152:155]
	v_mfma_f32_16x16x32_bf16 v[156:159], v[112:115], v[184:187], v[156:159]
	v_mfma_f32_16x16x32_bf16 v[160:163], v[24:27], v[192:195], v[160:163]
	v_mfma_f32_16x16x32_bf16 v[164:167], v[112:115], v[192:195], v[164:167]
	v_mfma_f32_16x16x32_bf16 v[0:3], v[28:31], v[204:207], v[0:3]
	v_mfma_f32_16x16x32_bf16 v[4:7], v[116:119], v[204:207], v[4:7]
	v_mfma_f32_16x16x32_bf16 v[144:147], v[28:31], v[180:183], v[144:147]
	v_mfma_f32_16x16x32_bf16 v[148:151], v[116:119], v[180:183], v[148:151]
	v_mfma_f32_16x16x32_bf16 v[152:155], v[28:31], v[188:191], v[152:155]
	v_mfma_f32_16x16x32_bf16 v[156:159], v[116:119], v[188:191], v[156:159]
	v_mfma_f32_16x16x32_bf16 v[160:163], v[28:31], v[196:199], v[160:163]
	v_mfma_f32_16x16x32_bf16 v[164:167], v[116:119], v[196:199], v[164:167]
	s_setprio 0
	s_setprio 1
	v_mfma_f32_16x16x32_bf16 v[8:11], v[120:123], v[176:179], v[8:11]
	v_mfma_f32_16x16x32_bf16 v[12:15], v[168:171], v[176:179], v[12:15]
	v_mfma_f32_16x16x32_bf16 v[24:27], v[120:123], v[184:187], v[60:63]
	v_mfma_f32_16x16x32_bf16 v[28:31], v[168:171], v[184:187], v[100:103]
	v_mfma_f32_16x16x32_bf16 v[60:63], v[120:123], v[192:195], v[104:107]
	v_mfma_f32_16x16x32_bf16 v[100:103], v[168:171], v[192:195], v[108:111]
	v_mfma_f32_16x16x32_bf16 v[16:19], v[120:123], v[200:203], v[16:19]
	v_mfma_f32_16x16x32_bf16 v[20:23], v[168:171], v[200:203], v[20:23]
	v_mfma_f32_16x16x32_bf16 v[8:11], v[124:127], v[180:183], v[8:11]
	v_mfma_f32_16x16x32_bf16 v[12:15], v[172:175], v[180:183], v[12:15]
	v_mfma_f32_16x16x32_bf16 v[24:27], v[124:127], v[188:191], v[24:27]
	v_mfma_f32_16x16x32_bf16 v[28:31], v[172:175], v[188:191], v[28:31]
	v_mfma_f32_16x16x32_bf16 v[60:63], v[124:127], v[196:199], v[60:63]
	v_mfma_f32_16x16x32_bf16 v[100:103], v[172:175], v[196:199], v[100:103]
	v_mfma_f32_16x16x32_bf16 v[16:19], v[124:127], v[204:207], v[16:19]
	v_mfma_f32_16x16x32_bf16 v[20:23], v[172:175], v[204:207], v[20:23]
	s_setprio 0
	s_barrier
	ds_read_b128 v[104:107], v141
	ds_read_b128 v[108:111], v141 offset:1024
	ds_read_b128 v[112:115], v141 offset:2048
	ds_read_b128 v[116:119], v141 offset:3072
	ds_read_b128 v[120:123], v142
	ds_read_b128 v[124:127], v142 offset:1024
	ds_read_b128 v[168:171], v142 offset:2048
	ds_read_b128 v[172:175], v142 offset:3072
	s_add_u32 s60, s60, 0x10180
	s_mov_b32 m0, s77
	ds_read_b128 v[176:179], v143
	ds_read_b128 v[180:183], v143 offset:1024
	ds_read_b128 v[184:187], v143 offset:2048
	ds_read_b128 v[188:191], v143 offset:3072
	ds_read_b128 v[192:195], v143 offset:4096
	ds_read_b128 v[196:199], v143 offset:5120
	ds_read_b128 v[200:203], v143 offset:6144
	ds_read_b128 v[204:207], v143 offset:7168
	s_addc_u32 s61, s61, 0
	s_nop 0
	global_load_lds_dwordx4 v134, s[60:61]
	s_mov_b32 m0, s78
	s_nop 0
	global_load_lds_dwordx4 v136, s[60:61]
	s_waitcnt vmcnt(8)
	s_waitcnt lgkmcnt(0)
	s_barrier
; #define PG8_STAGE(bufoff, gbase, voff) do { _Pragma("unroll") for (int _i = 0; _i < 2; ++_i) \
;         { unsigned _vo = (voff)[_i]; asm volatile("" : "+v"(_vo));     \
;         __builtin_amdgcn_global_load_lds((const unsigned*)((const char*)(gbase) + _vo), (PG8_LAS unsigned*)(lds + (bufoff) + ldsw + _i * 8192), 16, 0, 0); } } while (0)
; #define PG8_LDA(dst, b, h) do { _Pragma("unroll") for (int m = 0; m < 4; ++m) _Pragma("unroll") for (int k = 0; k < 2; ++k) dst[m][k] = *(const PG8_LAS bf16x8*)(lds + PG8_SA(b, h) + aoff + m * 2048 + k * 1024); } while (0)
; #define PG8_WAIT_V(n) asm volatile("s_waitcnt vmcnt(" #n ")" ::: "memory")
; #define PG8_WAIT_L(n) asm volatile("s_waitcnt lgkmcnt(" #n ")" ::: "memory")
; #define PG8_BAR __builtin_amdgcn_s_barrier()
; #define PG8_SCHED __builtin_amdgcn_sched_barrier(0)
; template <class Epi, class Sched, bool ALIGN_EPI = false, bool SP2 = false, bool ABLK = false, bool F8 = false>
; __device__ __forceinline__ void gemm_phase(PG8_LAS unsigned char* lds, const Gemm g, const Sched& S, const Epi& E, const int wave_s) {
;     ...
;             PG8_WAIT_V(8); PG8_WAIT_L(0); PG8_BAR; PG8_MMA(0, 0, At, B0); PG8_MMA(0, 1, At, B1); PG8_BAR; PG8_SCHED;
;             PG8_LDA(At, 0, 1); PG8_STAGE(PG8_SB(0, 0), b2, voffB); PG8_STAGE(PG8_SB(0, 1), b2 + hstep, voffB); PG8_STAGE(PG8_SA(0, 0), a2, voffA);
;             PG8_WAIT_V(8); PG8_WAIT_L(0); PG8_BAR; PG8_MMA(1, 0, At, B0); PG8_MMA(1, 1, At, B1); PG8_BAR; PG8_SCHED;
	s_setprio 1
	s_waitcnt lgkmcnt(0)
	v_mfma_f32_16x16x32_bf16 v[64:67], v[104:107], v[176:179], v[64:67]
	v_mfma_f32_16x16x32_bf16 v[68:71], v[112:115], v[176:179], v[68:71]
	v_mfma_f32_16x16x32_bf16 v[72:75], v[104:107], v[184:187], v[72:75]
	v_mfma_f32_16x16x32_bf16 v[76:79], v[112:115], v[184:187], v[76:79]
	v_mfma_f32_16x16x32_bf16 v[80:83], v[104:107], v[192:195], v[80:83]
	v_mfma_f32_16x16x32_bf16 v[84:87], v[112:115], v[192:195], v[84:87]
	v_mfma_f32_16x16x32_bf16 v[88:91], v[104:107], v[200:203], v[88:91]
	v_mfma_f32_16x16x32_bf16 v[92:95], v[112:115], v[200:203], v[92:95]
	v_mfma_f32_16x16x32_bf16 v[64:67], v[108:111], v[180:183], v[64:67]
	v_mfma_f32_16x16x32_bf16 v[68:71], v[116:119], v[180:183], v[68:71]
	v_mfma_f32_16x16x32_bf16 v[72:75], v[108:111], v[188:191], v[72:75]
	v_mfma_f32_16x16x32_bf16 v[76:79], v[116:119], v[188:191], v[76:79]
	v_mfma_f32_16x16x32_bf16 v[80:83], v[108:111], v[196:199], v[80:83]
	v_mfma_f32_16x16x32_bf16 v[84:87], v[116:119], v[196:199], v[84:87]
	v_mfma_f32_16x16x32_bf16 v[88:91], v[108:111], v[204:207], v[88:91]
	v_mfma_f32_16x16x32_bf16 v[92:95], v[116:119], v[204:207], v[92:95]
	s_setprio 0
	s_setprio 1
	v_mfma_f32_16x16x32_bf16 v[36:39], v[120:123], v[184:187], v[36:39]
	v_mfma_f32_16x16x32_bf16 v[96:99], v[120:123], v[176:179], v[96:99]
	v_mfma_f32_16x16x32_bf16 v[32:35], v[168:171], v[176:179], v[32:35]
	v_mfma_f32_16x16x32_bf16 v[176:179], v[124:127], v[188:191], v[36:39]
	v_mfma_f32_16x16x32_bf16 v[36:39], v[168:171], v[184:187], v[40:43]
	v_mfma_f32_16x16x32_bf16 v[40:43], v[172:175], v[188:191], v[36:39]
	v_mfma_f32_16x16x32_bf16 v[36:39], v[120:123], v[192:195], v[44:47]
	v_mfma_f32_16x16x32_bf16 v[96:99], v[124:127], v[180:183], v[96:99]
	v_mfma_f32_16x16x32_bf16 v[32:35], v[172:175], v[180:183], v[32:35]
	v_mfma_f32_16x16x32_bf16 v[180:183], v[124:127], v[196:199], v[36:39]
	v_mfma_f32_16x16x32_bf16 v[36:39], v[168:171], v[192:195], v[48:51]
	v_mfma_f32_16x16x32_bf16 v[48:51], v[172:175], v[196:199], v[36:39]
	v_mfma_f32_16x16x32_bf16 v[36:39], v[120:123], v[200:203], v[52:55]
	v_mfma_f32_16x16x32_bf16 v[52:55], v[124:127], v[204:207], v[36:39]
	v_mfma_f32_16x16x32_bf16 v[36:39], v[168:171], v[200:203], v[56:59]
	v_mfma_f32_16x16x32_bf16 v[56:59], v[172:175], v[204:207], v[36:39]
	s_setprio 0
	s_barrier
	s_mov_b32 m0, s85
	s_nop 2
	ds_read_b128 v[36:39], v143 offset:16384
	ds_read_b128 v[44:47], v143 offset:17408
	ds_read_b128 v[184:187], v143 offset:18432
	ds_read_b128 v[188:191], v143 offset:19456
	ds_read_b128 v[192:195], v143 offset:20480
	ds_read_b128 v[196:199], v143 offset:21504
	ds_read_b128 v[200:203], v143 offset:22528
	ds_read_b128 v[204:207], v143 offset:23552
	s_add_u32 s60, s66, 0x10000
	global_load_lds_dwordx4 v135, s[66:67]
	s_mov_b32 m0, s51
	s_addc_u32 s61, s67, 0
	global_load_lds_dwordx4 v137, s[66:67]
	s_mov_b32 m0, s53
	s_nop 0
	global_load_lds_dwordx4 v135, s[60:61]
	s_mov_b32 m0, s84
	s_nop 0
	global_load_lds_dwordx4 v137, s[60:61]
	s_mov_b32 m0, s23
	s_nop 0
	global_load_lds_dwordx4 v134, s[62:63]
	s_mov_b32 m0, s33
	s_nop 0
	global_load_lds_dwordx4 v136, s[62:63]
	s_waitcnt vmcnt(8)
	s_waitcnt lgkmcnt(0)
	s_barrier
	s_setprio 1
	s_waitcnt lgkmcnt(0)
	v_mfma_f32_16x16x32_bf16 v[0:3], v[104:107], v[200:203], v[0:3]
	v_mfma_f32_16x16x32_bf16 v[4:7], v[112:115], v[200:203], v[4:7]
	v_mfma_f32_16x16x32_bf16 v[144:147], v[104:107], v[36:39], v[144:147]
	v_mfma_f32_16x16x32_bf16 v[148:151], v[112:115], v[36:39], v[148:151]
	v_mfma_f32_16x16x32_bf16 v[152:155], v[104:107], v[184:187], v[152:155]
	v_mfma_f32_16x16x32_bf16 v[156:159], v[112:115], v[184:187], v[156:159]
	v_mfma_f32_16x16x32_bf16 v[160:163], v[104:107], v[192:195], v[160:163]
	v_mfma_f32_16x16x32_bf16 v[164:167], v[112:115], v[192:195], v[164:167]
	v_mfma_f32_16x16x32_bf16 v[0:3], v[108:111], v[204:207], v[0:3]
	v_mfma_f32_16x16x32_bf16 v[4:7], v[116:119], v[204:207], v[4:7]
	v_mfma_f32_16x16x32_bf16 v[144:147], v[108:111], v[44:47], v[144:147]
	v_mfma_f32_16x16x32_bf16 v[148:151], v[116:119], v[44:47], v[148:151]
	v_mfma_f32_16x16x32_bf16 v[152:155], v[108:111], v[188:191], v[152:155]
	v_mfma_f32_16x16x32_bf16 v[156:159], v[116:119], v[188:191], v[156:159]
	v_mfma_f32_16x16x32_bf16 v[160:163], v[108:111], v[196:199], v[160:163]
	v_mfma_f32_16x16x32_bf16 v[164:167], v[116:119], v[196:199], v[164:167]
	s_setprio 0
	s_setprio 1
	v_mfma_f32_16x16x32_bf16 v[12:15], v[168:171], v[36:39], v[12:15]
	v_mfma_f32_16x16x32_bf16 v[208:211], v[172:175], v[44:47], v[12:15]
	v_mfma_f32_16x16x32_bf16 v[12:15], v[120:123], v[184:187], v[24:27]
	v_mfma_f32_16x16x32_bf16 v[24:27], v[124:127], v[188:191], v[12:15]
	v_mfma_f32_16x16x32_bf16 v[12:15], v[168:171], v[184:187], v[28:31]
	v_mfma_f32_16x16x32_bf16 v[184:187], v[172:175], v[188:191], v[12:15]
	v_mfma_f32_16x16x32_bf16 v[12:15], v[120:123], v[192:195], v[60:63]
	v_mfma_f32_16x16x32_bf16 v[188:191], v[124:127], v[196:199], v[12:15]
	v_mfma_f32_16x16x32_bf16 v[12:15], v[168:171], v[192:195], v[100:103]
	v_mfma_f32_16x16x32_bf16 v[8:11], v[120:123], v[36:39], v[8:11]
	v_mfma_f32_16x16x32_bf16 v[192:195], v[172:175], v[196:199], v[12:15]
	v_mfma_f32_16x16x32_bf16 v[12:15], v[120:123], v[200:203], v[16:19]
	v_mfma_f32_16x16x32_bf16 v[8:11], v[124:127], v[44:47], v[8:11]
	v_mfma_f32_16x16x32_bf16 v[196:199], v[124:127], v[204:207], v[12:15]
	v_mfma_f32_16x16x32_bf16 v[12:15], v[168:171], v[200:203], v[20:23]
	v_mfma_f32_16x16x32_bf16 v[168:171], v[172:175], v[204:207], v[12:15]
	s_setprio 0
	s_barrier
; #define PG8_STAGE(bufoff, gbase, voff) do { _Pragma("unroll") for (int _i = 0; _i < 2; ++_i) \
;         { unsigned _vo = (voff)[_i]; asm volatile("" : "+v"(_vo));     \
;         __builtin_amdgcn_global_load_lds((const unsigned*)((const char*)(gbase) + _vo), (PG8_LAS unsigned*)(lds + (bufoff) + ldsw + _i * 8192), 16, 0, 0); } } while (0)
; #define PG8_LDA(dst, b, h) do { _Pragma("unroll") for (int m = 0; m < 4; ++m) _Pragma("unroll") for (int k = 0; k < 2; ++k) dst[m][k] = *(const PG8_LAS bf16x8*)(lds + PG8_SA(b, h) + aoff + m * 2048 + k * 1024); } while (0)
; #define PG8_LDB(dst, b, h) do { _Pragma("unroll") for (int n = 0; n < 2; ++n) _Pragma("unroll") for (int k = 0; k < 2; ++k) dst[n][k] = *(const PG8_LAS bf16x8*)(lds + PG8_SB(b, h) + boff + n * 2048 + k * 1024); } while (0)
; #define PG8_WAIT_V(n) asm volatile("s_waitcnt vmcnt(" #n ")" ::: "memory")
; #define PG8_WAIT_L(n) asm volatile("s_waitcnt lgkmcnt(" #n ")" ::: "memory")
; #define PG8_BAR __builtin_amdgcn_s_barrier()
; #define PG8_SCHED __builtin_amdgcn_sched_barrier(0)
; template <class Epi, class Sched, bool ALIGN_EPI = false, bool SP2 = false, bool ABLK = false, bool F8 = false>
; __device__ __forceinline__ void gemm_phase(PG8_LAS unsigned char* lds, const Gemm g, const Sched& S, const Epi& E, const int wave_s) {
;     ...
;             PG8_LDB(B0, 1, 0); PG8_LDB(B1, 1, 1); PG8_SCHED; PG8_LDA(At, 1, 0); PG8_STAGE(PG8_SA(0, 1), a2 + hstepA, voffA);
;             PG8_WAIT_V(8); PG8_WAIT_L(0); PG8_BAR; PG8_MMA(0, 0, At, B0); PG8_MMA(0, 1, At, B1); PG8_BAR; PG8_SCHED;
;             PG8_LDA(At, 1, 1); PG8_STAGE(PG8_SB(1, 0), b3, voffB); PG8_STAGE(PG8_SB(1, 1), b3 + hstep, voffB); PG8_STAGE(PG8_SA(1, 0), a3, voffA);
;             PG8_WAIT_V(8); PG8_WAIT_L(0); PG8_BAR; PG8_MMA(1, 0, At, B0); PG8_MMA(1, 1, At, B1); PG8_BAR; PG8_SCHED;
	s_nop 4
	ds_read_b128 v[12:15], v212
	ds_read_b128 v[16:19], v212 offset:1024
	ds_read_b128 v[172:175], v212 offset:2048
	ds_read_b128 v[200:203], v212 offset:3072
	ds_read_b128 v[204:207], v220
	ds_read_b128 v[212:215], v220 offset:1024
	ds_read_b128 v[216:219], v220 offset:2048
	ds_read_b128 v[220:223], v220 offset:3072
	s_add_u32 s60, s62, 0x10000
	s_mov_b32 m0, s59
	ds_read_b128 v[20:23], v143 offset:32768
	ds_read_b128 v[28:31], v143 offset:33792
	ds_read_b128 v[60:63], v143 offset:34816
	ds_read_b128 v[224:227], v143 offset:35840
	ds_read_b128 v[228:231], v143 offset:36864
	ds_read_b128 v[232:235], v143 offset:37888
	ds_read_b128 v[236:239], v143 offset:38912
	ds_read_b128 v[240:243], v143 offset:39936
	s_addc_u32 s61, s63, 0
	s_nop 0
	global_load_lds_dwordx4 v134, s[60:61]
	s_mov_b32 m0, s72
	s_nop 0
	global_load_lds_dwordx4 v136, s[60:61]
	s_waitcnt vmcnt(8)
	s_waitcnt lgkmcnt(0)
	s_barrier
	s_setprio 1
	s_waitcnt lgkmcnt(0)
	v_mfma_f32_16x16x32_bf16 v[36:39], v[12:15], v[20:23], v[64:67]
	v_mfma_f32_16x16x32_bf16 v[124:127], v[16:19], v[28:31], v[36:39]
	v_mfma_f32_16x16x32_bf16 v[36:39], v[172:175], v[20:23], v[68:71]
	v_mfma_f32_16x16x32_bf16 v[116:119], v[200:203], v[28:31], v[36:39]
	v_mfma_f32_16x16x32_bf16 v[36:39], v[12:15], v[60:63], v[72:75]
	v_mfma_f32_16x16x32_bf16 v[108:111], v[16:19], v[224:227], v[36:39]
	v_mfma_f32_16x16x32_bf16 v[36:39], v[172:175], v[60:63], v[76:79]
	v_mfma_f32_16x16x32_bf16 v[100:103], v[200:203], v[224:227], v[36:39]
	v_mfma_f32_16x16x32_bf16 v[36:39], v[12:15], v[228:231], v[80:83]
	v_mfma_f32_16x16x32_bf16 v[80:83], v[16:19], v[232:235], v[36:39]
	v_mfma_f32_16x16x32_bf16 v[36:39], v[172:175], v[228:231], v[84:87]
	v_mfma_f32_16x16x32_bf16 v[68:71], v[200:203], v[232:235], v[36:39]
	v_mfma_f32_16x16x32_bf16 v[36:39], v[12:15], v[236:239], v[88:91]
	v_mfma_f32_16x16x32_bf16 v[44:47], v[16:19], v[240:243], v[36:39]
	v_mfma_f32_16x16x32_bf16 v[36:39], v[172:175], v[236:239], v[92:95]
	v_mfma_f32_16x16x32_bf16 v[36:39], v[200:203], v[240:243], v[36:39]
	s_setprio 0
	s_setprio 1
	v_mfma_f32_16x16x32_bf16 v[64:67], v[204:207], v[20:23], v[96:99]
	v_mfma_f32_16x16x32_bf16 v[20:23], v[216:219], v[20:23], v[32:35]
	v_mfma_f32_16x16x32_bf16 v[112:115], v[220:223], v[28:31], v[20:23]
	v_mfma_f32_16x16x32_bf16 v[20:23], v[204:207], v[60:63], v[176:179]
	v_mfma_f32_16x16x32_bf16 v[104:107], v[212:215], v[224:227], v[20:23]
	v_mfma_f32_16x16x32_bf16 v[20:23], v[216:219], v[60:63], v[40:43]
	v_mfma_f32_16x16x32_bf16 v[96:99], v[220:223], v[224:227], v[20:23]
	v_mfma_f32_16x16x32_bf16 v[20:23], v[204:207], v[228:231], v[180:183]
	v_mfma_f32_16x16x32_bf16 v[72:75], v[212:215], v[232:235], v[20:23]
	v_mfma_f32_16x16x32_bf16 v[20:23], v[216:219], v[228:231], v[48:51]
	v_mfma_f32_16x16x32_bf16 v[120:123], v[212:215], v[28:31], v[64:67]
	v_mfma_f32_16x16x32_bf16 v[64:67], v[220:223], v[232:235], v[20:23]
	v_mfma_f32_16x16x32_bf16 v[20:23], v[204:207], v[236:239], v[52:55]
	v_mfma_f32_16x16x32_bf16 v[40:43], v[212:215], v[240:243], v[20:23]
	v_mfma_f32_16x16x32_bf16 v[20:23], v[216:219], v[236:239], v[56:59]
	v_mfma_f32_16x16x32_bf16 v[32:35], v[220:223], v[240:243], v[20:23]
	s_setprio 0
	s_barrier
	v_mov_b32_e32 v128, v135
	ds_read_b128 v[48:51], v143 offset:49152
	ds_read_b128 v[56:59], v143 offset:50176
	ds_read_b128 v[176:179], v143 offset:51200
	ds_read_b128 v[180:183], v143 offset:52224
	ds_read_b128 v[224:227], v143 offset:53248
	ds_read_b128 v[228:231], v143 offset:54272
	ds_read_b128 v[232:235], v143 offset:55296
	ds_read_b128 v[236:239], v143 offset:56320
	s_mov_b32 m0, s87
	v_lshl_add_u64 v[20:21], s[66:67], 0, v[128:129]
	v_lshl_add_u64 v[20:21], v[20:21], 0, s[10:11]
	v_mov_b32_e32 v128, v137
	global_load_lds_dwordx4 v[20:21], off
	s_mov_b32 m0, s86
	v_lshl_add_u64 v[20:21], s[66:67], 0, v[128:129]
	v_lshl_add_u64 v[20:21], v[20:21], 0, s[10:11]
	global_load_lds_dwordx4 v[20:21], off
	s_add_u32 s60, s66, 0x10080
	s_addc_u32 s61, s67, 0
	s_mov_b32 m0, s64
	v_mov_b32_e32 v128, v134
	global_load_lds_dwordx4 v135, s[60:61]
	s_mov_b32 m0, s65
	s_nop 0
	global_load_lds_dwordx4 v137, s[60:61]
	s_mov_b32 m0, s73
	v_lshl_add_u64 v[20:21], s[62:63], 0, v[128:129]
	v_lshl_add_u64 v[20:21], v[20:21], 0, s[10:11]
	v_mov_b32_e32 v128, v136
	global_load_lds_dwordx4 v[20:21], off
	s_mov_b32 m0, s74
	v_lshl_add_u64 v[20:21], s[62:63], 0, v[128:129]
	v_lshl_add_u64 v[20:21], v[20:21], 0, s[10:11]
	global_load_lds_dwordx4 v[20:21], off
	s_waitcnt vmcnt(8)
	s_waitcnt lgkmcnt(0)
	s_barrier
	s_setprio 1
	s_waitcnt lgkmcnt(0)
	v_mfma_f32_16x16x32_bf16 v[20:23], v[12:15], v[48:51], v[144:147]
	v_mfma_f32_16x16x32_bf16 v[92:95], v[16:19], v[56:59], v[20:23]
	v_mfma_f32_16x16x32_bf16 v[20:23], v[172:175], v[48:51], v[148:151]
	v_mfma_f32_16x16x32_bf16 v[88:91], v[200:203], v[56:59], v[20:23]
	v_mfma_f32_16x16x32_bf16 v[20:23], v[12:15], v[176:179], v[152:155]
	v_mfma_f32_16x16x32_bf16 v[60:63], v[16:19], v[180:183], v[20:23]
	v_mfma_f32_16x16x32_bf16 v[20:23], v[172:175], v[176:179], v[156:159]
	v_mfma_f32_16x16x32_bf16 v[52:55], v[200:203], v[180:183], v[20:23]
	v_mfma_f32_16x16x32_bf16 v[20:23], v[12:15], v[224:227], v[160:163]
	v_mfma_f32_16x16x32_bf16 v[0:3], v[12:15], v[232:235], v[0:3]
	v_mfma_f32_16x16x32_bf16 v[28:31], v[16:19], v[228:231], v[20:23]
	v_mfma_f32_16x16x32_bf16 v[20:23], v[172:175], v[224:227], v[164:167]
	v_mfma_f32_16x16x32_bf16 v[12:15], v[16:19], v[236:239], v[0:3]
	v_mfma_f32_16x16x32_bf16 v[0:3], v[172:175], v[232:235], v[4:7]
	v_mfma_f32_16x16x32_bf16 v[20:23], v[200:203], v[228:231], v[20:23]
	v_mfma_f32_16x16x32_bf16 v[4:7], v[200:203], v[236:239], v[0:3]
	s_setprio 0
	s_setprio 1
	v_mfma_f32_16x16x32_bf16 v[0:3], v[204:207], v[48:51], v[8:11]
	v_mfma_f32_16x16x32_bf16 v[84:87], v[212:215], v[56:59], v[0:3]
	v_mfma_f32_16x16x32_bf16 v[0:3], v[216:219], v[48:51], v[208:211]
	v_mfma_f32_16x16x32_bf16 v[76:79], v[220:223], v[56:59], v[0:3]
	v_mfma_f32_16x16x32_bf16 v[0:3], v[204:207], v[176:179], v[24:27]
	v_mfma_f32_16x16x32_bf16 v[56:59], v[212:215], v[180:183], v[0:3]
	v_mfma_f32_16x16x32_bf16 v[0:3], v[216:219], v[176:179], v[184:187]
	v_mfma_f32_16x16x32_bf16 v[48:51], v[220:223], v[180:183], v[0:3]
	v_mfma_f32_16x16x32_bf16 v[0:3], v[204:207], v[224:227], v[188:191]
	v_mfma_f32_16x16x32_bf16 v[24:27], v[212:215], v[228:231], v[0:3]
	v_mfma_f32_16x16x32_bf16 v[0:3], v[216:219], v[224:227], v[192:195]
	v_mfma_f32_16x16x32_bf16 v[16:19], v[220:223], v[228:231], v[0:3]
	v_mfma_f32_16x16x32_bf16 v[0:3], v[204:207], v[232:235], v[196:199]
	v_mfma_f32_16x16x32_bf16 v[8:11], v[212:215], v[236:239], v[0:3]
	v_mfma_f32_16x16x32_bf16 v[0:3], v[216:219], v[232:235], v[168:171]
	v_mfma_f32_16x16x32_bf16 v[0:3], v[220:223], v[236:239], v[0:3]
	s_setprio 0
	s_barrier
	s_and_b64 vcc, exec, s[4:5]
	s_cbranch_vccnz .LBB0_987
	s_barrier

; #define PG8_STAGE(bufoff, gbase, voff) do { _Pragma("unroll") for (int _i = 0; _i < 2; ++_i) \
;         { unsigned _vo = (voff)[_i]; asm volatile("" : "+v"(_vo));     \
;         __builtin_amdgcn_global_load_lds((const unsigned*)((const char*)(gbase) + _vo), (PG8_LAS unsigned*)(lds + (bufoff) + ldsw + _i * 8192), 16, 0, 0); } } while (0)
; #define PG8_LDA(dst, b, h) do { _Pragma("unroll") for (int m = 0; m < 4; ++m) _Pragma("unroll") for (int k = 0; k < 2; ++k) dst[m][k] = *(const PG8_LAS bf16x8*)(lds + PG8_SA(b, h) + aoff + m * 2048 + k * 1024); } while (0)
; #define PG8_LDB(dst, b, h) do { _Pragma("unroll") for (int n = 0; n < 2; ++n) _Pragma("unroll") for (int k = 0; k < 2; ++k) dst[n][k] = *(const PG8_LAS bf16x8*)(lds + PG8_SB(b, h) + boff + n * 2048 + k * 1024); } while (0)
; #define PG8_WAIT_V(n) asm volatile("s_waitcnt vmcnt(" #n ")" ::: "memory")
; #define PG8_WAIT_L(n) asm volatile("s_waitcnt lgkmcnt(" #n ")" ::: "memory")
; #define PG8_BAR __builtin_amdgcn_s_barrier()
; #define PG8_SCHED __builtin_amdgcn_sched_barrier(0)
; template <class Epi, class Sched, bool ALIGN_EPI = false, bool SP2 = false, bool ABLK = false, bool F8 = false>
; __device__ __forceinline__ void gemm_phase(PG8_LAS unsigned char* lds, const Gemm g, const Sched& S, const Epi& E, const int wave_s) {
;     ...
;             const bool last = (t == nt - 2);
;             const char* a1 = cA + (size_t)(t + 1) * kstepA;
;             const char* a2 = last ? nA : cA + (size_t)(t + 2) * kstepA; const char* b2 = last ? nB : cB + (size_t)(t + 2) * kstep;
;             const char* a3 = a2 + kstepA; const char* b3 = b2 + kstep;
;             if (last && has_next) { S.a_ready(nxt); if constexpr (Epi::PREF) E.prefetch(nxt, wid, lane); }
;             if constexpr (SP2) {
;             PG8_LDB(B0, 0, 0); PG8_LDB(B1, 0, 1); PG8_SCHED; PG8_LDA(At, 0, 0); PG8_STAGE(PG8_SA(1, 1), a1 + hstepA, voffA);
;             PG8_WAIT_V(8); PG8_WAIT_L(0); PG8_BAR; PG8_MMA(0, 0, At, B0); PG8_MMA(0, 1, At, B1); PG8_BAR; PG8_SCHED;
;             PG8_LDA(At, 0, 1); PG8_STAGE(PG8_SB(0, 0), b2, voffB); PG8_STAGE(PG8_SB(0, 1), b2 + hstep, voffB); PG8_STAGE(PG8_SA(0, 0), a2, voffA);
;             PG8_WAIT_V(8); PG8_WAIT_L(0); PG8_BAR; PG8_MMA(1, 0, At, B0); PG8_MMA(1, 1, At, B1); PG8_BAR; PG8_SCHED;
.LBB0_1010:
	ds_read_b128 v[64:67], v236
	ds_read_b128 v[68:71], v236 offset:1024
	ds_read_b128 v[88:91], v236 offset:2048
	ds_read_b128 v[92:95], v236 offset:3072
	ds_read_b128 v[112:115], v237
	ds_read_b128 v[116:119], v237 offset:1024
	ds_read_b128 v[136:139], v237 offset:2048
	ds_read_b128 v[140:143], v237 offset:3072
	s_add_u32 s52, s50, 0xfff80080
	s_addc_u32 s53, s51, -1
	s_cmp_eq_u32 s62, 28
	s_cselect_b32 s53, s41, s53
	s_cselect_b32 s52, s47, s52
	s_cselect_b32 s55, s13, s61
	s_cselect_b32 s54, s59, s60
	ds_read_b128 v[152:155], v238
	ds_read_b128 v[164:167], v238 offset:1024
	ds_read_b128 v[168:171], v238 offset:2048
	ds_read_b128 v[172:175], v238 offset:3072
	ds_read_b128 v[176:179], v238 offset:4096
	ds_read_b128 v[180:183], v238 offset:5120
	ds_read_b128 v[190:193], v238 offset:6144
	ds_read_b128 v[194:197], v238 offset:7168
	s_add_i32 m0, s20, 0xc000
	s_nop 0
	global_load_lds_dwordx4 v229, s[50:51]
	s_add_i32 m0, s20, 0xe000
	s_nop 0
	global_load_lds_dwordx4 v231, s[50:51]
	s_waitcnt vmcnt(8)
	s_waitcnt lgkmcnt(0)
	s_barrier
	s_setprio 1
	s_waitcnt lgkmcnt(0)
	v_mfma_f32_16x16x32_bf16 v[160:163], v[64:67], v[152:155], v[160:163]
	v_mfma_f32_16x16x32_bf16 v[156:159], v[88:91], v[152:155], v[156:159]
	v_mfma_f32_16x16x32_bf16 v[132:135], v[64:67], v[168:171], v[132:135]
	v_mfma_f32_16x16x32_bf16 v[128:131], v[88:91], v[168:171], v[128:131]
	v_mfma_f32_16x16x32_bf16 v[108:111], v[64:67], v[176:179], v[108:111]
	v_mfma_f32_16x16x32_bf16 v[104:107], v[88:91], v[176:179], v[104:107]
	v_mfma_f32_16x16x32_bf16 v[84:87], v[64:67], v[190:193], v[84:87]
	v_mfma_f32_16x16x32_bf16 v[80:83], v[88:91], v[190:193], v[80:83]
	v_mfma_f32_16x16x32_bf16 v[160:163], v[68:71], v[164:167], v[160:163]
	v_mfma_f32_16x16x32_bf16 v[156:159], v[92:95], v[164:167], v[156:159]
	v_mfma_f32_16x16x32_bf16 v[132:135], v[68:71], v[172:175], v[132:135]
	v_mfma_f32_16x16x32_bf16 v[128:131], v[92:95], v[172:175], v[128:131]
	v_mfma_f32_16x16x32_bf16 v[108:111], v[68:71], v[180:183], v[108:111]
	v_mfma_f32_16x16x32_bf16 v[104:107], v[92:95], v[180:183], v[104:107]
	v_mfma_f32_16x16x32_bf16 v[84:87], v[68:71], v[194:197], v[84:87]
	v_mfma_f32_16x16x32_bf16 v[80:83], v[92:95], v[194:197], v[80:83]
	s_setprio 0
	s_setprio 1
	v_mfma_f32_16x16x32_bf16 v[148:151], v[112:115], v[152:155], v[148:151]
	v_mfma_f32_16x16x32_bf16 v[144:147], v[136:139], v[152:155], v[144:147]
	v_mfma_f32_16x16x32_bf16 v[124:127], v[112:115], v[168:171], v[124:127]
	v_mfma_f32_16x16x32_bf16 v[120:123], v[136:139], v[168:171], v[120:123]
	v_mfma_f32_16x16x32_bf16 v[100:103], v[112:115], v[176:179], v[100:103]
	v_mfma_f32_16x16x32_bf16 v[96:99], v[136:139], v[176:179], v[96:99]
	v_mfma_f32_16x16x32_bf16 v[76:79], v[112:115], v[190:193], v[76:79]
	v_mfma_f32_16x16x32_bf16 v[72:75], v[136:139], v[190:193], v[72:75]
	v_mfma_f32_16x16x32_bf16 v[148:151], v[116:119], v[164:167], v[148:151]
	v_mfma_f32_16x16x32_bf16 v[144:147], v[140:143], v[164:167], v[144:147]
	v_mfma_f32_16x16x32_bf16 v[124:127], v[116:119], v[172:175], v[124:127]
	v_mfma_f32_16x16x32_bf16 v[120:123], v[140:143], v[172:175], v[120:123]
	v_mfma_f32_16x16x32_bf16 v[100:103], v[116:119], v[180:183], v[100:103]
	v_mfma_f32_16x16x32_bf16 v[96:99], v[140:143], v[180:183], v[96:99]
	v_mfma_f32_16x16x32_bf16 v[76:79], v[116:119], v[194:197], v[76:79]
	v_mfma_f32_16x16x32_bf16 v[72:75], v[140:143], v[194:197], v[72:75]
	s_setprio 0
	s_barrier
	s_add_i32 s63, s57, s3
	ds_read_b128 v[152:155], v238 offset:16384
	ds_read_b128 v[164:167], v238 offset:17408
	ds_read_b128 v[168:171], v238 offset:18432
	ds_read_b128 v[172:175], v238 offset:19456
	ds_read_b128 v[176:179], v238 offset:20480
	ds_read_b128 v[180:183], v238 offset:21504
	ds_read_b128 v[190:193], v238 offset:22528
	ds_read_b128 v[194:197], v238 offset:23552
	s_mov_b32 m0, s63
	s_nop 0
	global_load_lds_dwordx4 v230, s[54:55]
	s_add_i32 m0, s63, 0x2000
	s_add_u32 s64, s54, 0x80000
	global_load_lds_dwordx4 v232, s[54:55]
	s_addc_u32 s65, s55, 0
	s_add_i32 s63, s58, s3
	s_mov_b32 m0, s63
	s_nop 0
	global_load_lds_dwordx4 v230, s[64:65]
	s_add_i32 m0, s63, 0x2000
	s_nop 0
	global_load_lds_dwordx4 v232, s[64:65]
	s_mov_b32 m0, s20
	s_nop 0
	global_load_lds_dwordx4 v229, s[52:53]
	s_mov_b32 m0, s21
	s_nop 0
	global_load_lds_dwordx4 v231, s[52:53]
	s_waitcnt vmcnt(8)
	s_waitcnt lgkmcnt(0)
	s_barrier
	s_setprio 1
	s_waitcnt lgkmcnt(0)
	v_mfma_f32_16x16x32_bf16 v[60:63], v[64:67], v[152:155], v[60:63]
	v_mfma_f32_16x16x32_bf16 v[56:59], v[88:91], v[152:155], v[56:59]
	v_mfma_f32_16x16x32_bf16 v[44:47], v[64:67], v[168:171], v[44:47]
	v_mfma_f32_16x16x32_bf16 v[40:43], v[88:91], v[168:171], v[40:43]
	v_mfma_f32_16x16x32_bf16 v[28:31], v[64:67], v[176:179], v[28:31]
	v_mfma_f32_16x16x32_bf16 v[24:27], v[88:91], v[176:179], v[24:27]
	v_mfma_f32_16x16x32_bf16 v[12:15], v[64:67], v[190:193], v[12:15]
	v_mfma_f32_16x16x32_bf16 v[8:11], v[88:91], v[190:193], v[8:11]
	v_mfma_f32_16x16x32_bf16 v[60:63], v[68:71], v[164:167], v[60:63]
	v_mfma_f32_16x16x32_bf16 v[56:59], v[92:95], v[164:167], v[56:59]
	v_mfma_f32_16x16x32_bf16 v[44:47], v[68:71], v[172:175], v[44:47]
	v_mfma_f32_16x16x32_bf16 v[40:43], v[92:95], v[172:175], v[40:43]
	v_mfma_f32_16x16x32_bf16 v[28:31], v[68:71], v[180:183], v[28:31]
	v_mfma_f32_16x16x32_bf16 v[24:27], v[92:95], v[180:183], v[24:27]
	v_mfma_f32_16x16x32_bf16 v[12:15], v[68:71], v[194:197], v[12:15]
	v_mfma_f32_16x16x32_bf16 v[8:11], v[92:95], v[194:197], v[8:11]
	s_setprio 0
	s_setprio 1
	v_mfma_f32_16x16x32_bf16 v[52:55], v[112:115], v[152:155], v[52:55]
	v_mfma_f32_16x16x32_bf16 v[48:51], v[136:139], v[152:155], v[48:51]
	v_mfma_f32_16x16x32_bf16 v[36:39], v[112:115], v[168:171], v[36:39]
	v_mfma_f32_16x16x32_bf16 v[32:35], v[136:139], v[168:171], v[32:35]
	v_mfma_f32_16x16x32_bf16 v[20:23], v[112:115], v[176:179], v[20:23]
	v_mfma_f32_16x16x32_bf16 v[16:19], v[136:139], v[176:179], v[16:19]
	v_mfma_f32_16x16x32_bf16 v[4:7], v[112:115], v[190:193], v[4:7]
	v_mfma_f32_16x16x32_bf16 v[0:3], v[136:139], v[190:193], v[0:3]
	v_mfma_f32_16x16x32_bf16 v[52:55], v[116:119], v[164:167], v[52:55]
	v_mfma_f32_16x16x32_bf16 v[48:51], v[140:143], v[164:167], v[48:51]
	v_mfma_f32_16x16x32_bf16 v[36:39], v[116:119], v[172:175], v[36:39]
	v_mfma_f32_16x16x32_bf16 v[32:35], v[140:143], v[172:175], v[32:35]
	v_mfma_f32_16x16x32_bf16 v[20:23], v[116:119], v[180:183], v[20:23]
	v_mfma_f32_16x16x32_bf16 v[16:19], v[140:143], v[180:183], v[16:19]
	v_mfma_f32_16x16x32_bf16 v[4:7], v[116:119], v[194:197], v[4:7]
	v_mfma_f32_16x16x32_bf16 v[0:3], v[140:143], v[194:197], v[0:3]
	s_setprio 0
	s_barrier
; #define PG8_STAGE(bufoff, gbase, voff) do { _Pragma("unroll") for (int _i = 0; _i < 2; ++_i) \
;         { unsigned _vo = (voff)[_i]; asm volatile("" : "+v"(_vo));     \
;         __builtin_amdgcn_global_load_lds((const unsigned*)((const char*)(gbase) + _vo), (PG8_LAS unsigned*)(lds + (bufoff) + ldsw + _i * 8192), 16, 0, 0); } } while (0)
; #define PG8_LDA(dst, b, h) do { _Pragma("unroll") for (int m = 0; m < 4; ++m) _Pragma("unroll") for (int k = 0; k < 2; ++k) dst[m][k] = *(const PG8_LAS bf16x8*)(lds + PG8_SA(b, h) + aoff + m * 2048 + k * 1024); } while (0)
; #define PG8_LDB(dst, b, h) do { _Pragma("unroll") for (int n = 0; n < 2; ++n) _Pragma("unroll") for (int k = 0; k < 2; ++k) dst[n][k] = *(const PG8_LAS bf16x8*)(lds + PG8_SB(b, h) + boff + n * 2048 + k * 1024); } while (0)
; #define PG8_WAIT_V(n) asm volatile("s_waitcnt vmcnt(" #n ")" ::: "memory")
; #define PG8_WAIT_L(n) asm volatile("s_waitcnt lgkmcnt(" #n ")" ::: "memory")
; #define PG8_BAR __builtin_amdgcn_s_barrier()
; #define PG8_SCHED __builtin_amdgcn_sched_barrier(0)
; template <class Epi, class Sched, bool ALIGN_EPI = false, bool SP2 = false, bool ABLK = false, bool F8 = false>
; __device__ __forceinline__ void gemm_phase(PG8_LAS unsigned char* lds, const Gemm g, const Sched& S, const Epi& E, const int wave_s) {
;     ...
;             PG8_LDB(B0, 1, 0); PG8_LDB(B1, 1, 1); PG8_SCHED; PG8_LDA(At, 1, 0); PG8_STAGE(PG8_SA(0, 1), a2 + hstepA, voffA);
;             PG8_WAIT_V(8); PG8_WAIT_L(0); PG8_BAR; PG8_MMA(0, 0, At, B0); PG8_MMA(0, 1, At, B1); PG8_BAR; PG8_SCHED;
;             PG8_LDA(At, 1, 1); PG8_STAGE(PG8_SB(1, 0), b3, voffB); PG8_STAGE(PG8_SB(1, 1), b3 + hstep, voffB); PG8_STAGE(PG8_SA(1, 0), a3, voffA);
;             PG8_WAIT_V(8); PG8_WAIT_L(0); PG8_BAR; PG8_MMA(1, 0, At, B0); PG8_MMA(1, 1, At, B1); PG8_BAR; PG8_SCHED;
;     ...
;         if constexpr (ALIGN_EPI) { if (wr == 0) PG8_BAR; }
	s_add_i32 s63, 0, 0x18000
	s_add_i32 s66, 0, 0x1c000
	v_add_u32_e32 v92, s63, v234
	v_add_u32_e32 v140, s66, v234
	ds_read_b128 v[64:67], v92
	ds_read_b128 v[68:71], v92 offset:1024
	ds_read_b128 v[88:91], v92 offset:2048
	ds_read_b128 v[92:95], v92 offset:3072
	ds_read_b128 v[112:115], v140
	ds_read_b128 v[116:119], v140 offset:1024
	ds_read_b128 v[136:139], v140 offset:2048
	ds_read_b128 v[140:143], v140 offset:3072
	s_add_u32 s64, s52, 0x80000
	s_mov_b32 m0, s22
	ds_read_b128 v[152:155], v238 offset:32768
	ds_read_b128 v[164:167], v238 offset:33792
	ds_read_b128 v[168:171], v238 offset:34816
	ds_read_b128 v[172:175], v238 offset:35840
	ds_read_b128 v[176:179], v238 offset:36864
	ds_read_b128 v[180:183], v238 offset:37888
	ds_read_b128 v[190:193], v238 offset:38912
	ds_read_b128 v[194:197], v238 offset:39936
	s_addc_u32 s65, s53, 0
	s_nop 0
	global_load_lds_dwordx4 v229, s[64:65]
	s_mov_b32 m0, s23
	s_nop 0
	global_load_lds_dwordx4 v231, s[64:65]
	s_waitcnt vmcnt(8)
	s_waitcnt lgkmcnt(0)
	s_barrier
	s_setprio 1
	s_waitcnt lgkmcnt(0)
	v_mfma_f32_16x16x32_bf16 v[160:163], v[64:67], v[152:155], v[160:163]
	v_mfma_f32_16x16x32_bf16 v[156:159], v[88:91], v[152:155], v[156:159]
	v_mfma_f32_16x16x32_bf16 v[132:135], v[64:67], v[168:171], v[132:135]
	v_mfma_f32_16x16x32_bf16 v[128:131], v[88:91], v[168:171], v[128:131]
	v_mfma_f32_16x16x32_bf16 v[108:111], v[64:67], v[176:179], v[108:111]
	v_mfma_f32_16x16x32_bf16 v[104:107], v[88:91], v[176:179], v[104:107]
	v_mfma_f32_16x16x32_bf16 v[84:87], v[64:67], v[190:193], v[84:87]
	v_mfma_f32_16x16x32_bf16 v[80:83], v[88:91], v[190:193], v[80:83]
	v_mfma_f32_16x16x32_bf16 v[160:163], v[68:71], v[164:167], v[160:163]
	v_mfma_f32_16x16x32_bf16 v[156:159], v[92:95], v[164:167], v[156:159]
	v_mfma_f32_16x16x32_bf16 v[132:135], v[68:71], v[172:175], v[132:135]
	v_mfma_f32_16x16x32_bf16 v[128:131], v[92:95], v[172:175], v[128:131]
	v_mfma_f32_16x16x32_bf16 v[108:111], v[68:71], v[180:183], v[108:111]
	v_mfma_f32_16x16x32_bf16 v[104:107], v[92:95], v[180:183], v[104:107]
	v_mfma_f32_16x16x32_bf16 v[84:87], v[68:71], v[194:197], v[84:87]
	v_mfma_f32_16x16x32_bf16 v[80:83], v[92:95], v[194:197], v[80:83]
	s_setprio 0
	s_setprio 1
	v_mfma_f32_16x16x32_bf16 v[148:151], v[112:115], v[152:155], v[148:151]
	v_mfma_f32_16x16x32_bf16 v[144:147], v[136:139], v[152:155], v[144:147]
	v_mfma_f32_16x16x32_bf16 v[124:127], v[112:115], v[168:171], v[124:127]
	v_mfma_f32_16x16x32_bf16 v[120:123], v[136:139], v[168:171], v[120:123]
	v_mfma_f32_16x16x32_bf16 v[100:103], v[112:115], v[176:179], v[100:103]
	v_mfma_f32_16x16x32_bf16 v[96:99], v[136:139], v[176:179], v[96:99]
	v_mfma_f32_16x16x32_bf16 v[76:79], v[112:115], v[190:193], v[76:79]
	v_mfma_f32_16x16x32_bf16 v[72:75], v[136:139], v[190:193], v[72:75]
	v_mfma_f32_16x16x32_bf16 v[148:151], v[116:119], v[164:167], v[148:151]
	v_mfma_f32_16x16x32_bf16 v[144:147], v[140:143], v[164:167], v[144:147]
	v_mfma_f32_16x16x32_bf16 v[124:127], v[116:119], v[172:175], v[124:127]
	v_mfma_f32_16x16x32_bf16 v[120:123], v[140:143], v[172:175], v[120:123]
	v_mfma_f32_16x16x32_bf16 v[100:103], v[116:119], v[180:183], v[100:103]
	v_mfma_f32_16x16x32_bf16 v[96:99], v[140:143], v[180:183], v[96:99]
	v_mfma_f32_16x16x32_bf16 v[76:79], v[116:119], v[194:197], v[76:79]
	v_mfma_f32_16x16x32_bf16 v[72:75], v[140:143], v[194:197], v[72:75]
	s_setprio 0
	s_barrier
	ds_read_b128 v[152:155], v238 offset:49152
	ds_read_b128 v[164:167], v238 offset:50176
	ds_read_b128 v[168:171], v238 offset:51200
	ds_read_b128 v[172:175], v238 offset:52224
	ds_read_b128 v[176:179], v238 offset:53248
	ds_read_b128 v[180:183], v238 offset:54272
	ds_read_b128 v[190:193], v238 offset:55296
	ds_read_b128 v[194:197], v238 offset:56320
	s_add_i32 s63, s63, s3
	s_add_u32 vcc_lo, s54, s10
	s_addc_u32 vcc_hi, s55, s11
	s_mov_b32 m0, s63
	s_nop 0
	global_load_lds_dwordx4 v230, vcc
	s_add_i32 m0, s63, 0x2000
	s_nop 0
	s_add_u32 vcc_lo, s54, s10
	s_addc_u32 vcc_hi, s55, s11
	s_add_u32 s54, s54, 0x80080
	s_addc_u32 s55, s55, 0
	s_add_i32 s63, s66, s3
	global_load_lds_dwordx4 v232, vcc
	s_mov_b32 m0, s63
	s_nop 0
	global_load_lds_dwordx4 v230, s[54:55]
	s_add_i32 m0, s63, 0x2000
	s_nop 0
	global_load_lds_dwordx4 v232, s[54:55]
	s_mov_b32 m0, s49
	s_add_u32 vcc_lo, s52, s10
	s_addc_u32 vcc_hi, s53, s11
	v_mov_b32_e32 v184, v231
	global_load_lds_dwordx4 v229, vcc
	s_mov_b32 m0, s56
	s_add_u32 vcc_lo, s52, s10
	s_addc_u32 vcc_hi, s53, s11
	global_load_lds_dwordx4 v231, vcc
	s_waitcnt vmcnt(8)
	s_waitcnt lgkmcnt(0)
	s_barrier
	s_setprio 1
	s_waitcnt lgkmcnt(0)
	v_mfma_f32_16x16x32_bf16 v[60:63], v[64:67], v[152:155], v[60:63]
	v_mfma_f32_16x16x32_bf16 v[56:59], v[88:91], v[152:155], v[56:59]
	v_mfma_f32_16x16x32_bf16 v[44:47], v[64:67], v[168:171], v[44:47]
	v_mfma_f32_16x16x32_bf16 v[40:43], v[88:91], v[168:171], v[40:43]
	v_mfma_f32_16x16x32_bf16 v[28:31], v[64:67], v[176:179], v[28:31]
	v_mfma_f32_16x16x32_bf16 v[24:27], v[88:91], v[176:179], v[24:27]
	v_mfma_f32_16x16x32_bf16 v[12:15], v[64:67], v[190:193], v[12:15]
	v_mfma_f32_16x16x32_bf16 v[8:11], v[88:91], v[190:193], v[8:11]
	v_mfma_f32_16x16x32_bf16 v[60:63], v[68:71], v[164:167], v[60:63]
	v_mfma_f32_16x16x32_bf16 v[56:59], v[92:95], v[164:167], v[56:59]
	v_mfma_f32_16x16x32_bf16 v[44:47], v[68:71], v[172:175], v[44:47]
	v_mfma_f32_16x16x32_bf16 v[40:43], v[92:95], v[172:175], v[40:43]
	v_mfma_f32_16x16x32_bf16 v[28:31], v[68:71], v[180:183], v[28:31]
	v_mfma_f32_16x16x32_bf16 v[24:27], v[92:95], v[180:183], v[24:27]
	v_mfma_f32_16x16x32_bf16 v[12:15], v[68:71], v[194:197], v[12:15]
	v_mfma_f32_16x16x32_bf16 v[8:11], v[92:95], v[194:197], v[8:11]
	s_setprio 0
	s_setprio 1
	v_mfma_f32_16x16x32_bf16 v[52:55], v[112:115], v[152:155], v[52:55]
	v_mfma_f32_16x16x32_bf16 v[48:51], v[136:139], v[152:155], v[48:51]
	v_mfma_f32_16x16x32_bf16 v[36:39], v[112:115], v[168:171], v[36:39]
	v_mfma_f32_16x16x32_bf16 v[32:35], v[136:139], v[168:171], v[32:35]
	v_mfma_f32_16x16x32_bf16 v[20:23], v[112:115], v[176:179], v[20:23]
	v_mfma_f32_16x16x32_bf16 v[16:19], v[136:139], v[176:179], v[16:19]
	v_mfma_f32_16x16x32_bf16 v[4:7], v[112:115], v[190:193], v[4:7]
	v_mfma_f32_16x16x32_bf16 v[0:3], v[136:139], v[190:193], v[0:3]
	v_mfma_f32_16x16x32_bf16 v[52:55], v[116:119], v[164:167], v[52:55]
	v_mfma_f32_16x16x32_bf16 v[48:51], v[140:143], v[164:167], v[48:51]
	v_mfma_f32_16x16x32_bf16 v[36:39], v[116:119], v[172:175], v[36:39]
	v_mfma_f32_16x16x32_bf16 v[32:35], v[140:143], v[172:175], v[32:35]
	v_mfma_f32_16x16x32_bf16 v[20:23], v[116:119], v[180:183], v[20:23]
	v_mfma_f32_16x16x32_bf16 v[16:19], v[140:143], v[180:183], v[16:19]
	v_mfma_f32_16x16x32_bf16 v[4:7], v[116:119], v[194:197], v[4:7]
	v_mfma_f32_16x16x32_bf16 v[0:3], v[140:143], v[194:197], v[0:3]
	s_setprio 0
	s_barrier
	s_add_i32 s62, s62, 2
	s_add_u32 s50, s50, 0x100
	s_addc_u32 s51, s51, 0
	s_add_u32 s60, s60, 0x100
	s_addc_u32 s61, s61, 0
	s_cmp_gt_u32 s62, 29
	s_cbranch_scc0 .LBB0_1010
	s_and_b64 vcc, exec, s[36:37]
	s_cbranch_vccz .LBB0_1013
	s_barrier
